# GEMM main loops: one static s_setprio raise for the trailing half-workgroup instead of per-segment toggling
# speedup vs baseline: 1.0019x; 1.0019x over previous
.LBB0_225:
	s_ashr_i32 s15, s14, 31
	s_lshl_b64 s[16:17], s[14:15], 19
	s_add_u32 s16, s26, s16
	s_addc_u32 s17, s27, s17
	s_and_b64 s[18:19], s[0:1], exec
	s_cselect_b32 s15, s17, s21
	s_cselect_b32 s44, s16, s20
	s_ashr_i32 s13, s12, 31
	s_lshl_b64 s[18:19], s[12:13], 19
	s_add_u32 s18, s28, s18
	s_addc_u32 s19, s29, s19
	s_and_b64 s[24:25], s[0:1], exec
	s_cselect_b32 s13, s19, s23
	s_cselect_b32 s45, s18, s22
	s_add_u32 s20, s20, 0x40080
	s_addc_u32 s21, s21, 0
	s_add_u32 s46, s22, 0x100
	v_mov_b32_e32 v2, 0
	s_addc_u32 s47, s23, 0
	s_mov_b32 s48, -2
	v_mov_b32_e32 v3, v2
	v_mov_b32_e32 v4, v2
	v_mov_b32_e32 v5, v2
	v_mov_b32_e32 v6, v2
	v_mov_b32_e32 v7, v2
	v_mov_b32_e32 v8, v2
	v_mov_b32_e32 v9, v2
	v_mov_b32_e32 v18, v2
	v_mov_b32_e32 v19, v2
	v_mov_b32_e32 v20, v2
	v_mov_b32_e32 v21, v2
	v_mov_b32_e32 v22, v2
	v_mov_b32_e32 v23, v2
	v_mov_b32_e32 v24, v2
	v_mov_b32_e32 v25, v2
	v_mov_b32_e32 v50, v2
	v_mov_b32_e32 v51, v2
	v_mov_b32_e32 v52, v2
	v_mov_b32_e32 v53, v2
	v_mov_b32_e32 v54, v2
	v_mov_b32_e32 v55, v2
	v_mov_b32_e32 v56, v2
	v_mov_b32_e32 v57, v2
	v_mov_b32_e32 v66, v2
	v_mov_b32_e32 v67, v2
	v_mov_b32_e32 v68, v2
	v_mov_b32_e32 v69, v2
	v_mov_b32_e32 v70, v2
	v_mov_b32_e32 v71, v2
	v_mov_b32_e32 v72, v2
	v_mov_b32_e32 v73, v2
	v_mov_b32_e32 v10, v2
	v_mov_b32_e32 v11, v2
	v_mov_b32_e32 v12, v2
	v_mov_b32_e32 v13, v2
	v_mov_b32_e32 v14, v2
	v_mov_b32_e32 v15, v2
	v_mov_b32_e32 v16, v2
	v_mov_b32_e32 v17, v2
	v_mov_b32_e32 v26, v2
	v_mov_b32_e32 v27, v2
	v_mov_b32_e32 v28, v2
	v_mov_b32_e32 v29, v2
	v_mov_b32_e32 v30, v2
	v_mov_b32_e32 v31, v2
	v_mov_b32_e32 v32, v2
	v_mov_b32_e32 v33, v2
	v_mov_b32_e32 v58, v2
	v_mov_b32_e32 v59, v2
	v_mov_b32_e32 v60, v2
	v_mov_b32_e32 v61, v2
	v_mov_b32_e32 v62, v2
	v_mov_b32_e32 v63, v2
	v_mov_b32_e32 v64, v2
	v_mov_b32_e32 v65, v2
	v_mov_b32_e32 v74, v2
	v_mov_b32_e32 v75, v2
	v_mov_b32_e32 v76, v2
	v_mov_b32_e32 v77, v2
	v_mov_b32_e32 v78, v2
	v_mov_b32_e32 v79, v2
	v_mov_b32_e32 v80, v2
	v_mov_b32_e32 v81, v2
	v_mov_b32_e32 v82, v2
	v_mov_b32_e32 v83, v2
	v_mov_b32_e32 v84, v2
	v_mov_b32_e32 v85, v2
	v_mov_b32_e32 v86, v2
	v_mov_b32_e32 v87, v2
	v_mov_b32_e32 v88, v2
	v_mov_b32_e32 v89, v2
	v_mov_b32_e32 v98, v2
	v_mov_b32_e32 v99, v2
	v_mov_b32_e32 v100, v2
	v_mov_b32_e32 v101, v2
	v_mov_b32_e32 v102, v2
	v_mov_b32_e32 v103, v2
	v_mov_b32_e32 v104, v2
	v_mov_b32_e32 v105, v2
	v_mov_b32_e32 v114, v2
	v_mov_b32_e32 v115, v2
	v_mov_b32_e32 v116, v2
	v_mov_b32_e32 v117, v2
	v_mov_b32_e32 v118, v2
	v_mov_b32_e32 v119, v2
	v_mov_b32_e32 v120, v2
	v_mov_b32_e32 v121, v2
	v_mov_b32_e32 v130, v2
	v_mov_b32_e32 v131, v2
	v_mov_b32_e32 v132, v2
	v_mov_b32_e32 v133, v2
	v_mov_b32_e32 v134, v2
	v_mov_b32_e32 v135, v2
	v_mov_b32_e32 v136, v2
	v_mov_b32_e32 v137, v2
	v_mov_b32_e32 v90, v2
	v_mov_b32_e32 v91, v2
	v_mov_b32_e32 v92, v2
	v_mov_b32_e32 v93, v2
	v_mov_b32_e32 v94, v2
	v_mov_b32_e32 v95, v2
	v_mov_b32_e32 v96, v2
	v_mov_b32_e32 v97, v2
	v_mov_b32_e32 v106, v2
	v_mov_b32_e32 v107, v2
	v_mov_b32_e32 v108, v2
	v_mov_b32_e32 v109, v2
	v_mov_b32_e32 v110, v2
	v_mov_b32_e32 v111, v2
	v_mov_b32_e32 v112, v2
	v_mov_b32_e32 v113, v2
	v_mov_b32_e32 v122, v2
	v_mov_b32_e32 v123, v2
	v_mov_b32_e32 v124, v2
	v_mov_b32_e32 v125, v2
	v_mov_b32_e32 v126, v2
	v_mov_b32_e32 v127, v2
	v_mov_b32_e32 v128, v2
	v_mov_b32_e32 v129, v2
	v_mov_b32_e32 v138, v2
	v_mov_b32_e32 v139, v2
	v_mov_b32_e32 v140, v2
	v_mov_b32_e32 v141, v2
	v_mov_b32_e32 v142, v2
	v_mov_b32_e32 v143, v2
	v_mov_b32_e32 v144, v2
	v_mov_b32_e32 v145, v2
	v_readfirstlane_b32 s84, v224
	s_bitcmp1_b32 s84, 8
	s_cbranch_scc0 .Lsprio_0
	s_setprio 1
.Lsprio_0:
.LBB0_226:
	s_add_u32 s22, s20, 0xfffc0080
	s_addc_u32 s23, s21, -1
	s_add_i32 s49, 0, 0x10000
	s_cmp_eq_u32 s48, 12
	s_cselect_b32 s25, s15, s23
	s_cselect_b32 s24, s44, s22
	s_cselect_b32 s23, s13, s47
	s_cselect_b32 s22, s45, s46
	s_add_i32 s52, 0, 0x14000
	v_add_u32_e32 v46, s49, v164
	v_add_u32_e32 v171, s52, v164
	ds_read_b128 v[34:37], v46
	ds_read_b128 v[38:41], v46 offset:1024
	ds_read_b128 v[42:45], v46 offset:2048
	ds_read_b128 v[46:49], v46 offset:3072
	ds_read_b128 v[160:163], v171
	ds_read_b128 v[172:175], v171 offset:1024
	ds_read_b128 v[176:179], v171 offset:2048
	ds_read_b128 v[180:183], v171 offset:3072
	v_lshl_add_u64 v[216:217], s[20:21], 0, v[156:157]
	s_add_i32 m0, s31, 0xc000
	ds_read_b128 v[184:187], v169
	ds_read_b128 v[188:191], v169 offset:1024
	ds_read_b128 v[192:195], v169 offset:2048
	ds_read_b128 v[196:199], v169 offset:3072
	ds_read_b128 v[200:203], v169 offset:4096
	ds_read_b128 v[204:207], v169 offset:5120
	ds_read_b128 v[208:211], v169 offset:6144
	ds_read_b128 v[212:215], v169 offset:7168
	global_load_lds_dwordx4 v[216:217], off
	v_lshl_add_u64 v[216:217], s[20:21], 0, v[158:159]
	s_add_i32 m0, s31, 0xe000
	s_nop 0
	global_load_lds_dwordx4 v[216:217], off
	s_waitcnt vmcnt(8)
	s_waitcnt lgkmcnt(0)
	s_barrier
	s_waitcnt lgkmcnt(0)
	v_mfma_f32_16x16x32_bf16 v[142:145], v[34:37], v[184:187], v[142:145]
	v_mfma_f32_16x16x32_bf16 v[138:141], v[42:45], v[184:187], v[138:141]
	v_mfma_f32_16x16x32_bf16 v[126:129], v[34:37], v[192:195], v[126:129]
	v_mfma_f32_16x16x32_bf16 v[122:125], v[42:45], v[192:195], v[122:125]
	v_mfma_f32_16x16x32_bf16 v[110:113], v[34:37], v[200:203], v[110:113]
	v_mfma_f32_16x16x32_bf16 v[106:109], v[42:45], v[200:203], v[106:109]
	v_mfma_f32_16x16x32_bf16 v[94:97], v[34:37], v[208:211], v[94:97]
	v_mfma_f32_16x16x32_bf16 v[90:93], v[42:45], v[208:211], v[90:93]
	v_mfma_f32_16x16x32_bf16 v[142:145], v[38:41], v[188:191], v[142:145]
	v_mfma_f32_16x16x32_bf16 v[138:141], v[46:49], v[188:191], v[138:141]
	v_mfma_f32_16x16x32_bf16 v[126:129], v[38:41], v[196:199], v[126:129]
	v_mfma_f32_16x16x32_bf16 v[122:125], v[46:49], v[196:199], v[122:125]
	v_mfma_f32_16x16x32_bf16 v[110:113], v[38:41], v[204:207], v[110:113]
	v_mfma_f32_16x16x32_bf16 v[106:109], v[46:49], v[204:207], v[106:109]
	v_mfma_f32_16x16x32_bf16 v[94:97], v[38:41], v[212:215], v[94:97]
	v_mfma_f32_16x16x32_bf16 v[90:93], v[46:49], v[212:215], v[90:93]
	v_mfma_f32_16x16x32_bf16 v[134:137], v[160:163], v[184:187], v[134:137]
	v_mfma_f32_16x16x32_bf16 v[130:133], v[176:179], v[184:187], v[130:133]
	v_mfma_f32_16x16x32_bf16 v[118:121], v[160:163], v[192:195], v[118:121]
	v_mfma_f32_16x16x32_bf16 v[114:117], v[176:179], v[192:195], v[114:117]
	v_mfma_f32_16x16x32_bf16 v[102:105], v[160:163], v[200:203], v[102:105]
	v_mfma_f32_16x16x32_bf16 v[98:101], v[176:179], v[200:203], v[98:101]
	v_mfma_f32_16x16x32_bf16 v[86:89], v[160:163], v[208:211], v[86:89]
	v_mfma_f32_16x16x32_bf16 v[82:85], v[176:179], v[208:211], v[82:85]
	v_mfma_f32_16x16x32_bf16 v[134:137], v[172:175], v[188:191], v[134:137]
	v_mfma_f32_16x16x32_bf16 v[130:133], v[180:183], v[188:191], v[130:133]
	v_mfma_f32_16x16x32_bf16 v[118:121], v[172:175], v[196:199], v[118:121]
	v_mfma_f32_16x16x32_bf16 v[114:117], v[180:183], v[196:199], v[114:117]
	v_mfma_f32_16x16x32_bf16 v[102:105], v[172:175], v[204:207], v[102:105]
	v_mfma_f32_16x16x32_bf16 v[98:101], v[180:183], v[204:207], v[98:101]
	v_mfma_f32_16x16x32_bf16 v[86:89], v[172:175], v[212:215], v[86:89]
	v_mfma_f32_16x16x32_bf16 v[82:85], v[180:183], v[212:215], v[82:85]
	s_barrier
	s_add_i32 s49, s49, s30
	v_lshl_add_u64 v[216:217], s[22:23], 0, v[152:153]
	s_mov_b32 m0, s49
	ds_read_b128 v[184:187], v169 offset:16384
	ds_read_b128 v[188:191], v169 offset:17408
	ds_read_b128 v[192:195], v169 offset:18432
	ds_read_b128 v[196:199], v169 offset:19456
	ds_read_b128 v[200:203], v169 offset:20480
	ds_read_b128 v[204:207], v169 offset:21504
	ds_read_b128 v[208:211], v169 offset:22528
	ds_read_b128 v[212:215], v169 offset:23552
	global_load_lds_dwordx4 v[216:217], off
	s_add_i32 m0, s49, 0x2000
	s_add_u32 s50, s22, 0x40000
	v_lshl_add_u64 v[218:219], s[22:23], 0, v[148:149]
	s_addc_u32 s51, s23, 0
	s_add_i32 s49, s52, s30
	global_load_lds_dwordx4 v[218:219], off
	v_lshl_add_u64 v[220:221], s[50:51], 0, v[152:153]
	s_mov_b32 m0, s49
	v_lshl_add_u64 v[222:223], s[24:25], 0, v[150:151]
	global_load_lds_dwordx4 v[220:221], off
	v_lshl_add_u64 v[220:221], s[50:51], 0, v[148:149]
	s_add_i32 m0, s49, 0x2000
	s_nop 0
	global_load_lds_dwordx4 v[220:221], off
	v_lshl_add_u64 v[220:221], s[24:25], 0, v[154:155]
	s_mov_b32 m0, s31
	s_nop 0
	global_load_lds_dwordx4 v[220:221], off
	s_mov_b32 m0, s34
	s_nop 0
	global_load_lds_dwordx4 v[222:223], off
	s_waitcnt vmcnt(8)
	s_waitcnt lgkmcnt(0)
	s_barrier
	s_waitcnt lgkmcnt(0)
	v_mfma_f32_16x16x32_bf16 v[78:81], v[34:37], v[184:187], v[78:81]
	v_mfma_f32_16x16x32_bf16 v[74:77], v[42:45], v[184:187], v[74:77]
	v_mfma_f32_16x16x32_bf16 v[62:65], v[34:37], v[192:195], v[62:65]
	v_mfma_f32_16x16x32_bf16 v[58:61], v[42:45], v[192:195], v[58:61]
	v_mfma_f32_16x16x32_bf16 v[30:33], v[34:37], v[200:203], v[30:33]
	v_mfma_f32_16x16x32_bf16 v[26:29], v[42:45], v[200:203], v[26:29]
	v_mfma_f32_16x16x32_bf16 v[14:17], v[34:37], v[208:211], v[14:17]
	v_mfma_f32_16x16x32_bf16 v[10:13], v[42:45], v[208:211], v[10:13]
	v_mfma_f32_16x16x32_bf16 v[78:81], v[38:41], v[188:191], v[78:81]
	v_mfma_f32_16x16x32_bf16 v[74:77], v[46:49], v[188:191], v[74:77]
	v_mfma_f32_16x16x32_bf16 v[62:65], v[38:41], v[196:199], v[62:65]
	v_mfma_f32_16x16x32_bf16 v[58:61], v[46:49], v[196:199], v[58:61]
	v_mfma_f32_16x16x32_bf16 v[30:33], v[38:41], v[204:207], v[30:33]
	v_mfma_f32_16x16x32_bf16 v[26:29], v[46:49], v[204:207], v[26:29]
	v_mfma_f32_16x16x32_bf16 v[14:17], v[38:41], v[212:215], v[14:17]
	v_mfma_f32_16x16x32_bf16 v[10:13], v[46:49], v[212:215], v[10:13]
	v_mfma_f32_16x16x32_bf16 v[22:25], v[160:163], v[200:203], v[22:25]
	v_mfma_f32_16x16x32_bf16 v[18:21], v[176:179], v[200:203], v[18:21]
	v_mfma_f32_16x16x32_bf16 v[6:9], v[160:163], v[208:211], v[6:9]
	v_mfma_f32_16x16x32_bf16 v[2:5], v[176:179], v[208:211], v[2:5]
	v_mfma_f32_16x16x32_bf16 v[34:37], v[160:163], v[184:187], v[70:73]
	v_mfma_f32_16x16x32_bf16 v[38:41], v[176:179], v[184:187], v[66:69]
	v_mfma_f32_16x16x32_bf16 v[42:45], v[160:163], v[192:195], v[54:57]
	v_mfma_f32_16x16x32_bf16 v[46:49], v[176:179], v[192:195], v[50:53]
	v_mfma_f32_16x16x32_bf16 v[22:25], v[172:175], v[204:207], v[22:25]
	v_mfma_f32_16x16x32_bf16 v[18:21], v[180:183], v[204:207], v[18:21]
	v_mfma_f32_16x16x32_bf16 v[6:9], v[172:175], v[212:215], v[6:9]
	v_mfma_f32_16x16x32_bf16 v[2:5], v[180:183], v[212:215], v[2:5]
	v_mfma_f32_16x16x32_bf16 v[34:37], v[172:175], v[188:191], v[34:37]
	v_mfma_f32_16x16x32_bf16 v[38:41], v[180:183], v[188:191], v[38:41]
	v_mfma_f32_16x16x32_bf16 v[42:45], v[172:175], v[196:199], v[42:45]
	v_mfma_f32_16x16x32_bf16 v[46:49], v[180:183], v[196:199], v[46:49]
	s_barrier
	s_add_i32 s49, 0, 0x18000
	s_add_i32 s50, 0, 0x1c000
	v_add_u32_e32 v70, s49, v164
	v_add_u32_e32 v171, s50, v164
	ds_read_b128 v[50:53], v70
	ds_read_b128 v[54:57], v70 offset:1024
	ds_read_b128 v[66:69], v70 offset:2048
	ds_read_b128 v[70:73], v70 offset:3072
	ds_read_b128 v[160:163], v171
	ds_read_b128 v[172:175], v171 offset:1024
	ds_read_b128 v[176:179], v171 offset:2048
	ds_read_b128 v[180:183], v171 offset:3072
	s_add_u32 s24, s24, 0x40000
	s_addc_u32 s25, s25, 0
	s_mov_b32 m0, s35
	v_lshl_add_u64 v[226:227], s[24:25], 0, v[154:155]
	ds_read_b128 v[184:187], v169 offset:32768
	ds_read_b128 v[188:191], v169 offset:33792
	ds_read_b128 v[192:195], v169 offset:34816
	ds_read_b128 v[196:199], v169 offset:35840
	ds_read_b128 v[200:203], v169 offset:36864
	ds_read_b128 v[204:207], v169 offset:37888
	ds_read_b128 v[208:211], v169 offset:38912
	ds_read_b128 v[212:215], v169 offset:39936
	global_load_lds_dwordx4 v[226:227], off
	v_lshl_add_u64 v[226:227], s[24:25], 0, v[150:151]
	s_mov_b32 m0, s36
	s_nop 0
	global_load_lds_dwordx4 v[226:227], off
	s_waitcnt vmcnt(8)
	s_waitcnt lgkmcnt(0)
	s_barrier
	s_waitcnt lgkmcnt(0)
	v_mfma_f32_16x16x32_bf16 v[142:145], v[50:53], v[184:187], v[142:145]
	v_mfma_f32_16x16x32_bf16 v[138:141], v[66:69], v[184:187], v[138:141]
	v_mfma_f32_16x16x32_bf16 v[126:129], v[50:53], v[192:195], v[126:129]
	v_mfma_f32_16x16x32_bf16 v[122:125], v[66:69], v[192:195], v[122:125]
	v_mfma_f32_16x16x32_bf16 v[110:113], v[50:53], v[200:203], v[110:113]
	v_mfma_f32_16x16x32_bf16 v[106:109], v[66:69], v[200:203], v[106:109]
	v_mfma_f32_16x16x32_bf16 v[94:97], v[50:53], v[208:211], v[94:97]
	v_mfma_f32_16x16x32_bf16 v[90:93], v[66:69], v[208:211], v[90:93]
	v_mfma_f32_16x16x32_bf16 v[142:145], v[54:57], v[188:191], v[142:145]
	v_mfma_f32_16x16x32_bf16 v[138:141], v[70:73], v[188:191], v[138:141]
	v_mfma_f32_16x16x32_bf16 v[126:129], v[54:57], v[196:199], v[126:129]
	v_mfma_f32_16x16x32_bf16 v[122:125], v[70:73], v[196:199], v[122:125]
	v_mfma_f32_16x16x32_bf16 v[110:113], v[54:57], v[204:207], v[110:113]
	v_mfma_f32_16x16x32_bf16 v[106:109], v[70:73], v[204:207], v[106:109]
	v_mfma_f32_16x16x32_bf16 v[94:97], v[54:57], v[212:215], v[94:97]
	v_mfma_f32_16x16x32_bf16 v[90:93], v[70:73], v[212:215], v[90:93]
	v_mfma_f32_16x16x32_bf16 v[134:137], v[160:163], v[184:187], v[134:137]
	v_mfma_f32_16x16x32_bf16 v[130:133], v[176:179], v[184:187], v[130:133]
	v_mfma_f32_16x16x32_bf16 v[118:121], v[160:163], v[192:195], v[118:121]
	v_mfma_f32_16x16x32_bf16 v[114:117], v[176:179], v[192:195], v[114:117]
	v_mfma_f32_16x16x32_bf16 v[102:105], v[160:163], v[200:203], v[102:105]
	v_mfma_f32_16x16x32_bf16 v[98:101], v[176:179], v[200:203], v[98:101]
	v_mfma_f32_16x16x32_bf16 v[86:89], v[160:163], v[208:211], v[86:89]
	v_mfma_f32_16x16x32_bf16 v[82:85], v[176:179], v[208:211], v[82:85]
	v_mfma_f32_16x16x32_bf16 v[134:137], v[172:175], v[188:191], v[134:137]
	v_mfma_f32_16x16x32_bf16 v[130:133], v[180:183], v[188:191], v[130:133]
	v_mfma_f32_16x16x32_bf16 v[118:121], v[172:175], v[196:199], v[118:121]
	v_mfma_f32_16x16x32_bf16 v[114:117], v[180:183], v[196:199], v[114:117]
	v_mfma_f32_16x16x32_bf16 v[102:105], v[172:175], v[204:207], v[102:105]
	v_mfma_f32_16x16x32_bf16 v[98:101], v[180:183], v[204:207], v[98:101]
	v_mfma_f32_16x16x32_bf16 v[86:89], v[172:175], v[212:215], v[86:89]
	v_mfma_f32_16x16x32_bf16 v[82:85], v[180:183], v[212:215], v[82:85]
	s_barrier
	s_add_i32 s24, s49, s30
	v_lshl_add_u64 v[216:217], v[216:217], 0, s[2:3]
	s_mov_b32 m0, s24
	ds_read_b128 v[184:187], v169 offset:49152
	ds_read_b128 v[188:191], v169 offset:50176
	ds_read_b128 v[192:195], v169 offset:51200
	ds_read_b128 v[196:199], v169 offset:52224
	ds_read_b128 v[200:203], v169 offset:53248
	ds_read_b128 v[204:207], v169 offset:54272
	ds_read_b128 v[208:211], v169 offset:55296
	ds_read_b128 v[212:215], v169 offset:56320
	global_load_lds_dwordx4 v[216:217], off
	s_add_i32 m0, s24, 0x2000
	s_add_u32 s22, s22, 0x40080
	v_lshl_add_u64 v[216:217], v[218:219], 0, s[2:3]
	s_addc_u32 s23, s23, 0
	s_add_i32 s24, s50, s30
	global_load_lds_dwordx4 v[216:217], off
	v_lshl_add_u64 v[216:217], s[22:23], 0, v[152:153]
	s_mov_b32 m0, s24
	s_nop 0
	global_load_lds_dwordx4 v[216:217], off
	v_lshl_add_u64 v[216:217], s[22:23], 0, v[148:149]
	s_add_i32 m0, s24, 0x2000
	s_nop 0
	global_load_lds_dwordx4 v[216:217], off
	v_lshl_add_u64 v[216:217], v[220:221], 0, s[2:3]
	s_mov_b32 m0, s39
	s_nop 0
	global_load_lds_dwordx4 v[216:217], off
	v_lshl_add_u64 v[216:217], v[222:223], 0, s[2:3]
	s_mov_b32 m0, s40
	s_nop 0
	global_load_lds_dwordx4 v[216:217], off
	s_waitcnt vmcnt(8)
	s_waitcnt lgkmcnt(0)
	s_barrier
	s_waitcnt lgkmcnt(0)
	v_mfma_f32_16x16x32_bf16 v[78:81], v[50:53], v[184:187], v[78:81]
	v_mfma_f32_16x16x32_bf16 v[74:77], v[66:69], v[184:187], v[74:77]
	v_mfma_f32_16x16x32_bf16 v[62:65], v[50:53], v[192:195], v[62:65]
	v_mfma_f32_16x16x32_bf16 v[58:61], v[66:69], v[192:195], v[58:61]
	v_mfma_f32_16x16x32_bf16 v[30:33], v[50:53], v[200:203], v[30:33]
	v_mfma_f32_16x16x32_bf16 v[26:29], v[66:69], v[200:203], v[26:29]
	v_mfma_f32_16x16x32_bf16 v[14:17], v[50:53], v[208:211], v[14:17]
	v_mfma_f32_16x16x32_bf16 v[10:13], v[66:69], v[208:211], v[10:13]
	v_mfma_f32_16x16x32_bf16 v[78:81], v[54:57], v[188:191], v[78:81]
	v_mfma_f32_16x16x32_bf16 v[74:77], v[70:73], v[188:191], v[74:77]
	v_mfma_f32_16x16x32_bf16 v[62:65], v[54:57], v[196:199], v[62:65]
	v_mfma_f32_16x16x32_bf16 v[58:61], v[70:73], v[196:199], v[58:61]
	v_mfma_f32_16x16x32_bf16 v[30:33], v[54:57], v[204:207], v[30:33]
	v_mfma_f32_16x16x32_bf16 v[26:29], v[70:73], v[204:207], v[26:29]
	v_mfma_f32_16x16x32_bf16 v[14:17], v[54:57], v[212:215], v[14:17]
	v_mfma_f32_16x16x32_bf16 v[10:13], v[70:73], v[212:215], v[10:13]
	v_mfma_f32_16x16x32_bf16 v[34:37], v[160:163], v[184:187], v[34:37]
	v_mfma_f32_16x16x32_bf16 v[70:73], v[172:175], v[188:191], v[34:37]
	v_mfma_f32_16x16x32_bf16 v[34:37], v[176:179], v[184:187], v[38:41]
	v_mfma_f32_16x16x32_bf16 v[66:69], v[180:183], v[188:191], v[34:37]
	v_mfma_f32_16x16x32_bf16 v[34:37], v[160:163], v[192:195], v[42:45]
	v_mfma_f32_16x16x32_bf16 v[54:57], v[172:175], v[196:199], v[34:37]
	v_mfma_f32_16x16x32_bf16 v[34:37], v[176:179], v[192:195], v[46:49]
	v_mfma_f32_16x16x32_bf16 v[22:25], v[160:163], v[200:203], v[22:25]
	v_mfma_f32_16x16x32_bf16 v[18:21], v[176:179], v[200:203], v[18:21]
	v_mfma_f32_16x16x32_bf16 v[6:9], v[160:163], v[208:211], v[6:9]
	v_mfma_f32_16x16x32_bf16 v[2:5], v[176:179], v[208:211], v[2:5]
	v_mfma_f32_16x16x32_bf16 v[50:53], v[180:183], v[196:199], v[34:37]
	v_mfma_f32_16x16x32_bf16 v[22:25], v[172:175], v[204:207], v[22:25]
	v_mfma_f32_16x16x32_bf16 v[18:21], v[180:183], v[204:207], v[18:21]
	v_mfma_f32_16x16x32_bf16 v[6:9], v[172:175], v[212:215], v[6:9]
	v_mfma_f32_16x16x32_bf16 v[2:5], v[180:183], v[212:215], v[2:5]
	s_barrier
	s_add_i32 s48, s48, 2
	s_add_u32 s20, s20, 0x100
	s_addc_u32 s21, s21, 0
	s_add_u32 s46, s46, 0x100
	s_addc_u32 s47, s47, 0
	s_cmp_gt_u32 s48, 13
	s_cbranch_scc0 .LBB0_226
	s_setprio 0
	s_and_b64 vcc, exec, s[10:11]
	s_cbranch_vccz .LBB0_229
	s_barrier

.LBB0_311:
	s_add_u32 s7, s36, 0x100
	v_mov_b32_e32 v2, 0
	s_addc_u32 s27, s37, 0
	s_mov_b32 s40, 2
	v_mov_b32_e32 v3, v2
	v_mov_b32_e32 v4, v2
	v_mov_b32_e32 v5, v2
	v_mov_b32_e32 v6, v2
	v_mov_b32_e32 v7, v2
	v_mov_b32_e32 v8, v2
	v_mov_b32_e32 v9, v2
	v_mov_b32_e32 v10, v2
	v_mov_b32_e32 v11, v2
	v_mov_b32_e32 v12, v2
	v_mov_b32_e32 v13, v2
	v_mov_b32_e32 v14, v2
	v_mov_b32_e32 v15, v2
	v_mov_b32_e32 v16, v2
	v_mov_b32_e32 v17, v2
	v_mov_b32_e32 v18, v2
	v_mov_b32_e32 v19, v2
	v_mov_b32_e32 v20, v2
	v_mov_b32_e32 v21, v2
	v_mov_b32_e32 v22, v2
	v_mov_b32_e32 v23, v2
	v_mov_b32_e32 v24, v2
	v_mov_b32_e32 v25, v2
	v_mov_b32_e32 v26, v2
	v_mov_b32_e32 v27, v2
	v_mov_b32_e32 v28, v2
	v_mov_b32_e32 v29, v2
	v_mov_b32_e32 v30, v2
	v_mov_b32_e32 v31, v2
	v_mov_b32_e32 v32, v2
	v_mov_b32_e32 v33, v2
	v_mov_b32_e32 v66, v2
	v_mov_b32_e32 v67, v2
	v_mov_b32_e32 v68, v2
	v_mov_b32_e32 v69, v2
	v_mov_b32_e32 v70, v2
	v_mov_b32_e32 v71, v2
	v_mov_b32_e32 v72, v2
	v_mov_b32_e32 v73, v2
	v_mov_b32_e32 v82, v2
	v_mov_b32_e32 v83, v2
	v_mov_b32_e32 v84, v2
	v_mov_b32_e32 v85, v2
	v_mov_b32_e32 v86, v2
	v_mov_b32_e32 v87, v2
	v_mov_b32_e32 v88, v2
	v_mov_b32_e32 v89, v2
	v_mov_b32_e32 v106, v2
	v_mov_b32_e32 v107, v2
	v_mov_b32_e32 v108, v2
	v_mov_b32_e32 v109, v2
	v_mov_b32_e32 v110, v2
	v_mov_b32_e32 v111, v2
	v_mov_b32_e32 v112, v2
	v_mov_b32_e32 v113, v2
	v_mov_b32_e32 v126, v2
	v_mov_b32_e32 v127, v2
	v_mov_b32_e32 v128, v2
	v_mov_b32_e32 v129, v2
	v_mov_b32_e32 v122, v2
	v_mov_b32_e32 v123, v2
	v_mov_b32_e32 v124, v2
	v_mov_b32_e32 v125, v2
	v_mov_b32_e32 v34, v2
	v_mov_b32_e32 v35, v2
	v_mov_b32_e32 v36, v2
	v_mov_b32_e32 v37, v2
	v_mov_b32_e32 v38, v2
	v_mov_b32_e32 v39, v2
	v_mov_b32_e32 v40, v2
	v_mov_b32_e32 v41, v2
	v_mov_b32_e32 v42, v2
	v_mov_b32_e32 v43, v2
	v_mov_b32_e32 v44, v2
	v_mov_b32_e32 v45, v2
	v_mov_b32_e32 v46, v2
	v_mov_b32_e32 v47, v2
	v_mov_b32_e32 v48, v2
	v_mov_b32_e32 v49, v2
	v_mov_b32_e32 v50, v2
	v_mov_b32_e32 v51, v2
	v_mov_b32_e32 v52, v2
	v_mov_b32_e32 v53, v2
	v_mov_b32_e32 v54, v2
	v_mov_b32_e32 v55, v2
	v_mov_b32_e32 v56, v2
	v_mov_b32_e32 v57, v2
	v_mov_b32_e32 v58, v2
	v_mov_b32_e32 v59, v2
	v_mov_b32_e32 v60, v2
	v_mov_b32_e32 v61, v2
	v_mov_b32_e32 v62, v2
	v_mov_b32_e32 v63, v2
	v_mov_b32_e32 v64, v2
	v_mov_b32_e32 v65, v2
	v_mov_b32_e32 v118, v2
	v_mov_b32_e32 v119, v2
	v_mov_b32_e32 v120, v2
	v_mov_b32_e32 v121, v2
	v_mov_b32_e32 v114, v2
	v_mov_b32_e32 v115, v2
	v_mov_b32_e32 v116, v2
	v_mov_b32_e32 v117, v2
	v_mov_b32_e32 v102, v2
	v_mov_b32_e32 v103, v2
	v_mov_b32_e32 v104, v2
	v_mov_b32_e32 v105, v2
	v_mov_b32_e32 v98, v2
	v_mov_b32_e32 v99, v2
	v_mov_b32_e32 v100, v2
	v_mov_b32_e32 v101, v2
	v_mov_b32_e32 v94, v2
	v_mov_b32_e32 v95, v2
	v_mov_b32_e32 v96, v2
	v_mov_b32_e32 v97, v2
	v_mov_b32_e32 v90, v2
	v_mov_b32_e32 v91, v2
	v_mov_b32_e32 v92, v2
	v_mov_b32_e32 v93, v2
	v_mov_b32_e32 v78, v2
	v_mov_b32_e32 v79, v2
	v_mov_b32_e32 v80, v2
	v_mov_b32_e32 v81, v2
	v_mov_b32_e32 v74, v2
	v_mov_b32_e32 v75, v2
	v_mov_b32_e32 v76, v2
	v_mov_b32_e32 v77, v2
	v_readfirstlane_b32 s84, v224
	s_bitcmp1_b32 s84, 8
	s_cbranch_scc0 .Lsprio_1
	s_setprio 1
.Lsprio_1:
.LBB0_312:
	s_add_u32 s4, s34, 0x100
	s_addc_u32 s5, s35, 0
	s_add_i32 s41, 0, 0x10000
	s_cmp_eq_u32 s70, s40
	s_cselect_b32 s39, s29, s5
	s_cselect_b32 s38, s28, s4
	s_cselect_b32 s37, s31, s27
	s_cselect_b32 s36, s30, s7
	s_add_i32 s42, 0, 0x14000
	v_add_u32_e32 v158, s41, v236
	v_add_u32_e32 v174, s42, v236
	ds_read_b128 v[130:133], v158
	ds_read_b128 v[134:137], v158 offset:1024
	ds_read_b128 v[154:157], v158 offset:2048
	ds_read_b128 v[158:161], v158 offset:3072
	ds_read_b128 v[162:165], v174
	ds_read_b128 v[166:169], v174 offset:1024
	ds_read_b128 v[170:173], v174 offset:2048
	ds_read_b128 v[174:177], v174 offset:3072
	v_lshl_add_u64 v[210:211], s[34:35], 0, v[150:151]
	s_add_i32 m0, s48, 0xc000
	ds_read_b128 v[178:181], v245
	ds_read_b128 v[182:185], v245 offset:1024
	ds_read_b128 v[186:189], v245 offset:2048
	ds_read_b128 v[190:193], v245 offset:3072
	ds_read_b128 v[194:197], v245 offset:4096
	ds_read_b128 v[198:201], v245 offset:5120
	ds_read_b128 v[202:205], v245 offset:6144
	ds_read_b128 v[206:209], v245 offset:7168
	global_load_lds_dwordx4 v[210:211], off
	v_lshl_add_u64 v[210:211], s[34:35], 0, v[152:153]
	s_add_i32 m0, s48, 0xe000
	s_nop 0
	global_load_lds_dwordx4 v[210:211], off
	s_waitcnt vmcnt(8)
	s_waitcnt lgkmcnt(0)
	s_barrier
	s_waitcnt lgkmcnt(0)
	v_mfma_f32_16x16x32_bf16 v[74:77], v[130:133], v[178:181], v[74:77]
	v_mfma_f32_16x16x32_bf16 v[78:81], v[154:157], v[178:181], v[78:81]
	v_mfma_f32_16x16x32_bf16 v[90:93], v[130:133], v[186:189], v[90:93]
	v_mfma_f32_16x16x32_bf16 v[94:97], v[154:157], v[186:189], v[94:97]
	v_mfma_f32_16x16x32_bf16 v[98:101], v[130:133], v[194:197], v[98:101]
	v_mfma_f32_16x16x32_bf16 v[102:105], v[154:157], v[194:197], v[102:105]
	v_mfma_f32_16x16x32_bf16 v[114:117], v[130:133], v[202:205], v[114:117]
	v_mfma_f32_16x16x32_bf16 v[118:121], v[154:157], v[202:205], v[118:121]
	v_mfma_f32_16x16x32_bf16 v[74:77], v[134:137], v[182:185], v[74:77]
	v_mfma_f32_16x16x32_bf16 v[78:81], v[158:161], v[182:185], v[78:81]
	v_mfma_f32_16x16x32_bf16 v[90:93], v[134:137], v[190:193], v[90:93]
	v_mfma_f32_16x16x32_bf16 v[94:97], v[158:161], v[190:193], v[94:97]
	v_mfma_f32_16x16x32_bf16 v[98:101], v[134:137], v[198:201], v[98:101]
	v_mfma_f32_16x16x32_bf16 v[102:105], v[158:161], v[198:201], v[102:105]
	v_mfma_f32_16x16x32_bf16 v[114:117], v[134:137], v[206:209], v[114:117]
	v_mfma_f32_16x16x32_bf16 v[118:121], v[158:161], v[206:209], v[118:121]
	v_mfma_f32_16x16x32_bf16 v[62:65], v[162:165], v[178:181], v[62:65]
	v_mfma_f32_16x16x32_bf16 v[58:61], v[170:173], v[178:181], v[58:61]
	v_mfma_f32_16x16x32_bf16 v[54:57], v[162:165], v[186:189], v[54:57]
	v_mfma_f32_16x16x32_bf16 v[50:53], v[170:173], v[186:189], v[50:53]
	v_mfma_f32_16x16x32_bf16 v[46:49], v[162:165], v[194:197], v[46:49]
	v_mfma_f32_16x16x32_bf16 v[42:45], v[170:173], v[194:197], v[42:45]
	v_mfma_f32_16x16x32_bf16 v[38:41], v[162:165], v[202:205], v[38:41]
	v_mfma_f32_16x16x32_bf16 v[34:37], v[170:173], v[202:205], v[34:37]
	v_mfma_f32_16x16x32_bf16 v[62:65], v[166:169], v[182:185], v[62:65]
	v_mfma_f32_16x16x32_bf16 v[58:61], v[174:177], v[182:185], v[58:61]
	v_mfma_f32_16x16x32_bf16 v[54:57], v[166:169], v[190:193], v[54:57]
	v_mfma_f32_16x16x32_bf16 v[50:53], v[174:177], v[190:193], v[50:53]
	v_mfma_f32_16x16x32_bf16 v[46:49], v[166:169], v[198:201], v[46:49]
	v_mfma_f32_16x16x32_bf16 v[42:45], v[174:177], v[198:201], v[42:45]
	v_mfma_f32_16x16x32_bf16 v[38:41], v[166:169], v[206:209], v[38:41]
	v_mfma_f32_16x16x32_bf16 v[34:37], v[174:177], v[206:209], v[34:37]
	s_barrier
	s_add_i32 s34, s41, s33
	v_lshl_add_u64 v[210:211], s[36:37], 0, v[140:141]
	s_mov_b32 m0, s34
	ds_read_b128 v[178:181], v245 offset:16384
	ds_read_b128 v[182:185], v245 offset:17408
	ds_read_b128 v[186:189], v245 offset:18432
	ds_read_b128 v[190:193], v245 offset:19456
	ds_read_b128 v[194:197], v245 offset:20480
	ds_read_b128 v[198:201], v245 offset:21504
	ds_read_b128 v[202:205], v245 offset:22528
	ds_read_b128 v[206:209], v245 offset:23552
	global_load_lds_dwordx4 v[210:211], off
	s_add_i32 m0, s34, 0x2000
	s_add_u32 s34, s36, 0xb0000
	v_lshl_add_u64 v[212:213], s[36:37], 0, v[144:145]
	s_addc_u32 s35, s37, 0
	s_add_i32 s41, s42, s33
	global_load_lds_dwordx4 v[212:213], off
	v_lshl_add_u64 v[214:215], s[34:35], 0, v[140:141]
	s_mov_b32 m0, s41
	v_lshl_add_u64 v[216:217], s[38:39], 0, v[142:143]
	global_load_lds_dwordx4 v[214:215], off
	v_lshl_add_u64 v[214:215], s[34:35], 0, v[144:145]
	s_add_i32 m0, s41, 0x2000
	s_nop 0
	global_load_lds_dwordx4 v[214:215], off
	v_lshl_add_u64 v[214:215], s[38:39], 0, v[138:139]
	s_mov_b32 m0, s48
	s_nop 0
	global_load_lds_dwordx4 v[214:215], off
	s_mov_b32 m0, s49
	s_nop 0
	global_load_lds_dwordx4 v[216:217], off
	s_waitcnt vmcnt(8)
	s_waitcnt lgkmcnt(0)
	s_barrier
	s_waitcnt lgkmcnt(0)
	v_mfma_f32_16x16x32_bf16 v[122:125], v[130:133], v[178:181], v[122:125]
	v_mfma_f32_16x16x32_bf16 v[126:129], v[154:157], v[178:181], v[126:129]
	v_mfma_f32_16x16x32_bf16 v[110:113], v[130:133], v[186:189], v[110:113]
	v_mfma_f32_16x16x32_bf16 v[106:109], v[154:157], v[186:189], v[106:109]
	v_mfma_f32_16x16x32_bf16 v[86:89], v[130:133], v[194:197], v[86:89]
	v_mfma_f32_16x16x32_bf16 v[82:85], v[154:157], v[194:197], v[82:85]
	v_mfma_f32_16x16x32_bf16 v[70:73], v[130:133], v[202:205], v[70:73]
	v_mfma_f32_16x16x32_bf16 v[66:69], v[154:157], v[202:205], v[66:69]
	v_mfma_f32_16x16x32_bf16 v[122:125], v[134:137], v[182:185], v[122:125]
	v_mfma_f32_16x16x32_bf16 v[126:129], v[158:161], v[182:185], v[126:129]
	v_mfma_f32_16x16x32_bf16 v[110:113], v[134:137], v[190:193], v[110:113]
	v_mfma_f32_16x16x32_bf16 v[106:109], v[158:161], v[190:193], v[106:109]
	v_mfma_f32_16x16x32_bf16 v[86:89], v[134:137], v[198:201], v[86:89]
	v_mfma_f32_16x16x32_bf16 v[82:85], v[158:161], v[198:201], v[82:85]
	v_mfma_f32_16x16x32_bf16 v[70:73], v[134:137], v[206:209], v[70:73]
	v_mfma_f32_16x16x32_bf16 v[66:69], v[158:161], v[206:209], v[66:69]
	v_mfma_f32_16x16x32_bf16 v[30:33], v[162:165], v[178:181], v[30:33]
	v_mfma_f32_16x16x32_bf16 v[26:29], v[170:173], v[178:181], v[26:29]
	v_mfma_f32_16x16x32_bf16 v[22:25], v[162:165], v[186:189], v[22:25]
	v_mfma_f32_16x16x32_bf16 v[18:21], v[170:173], v[186:189], v[18:21]
	v_mfma_f32_16x16x32_bf16 v[14:17], v[162:165], v[194:197], v[14:17]
	v_mfma_f32_16x16x32_bf16 v[10:13], v[170:173], v[194:197], v[10:13]
	v_mfma_f32_16x16x32_bf16 v[6:9], v[162:165], v[202:205], v[6:9]
	v_mfma_f32_16x16x32_bf16 v[2:5], v[170:173], v[202:205], v[2:5]
	v_mfma_f32_16x16x32_bf16 v[30:33], v[166:169], v[182:185], v[30:33]
	v_mfma_f32_16x16x32_bf16 v[26:29], v[174:177], v[182:185], v[26:29]
	v_mfma_f32_16x16x32_bf16 v[22:25], v[166:169], v[190:193], v[22:25]
	v_mfma_f32_16x16x32_bf16 v[18:21], v[174:177], v[190:193], v[18:21]
	v_mfma_f32_16x16x32_bf16 v[14:17], v[166:169], v[198:201], v[14:17]
	v_mfma_f32_16x16x32_bf16 v[10:13], v[174:177], v[198:201], v[10:13]
	v_mfma_f32_16x16x32_bf16 v[6:9], v[166:169], v[206:209], v[6:9]
	v_mfma_f32_16x16x32_bf16 v[2:5], v[174:177], v[206:209], v[2:5]
	s_barrier
	s_add_i32 s41, 0, 0x18000
	s_add_i32 s42, 0, 0x1c000
	v_add_u32_e32 v158, s41, v236
	v_add_u32_e32 v174, s42, v236
	ds_read_b128 v[130:133], v158
	ds_read_b128 v[134:137], v158 offset:1024
	ds_read_b128 v[154:157], v158 offset:2048
	ds_read_b128 v[158:161], v158 offset:3072
	ds_read_b128 v[162:165], v174
	ds_read_b128 v[166:169], v174 offset:1024
	ds_read_b128 v[170:173], v174 offset:2048
	ds_read_b128 v[174:177], v174 offset:3072
	s_add_u32 s34, s38, 0xb0000
	s_addc_u32 s35, s39, 0
	s_mov_b32 m0, s54
	v_lshl_add_u64 v[218:219], s[34:35], 0, v[138:139]
	ds_read_b128 v[178:181], v245 offset:32768
	ds_read_b128 v[182:185], v245 offset:33792
	ds_read_b128 v[186:189], v245 offset:34816
	ds_read_b128 v[190:193], v245 offset:35840
	ds_read_b128 v[194:197], v245 offset:36864
	ds_read_b128 v[198:201], v245 offset:37888
	ds_read_b128 v[202:205], v245 offset:38912
	ds_read_b128 v[206:209], v245 offset:39936
	global_load_lds_dwordx4 v[218:219], off
	v_lshl_add_u64 v[218:219], s[34:35], 0, v[142:143]
	s_mov_b32 m0, s55
	s_nop 0
	global_load_lds_dwordx4 v[218:219], off
	s_waitcnt vmcnt(8)
	s_waitcnt lgkmcnt(0)
	s_barrier
	s_waitcnt lgkmcnt(0)
	v_mfma_f32_16x16x32_bf16 v[74:77], v[130:133], v[178:181], v[74:77]
	v_mfma_f32_16x16x32_bf16 v[78:81], v[154:157], v[178:181], v[78:81]
	v_mfma_f32_16x16x32_bf16 v[90:93], v[130:133], v[186:189], v[90:93]
	v_mfma_f32_16x16x32_bf16 v[94:97], v[154:157], v[186:189], v[94:97]
	v_mfma_f32_16x16x32_bf16 v[98:101], v[130:133], v[194:197], v[98:101]
	v_mfma_f32_16x16x32_bf16 v[102:105], v[154:157], v[194:197], v[102:105]
	v_mfma_f32_16x16x32_bf16 v[114:117], v[130:133], v[202:205], v[114:117]
	v_mfma_f32_16x16x32_bf16 v[118:121], v[154:157], v[202:205], v[118:121]
	v_mfma_f32_16x16x32_bf16 v[74:77], v[134:137], v[182:185], v[74:77]
	v_mfma_f32_16x16x32_bf16 v[78:81], v[158:161], v[182:185], v[78:81]
	v_mfma_f32_16x16x32_bf16 v[90:93], v[134:137], v[190:193], v[90:93]
	v_mfma_f32_16x16x32_bf16 v[94:97], v[158:161], v[190:193], v[94:97]
	v_mfma_f32_16x16x32_bf16 v[98:101], v[134:137], v[198:201], v[98:101]
	v_mfma_f32_16x16x32_bf16 v[102:105], v[158:161], v[198:201], v[102:105]
	v_mfma_f32_16x16x32_bf16 v[114:117], v[134:137], v[206:209], v[114:117]
	v_mfma_f32_16x16x32_bf16 v[118:121], v[158:161], v[206:209], v[118:121]
	v_mfma_f32_16x16x32_bf16 v[62:65], v[162:165], v[178:181], v[62:65]
	v_mfma_f32_16x16x32_bf16 v[58:61], v[170:173], v[178:181], v[58:61]
	v_mfma_f32_16x16x32_bf16 v[54:57], v[162:165], v[186:189], v[54:57]
	v_mfma_f32_16x16x32_bf16 v[50:53], v[170:173], v[186:189], v[50:53]
	v_mfma_f32_16x16x32_bf16 v[46:49], v[162:165], v[194:197], v[46:49]
	v_mfma_f32_16x16x32_bf16 v[42:45], v[170:173], v[194:197], v[42:45]
	v_mfma_f32_16x16x32_bf16 v[38:41], v[162:165], v[202:205], v[38:41]
	v_mfma_f32_16x16x32_bf16 v[34:37], v[170:173], v[202:205], v[34:37]
	v_mfma_f32_16x16x32_bf16 v[62:65], v[166:169], v[182:185], v[62:65]
	v_mfma_f32_16x16x32_bf16 v[58:61], v[174:177], v[182:185], v[58:61]
	v_mfma_f32_16x16x32_bf16 v[54:57], v[166:169], v[190:193], v[54:57]
	v_mfma_f32_16x16x32_bf16 v[50:53], v[174:177], v[190:193], v[50:53]
	v_mfma_f32_16x16x32_bf16 v[46:49], v[166:169], v[198:201], v[46:49]
	v_mfma_f32_16x16x32_bf16 v[42:45], v[174:177], v[198:201], v[42:45]
	v_mfma_f32_16x16x32_bf16 v[38:41], v[166:169], v[206:209], v[38:41]
	v_mfma_f32_16x16x32_bf16 v[34:37], v[174:177], v[206:209], v[34:37]
	s_barrier
	s_add_i32 s34, s41, s33
	v_lshl_add_u64 v[210:211], v[210:211], 0, s[2:3]
	s_mov_b32 m0, s34
	ds_read_b128 v[178:181], v245 offset:49152
	ds_read_b128 v[182:185], v245 offset:50176
	ds_read_b128 v[186:189], v245 offset:51200
	ds_read_b128 v[190:193], v245 offset:52224
	ds_read_b128 v[194:197], v245 offset:53248
	ds_read_b128 v[198:201], v245 offset:54272
	ds_read_b128 v[202:205], v245 offset:55296
	ds_read_b128 v[206:209], v245 offset:56320
	global_load_lds_dwordx4 v[210:211], off
	s_add_i32 m0, s34, 0x2000
	s_add_u32 s34, s36, 0xb0080
	v_lshl_add_u64 v[210:211], v[212:213], 0, s[2:3]
	s_addc_u32 s35, s37, 0
	s_add_i32 s36, s42, s33
	global_load_lds_dwordx4 v[210:211], off
	v_lshl_add_u64 v[210:211], s[34:35], 0, v[140:141]
	s_mov_b32 m0, s36
	s_nop 0
	global_load_lds_dwordx4 v[210:211], off
	v_lshl_add_u64 v[210:211], s[34:35], 0, v[144:145]
	s_add_i32 m0, s36, 0x2000
	s_nop 0
	global_load_lds_dwordx4 v[210:211], off
	v_lshl_add_u64 v[210:211], v[214:215], 0, s[2:3]
	s_mov_b32 m0, s62
	s_nop 0
	global_load_lds_dwordx4 v[210:211], off
	v_lshl_add_u64 v[210:211], v[216:217], 0, s[2:3]
	s_mov_b32 m0, s63
	s_nop 0
	global_load_lds_dwordx4 v[210:211], off
	s_waitcnt vmcnt(8)
	s_waitcnt lgkmcnt(0)
	s_barrier
	s_waitcnt lgkmcnt(0)
	v_mfma_f32_16x16x32_bf16 v[122:125], v[130:133], v[178:181], v[122:125]
	v_mfma_f32_16x16x32_bf16 v[126:129], v[154:157], v[178:181], v[126:129]
	v_mfma_f32_16x16x32_bf16 v[110:113], v[130:133], v[186:189], v[110:113]
	v_mfma_f32_16x16x32_bf16 v[106:109], v[154:157], v[186:189], v[106:109]
	v_mfma_f32_16x16x32_bf16 v[86:89], v[130:133], v[194:197], v[86:89]
	v_mfma_f32_16x16x32_bf16 v[82:85], v[154:157], v[194:197], v[82:85]
	v_mfma_f32_16x16x32_bf16 v[70:73], v[130:133], v[202:205], v[70:73]
	v_mfma_f32_16x16x32_bf16 v[66:69], v[154:157], v[202:205], v[66:69]
	v_mfma_f32_16x16x32_bf16 v[122:125], v[134:137], v[182:185], v[122:125]
	v_mfma_f32_16x16x32_bf16 v[126:129], v[158:161], v[182:185], v[126:129]
	v_mfma_f32_16x16x32_bf16 v[110:113], v[134:137], v[190:193], v[110:113]
	v_mfma_f32_16x16x32_bf16 v[106:109], v[158:161], v[190:193], v[106:109]
	v_mfma_f32_16x16x32_bf16 v[86:89], v[134:137], v[198:201], v[86:89]
	v_mfma_f32_16x16x32_bf16 v[82:85], v[158:161], v[198:201], v[82:85]
	v_mfma_f32_16x16x32_bf16 v[70:73], v[134:137], v[206:209], v[70:73]
	v_mfma_f32_16x16x32_bf16 v[66:69], v[158:161], v[206:209], v[66:69]
	v_mfma_f32_16x16x32_bf16 v[30:33], v[162:165], v[178:181], v[30:33]
	v_mfma_f32_16x16x32_bf16 v[26:29], v[170:173], v[178:181], v[26:29]
	v_mfma_f32_16x16x32_bf16 v[22:25], v[162:165], v[186:189], v[22:25]
	v_mfma_f32_16x16x32_bf16 v[18:21], v[170:173], v[186:189], v[18:21]
	v_mfma_f32_16x16x32_bf16 v[14:17], v[162:165], v[194:197], v[14:17]
	v_mfma_f32_16x16x32_bf16 v[10:13], v[170:173], v[194:197], v[10:13]
	v_mfma_f32_16x16x32_bf16 v[6:9], v[162:165], v[202:205], v[6:9]
	v_mfma_f32_16x16x32_bf16 v[2:5], v[170:173], v[202:205], v[2:5]
	v_mfma_f32_16x16x32_bf16 v[30:33], v[166:169], v[182:185], v[30:33]
	v_mfma_f32_16x16x32_bf16 v[26:29], v[174:177], v[182:185], v[26:29]
	v_mfma_f32_16x16x32_bf16 v[22:25], v[166:169], v[190:193], v[22:25]
	v_mfma_f32_16x16x32_bf16 v[18:21], v[174:177], v[190:193], v[18:21]
	v_mfma_f32_16x16x32_bf16 v[14:17], v[166:169], v[198:201], v[14:17]
	v_mfma_f32_16x16x32_bf16 v[10:13], v[174:177], v[198:201], v[10:13]
	v_mfma_f32_16x16x32_bf16 v[6:9], v[166:169], v[206:209], v[6:9]
	v_mfma_f32_16x16x32_bf16 v[2:5], v[174:177], v[206:209], v[2:5]
	s_barrier
	s_add_i32 s36, s40, 2
	s_add_u32 s7, s7, 0x100
	s_addc_u32 s27, s27, 0
	s_cmp_ge_i32 s40, s70
	s_mov_b64 s[34:35], s[4:5]
	s_mov_b32 s40, s36
	s_cbranch_scc0 .LBB0_312
	s_setprio 0
	s_and_b64 vcc, exec, s[22:23]
	s_cbranch_vccz .LBB0_315
	s_barrier

.LBB0_549:
	s_ashr_i32 s11, s10, 31
	s_lshl_b64 s[14:15], s[10:11], 19
	s_add_u32 s14, s24, s14
	s_addc_u32 s15, s25, s15
	s_and_b64 s[16:17], s[0:1], exec
	s_cselect_b32 s11, s15, s19
	s_cselect_b32 s44, s14, s18
	s_ashr_i32 s13, s12, 31
	s_lshl_b64 s[16:17], s[12:13], 19
	s_add_u32 s16, s26, s16
	s_addc_u32 s17, s27, s17
	s_and_b64 s[22:23], s[0:1], exec
	s_cselect_b32 s13, s17, s21
	s_cselect_b32 s45, s16, s20
	s_add_u32 s18, s18, 0x40080
	s_addc_u32 s19, s19, 0
	s_add_u32 s46, s20, 0x100
	v_mov_b32_e32 v2, 0
	s_addc_u32 s47, s21, 0
	s_mov_b32 s48, -2
	v_mov_b32_e32 v3, v2
	v_mov_b32_e32 v4, v2
	v_mov_b32_e32 v5, v2
	v_mov_b32_e32 v6, v2
	v_mov_b32_e32 v7, v2
	v_mov_b32_e32 v8, v2
	v_mov_b32_e32 v9, v2
	v_mov_b32_e32 v18, v2
	v_mov_b32_e32 v19, v2
	v_mov_b32_e32 v20, v2
	v_mov_b32_e32 v21, v2
	v_mov_b32_e32 v22, v2
	v_mov_b32_e32 v23, v2
	v_mov_b32_e32 v24, v2
	v_mov_b32_e32 v25, v2
	v_mov_b32_e32 v34, v2
	v_mov_b32_e32 v35, v2
	v_mov_b32_e32 v36, v2
	v_mov_b32_e32 v37, v2
	v_mov_b32_e32 v38, v2
	v_mov_b32_e32 v39, v2
	v_mov_b32_e32 v40, v2
	v_mov_b32_e32 v41, v2
	v_mov_b32_e32 v50, v2
	v_mov_b32_e32 v51, v2
	v_mov_b32_e32 v52, v2
	v_mov_b32_e32 v53, v2
	v_mov_b32_e32 v54, v2
	v_mov_b32_e32 v55, v2
	v_mov_b32_e32 v56, v2
	v_mov_b32_e32 v57, v2
	v_mov_b32_e32 v10, v2
	v_mov_b32_e32 v11, v2
	v_mov_b32_e32 v12, v2
	v_mov_b32_e32 v13, v2
	v_mov_b32_e32 v14, v2
	v_mov_b32_e32 v15, v2
	v_mov_b32_e32 v16, v2
	v_mov_b32_e32 v17, v2
	v_mov_b32_e32 v26, v2
	v_mov_b32_e32 v27, v2
	v_mov_b32_e32 v28, v2
	v_mov_b32_e32 v29, v2
	v_mov_b32_e32 v30, v2
	v_mov_b32_e32 v31, v2
	v_mov_b32_e32 v32, v2
	v_mov_b32_e32 v33, v2
	v_mov_b32_e32 v42, v2
	v_mov_b32_e32 v43, v2
	v_mov_b32_e32 v44, v2
	v_mov_b32_e32 v45, v2
	v_mov_b32_e32 v46, v2
	v_mov_b32_e32 v47, v2
	v_mov_b32_e32 v48, v2
	v_mov_b32_e32 v49, v2
	v_mov_b32_e32 v58, v2
	v_mov_b32_e32 v59, v2
	v_mov_b32_e32 v60, v2
	v_mov_b32_e32 v61, v2
	v_mov_b32_e32 v62, v2
	v_mov_b32_e32 v63, v2
	v_mov_b32_e32 v64, v2
	v_mov_b32_e32 v65, v2
	v_mov_b32_e32 v66, v2
	v_mov_b32_e32 v67, v2
	v_mov_b32_e32 v68, v2
	v_mov_b32_e32 v69, v2
	v_mov_b32_e32 v70, v2
	v_mov_b32_e32 v71, v2
	v_mov_b32_e32 v72, v2
	v_mov_b32_e32 v73, v2
	v_mov_b32_e32 v82, v2
	v_mov_b32_e32 v83, v2
	v_mov_b32_e32 v84, v2
	v_mov_b32_e32 v85, v2
	v_mov_b32_e32 v86, v2
	v_mov_b32_e32 v87, v2
	v_mov_b32_e32 v88, v2
	v_mov_b32_e32 v89, v2
	v_mov_b32_e32 v98, v2
	v_mov_b32_e32 v99, v2
	v_mov_b32_e32 v100, v2
	v_mov_b32_e32 v101, v2
	v_mov_b32_e32 v102, v2
	v_mov_b32_e32 v103, v2
	v_mov_b32_e32 v104, v2
	v_mov_b32_e32 v105, v2
	v_mov_b32_e32 v114, v2
	v_mov_b32_e32 v115, v2
	v_mov_b32_e32 v116, v2
	v_mov_b32_e32 v117, v2
	v_mov_b32_e32 v118, v2
	v_mov_b32_e32 v119, v2
	v_mov_b32_e32 v120, v2
	v_mov_b32_e32 v121, v2
	v_mov_b32_e32 v74, v2
	v_mov_b32_e32 v75, v2
	v_mov_b32_e32 v76, v2
	v_mov_b32_e32 v77, v2
	v_mov_b32_e32 v78, v2
	v_mov_b32_e32 v79, v2
	v_mov_b32_e32 v80, v2
	v_mov_b32_e32 v81, v2
	v_mov_b32_e32 v90, v2
	v_mov_b32_e32 v91, v2
	v_mov_b32_e32 v92, v2
	v_mov_b32_e32 v93, v2
	v_mov_b32_e32 v94, v2
	v_mov_b32_e32 v95, v2
	v_mov_b32_e32 v96, v2
	v_mov_b32_e32 v97, v2
	v_mov_b32_e32 v106, v2
	v_mov_b32_e32 v107, v2
	v_mov_b32_e32 v108, v2
	v_mov_b32_e32 v109, v2
	v_mov_b32_e32 v110, v2
	v_mov_b32_e32 v111, v2
	v_mov_b32_e32 v112, v2
	v_mov_b32_e32 v113, v2
	v_mov_b32_e32 v122, v2
	v_mov_b32_e32 v123, v2
	v_mov_b32_e32 v124, v2
	v_mov_b32_e32 v125, v2
	v_mov_b32_e32 v126, v2
	v_mov_b32_e32 v127, v2
	v_mov_b32_e32 v128, v2
	v_mov_b32_e32 v129, v2
	v_readfirstlane_b32 s84, v224
	s_bitcmp1_b32 s84, 8
	s_cbranch_scc0 .Lsprio_2
	s_setprio 1
.Lsprio_2:
.LBB0_550:
	s_add_u32 s20, s18, 0xfffc0080
	s_addc_u32 s21, s19, -1
	s_add_i32 s49, 0, 0x10000
	s_cmp_eq_u32 s48, 12
	s_cselect_b32 s23, s11, s21
	s_cselect_b32 s22, s44, s20
	s_cselect_b32 s21, s13, s47
	s_cselect_b32 s20, s45, s46
	s_add_i32 s52, 0, 0x14000
	v_add_u32_e32 v142, s49, v157
	v_add_u32_e32 v162, s52, v157
	ds_read_b128 v[130:133], v142
	ds_read_b128 v[134:137], v142 offset:1024
	ds_read_b128 v[138:141], v142 offset:2048
	ds_read_b128 v[142:145], v142 offset:3072
	ds_read_b128 v[164:167], v162
	ds_read_b128 v[168:171], v162 offset:1024
	ds_read_b128 v[172:175], v162 offset:2048
	ds_read_b128 v[176:179], v162 offset:3072
	v_lshl_add_u64 v[212:213], s[18:19], 0, v[158:159]
	s_add_i32 m0, s29, 0xc000
	ds_read_b128 v[180:183], v163
	ds_read_b128 v[184:187], v163 offset:1024
	ds_read_b128 v[188:191], v163 offset:2048
	ds_read_b128 v[192:195], v163 offset:3072
	ds_read_b128 v[196:199], v163 offset:4096
	ds_read_b128 v[200:203], v163 offset:5120
	ds_read_b128 v[204:207], v163 offset:6144
	ds_read_b128 v[208:211], v163 offset:7168
	global_load_lds_dwordx4 v[212:213], off
	v_lshl_add_u64 v[212:213], s[18:19], 0, v[160:161]
	s_add_i32 m0, s29, 0xe000
	s_nop 0
	global_load_lds_dwordx4 v[212:213], off
	s_waitcnt vmcnt(8)
	s_waitcnt lgkmcnt(0)
	s_barrier
	s_waitcnt lgkmcnt(0)
	v_mfma_f32_16x16x32_bf16 v[126:129], v[130:133], v[180:183], v[126:129]
	v_mfma_f32_16x16x32_bf16 v[122:125], v[138:141], v[180:183], v[122:125]
	v_mfma_f32_16x16x32_bf16 v[110:113], v[130:133], v[188:191], v[110:113]
	v_mfma_f32_16x16x32_bf16 v[106:109], v[138:141], v[188:191], v[106:109]
	v_mfma_f32_16x16x32_bf16 v[94:97], v[130:133], v[196:199], v[94:97]
	v_mfma_f32_16x16x32_bf16 v[90:93], v[138:141], v[196:199], v[90:93]
	v_mfma_f32_16x16x32_bf16 v[78:81], v[130:133], v[204:207], v[78:81]
	v_mfma_f32_16x16x32_bf16 v[74:77], v[138:141], v[204:207], v[74:77]
	v_mfma_f32_16x16x32_bf16 v[126:129], v[134:137], v[184:187], v[126:129]
	v_mfma_f32_16x16x32_bf16 v[122:125], v[142:145], v[184:187], v[122:125]
	v_mfma_f32_16x16x32_bf16 v[110:113], v[134:137], v[192:195], v[110:113]
	v_mfma_f32_16x16x32_bf16 v[106:109], v[142:145], v[192:195], v[106:109]
	v_mfma_f32_16x16x32_bf16 v[94:97], v[134:137], v[200:203], v[94:97]
	v_mfma_f32_16x16x32_bf16 v[90:93], v[142:145], v[200:203], v[90:93]
	v_mfma_f32_16x16x32_bf16 v[78:81], v[134:137], v[208:211], v[78:81]
	v_mfma_f32_16x16x32_bf16 v[74:77], v[142:145], v[208:211], v[74:77]
	v_mfma_f32_16x16x32_bf16 v[118:121], v[164:167], v[180:183], v[118:121]
	v_mfma_f32_16x16x32_bf16 v[114:117], v[172:175], v[180:183], v[114:117]
	v_mfma_f32_16x16x32_bf16 v[102:105], v[164:167], v[188:191], v[102:105]
	v_mfma_f32_16x16x32_bf16 v[98:101], v[172:175], v[188:191], v[98:101]
	v_mfma_f32_16x16x32_bf16 v[86:89], v[164:167], v[196:199], v[86:89]
	v_mfma_f32_16x16x32_bf16 v[82:85], v[172:175], v[196:199], v[82:85]
	v_mfma_f32_16x16x32_bf16 v[70:73], v[164:167], v[204:207], v[70:73]
	v_mfma_f32_16x16x32_bf16 v[66:69], v[172:175], v[204:207], v[66:69]
	v_mfma_f32_16x16x32_bf16 v[118:121], v[168:171], v[184:187], v[118:121]
	v_mfma_f32_16x16x32_bf16 v[114:117], v[176:179], v[184:187], v[114:117]
	v_mfma_f32_16x16x32_bf16 v[102:105], v[168:171], v[192:195], v[102:105]
	v_mfma_f32_16x16x32_bf16 v[98:101], v[176:179], v[192:195], v[98:101]
	v_mfma_f32_16x16x32_bf16 v[86:89], v[168:171], v[200:203], v[86:89]
	v_mfma_f32_16x16x32_bf16 v[82:85], v[176:179], v[200:203], v[82:85]
	v_mfma_f32_16x16x32_bf16 v[70:73], v[168:171], v[208:211], v[70:73]
	v_mfma_f32_16x16x32_bf16 v[66:69], v[176:179], v[208:211], v[66:69]
	s_barrier
	s_add_i32 s49, s49, s28
	v_lshl_add_u64 v[212:213], s[20:21], 0, v[152:153]
	s_mov_b32 m0, s49
	ds_read_b128 v[180:183], v163 offset:16384
	ds_read_b128 v[184:187], v163 offset:17408
	ds_read_b128 v[188:191], v163 offset:18432
	ds_read_b128 v[192:195], v163 offset:19456
	ds_read_b128 v[196:199], v163 offset:20480
	ds_read_b128 v[200:203], v163 offset:21504
	ds_read_b128 v[204:207], v163 offset:22528
	ds_read_b128 v[208:211], v163 offset:23552
	global_load_lds_dwordx4 v[212:213], off
	s_add_i32 m0, s49, 0x2000
	s_add_u32 s50, s20, 0x40000
	v_lshl_add_u64 v[214:215], s[20:21], 0, v[148:149]
	s_addc_u32 s51, s21, 0
	s_add_i32 s49, s52, s28
	global_load_lds_dwordx4 v[214:215], off
	v_lshl_add_u64 v[216:217], s[50:51], 0, v[152:153]
	s_mov_b32 m0, s49
	v_lshl_add_u64 v[218:219], s[22:23], 0, v[150:151]
	global_load_lds_dwordx4 v[216:217], off
	v_lshl_add_u64 v[216:217], s[50:51], 0, v[148:149]
	s_add_i32 m0, s49, 0x2000
	s_nop 0
	global_load_lds_dwordx4 v[216:217], off
	v_lshl_add_u64 v[216:217], s[22:23], 0, v[154:155]
	s_mov_b32 m0, s29
	s_nop 0
	global_load_lds_dwordx4 v[216:217], off
	s_mov_b32 m0, s30
	s_nop 0
	global_load_lds_dwordx4 v[218:219], off
	s_waitcnt vmcnt(8)
	s_waitcnt lgkmcnt(0)
	s_barrier
	s_waitcnt lgkmcnt(0)
	v_mfma_f32_16x16x32_bf16 v[62:65], v[130:133], v[180:183], v[62:65]
	v_mfma_f32_16x16x32_bf16 v[58:61], v[138:141], v[180:183], v[58:61]
	v_mfma_f32_16x16x32_bf16 v[46:49], v[130:133], v[188:191], v[46:49]
	v_mfma_f32_16x16x32_bf16 v[42:45], v[138:141], v[188:191], v[42:45]
	v_mfma_f32_16x16x32_bf16 v[30:33], v[130:133], v[196:199], v[30:33]
	v_mfma_f32_16x16x32_bf16 v[26:29], v[138:141], v[196:199], v[26:29]
	v_mfma_f32_16x16x32_bf16 v[14:17], v[130:133], v[204:207], v[14:17]
	v_mfma_f32_16x16x32_bf16 v[10:13], v[138:141], v[204:207], v[10:13]
	v_mfma_f32_16x16x32_bf16 v[62:65], v[134:137], v[184:187], v[62:65]
	v_mfma_f32_16x16x32_bf16 v[58:61], v[142:145], v[184:187], v[58:61]
	v_mfma_f32_16x16x32_bf16 v[46:49], v[134:137], v[192:195], v[46:49]
	v_mfma_f32_16x16x32_bf16 v[42:45], v[142:145], v[192:195], v[42:45]
	v_mfma_f32_16x16x32_bf16 v[30:33], v[134:137], v[200:203], v[30:33]
	v_mfma_f32_16x16x32_bf16 v[26:29], v[142:145], v[200:203], v[26:29]
	v_mfma_f32_16x16x32_bf16 v[14:17], v[134:137], v[208:211], v[14:17]
	v_mfma_f32_16x16x32_bf16 v[10:13], v[142:145], v[208:211], v[10:13]
	v_mfma_f32_16x16x32_bf16 v[54:57], v[164:167], v[180:183], v[54:57]
	v_mfma_f32_16x16x32_bf16 v[50:53], v[172:175], v[180:183], v[50:53]
	v_mfma_f32_16x16x32_bf16 v[38:41], v[164:167], v[188:191], v[38:41]
	v_mfma_f32_16x16x32_bf16 v[34:37], v[172:175], v[188:191], v[34:37]
	v_mfma_f32_16x16x32_bf16 v[22:25], v[164:167], v[196:199], v[22:25]
	v_mfma_f32_16x16x32_bf16 v[18:21], v[172:175], v[196:199], v[18:21]
	v_mfma_f32_16x16x32_bf16 v[6:9], v[164:167], v[204:207], v[6:9]
	v_mfma_f32_16x16x32_bf16 v[2:5], v[172:175], v[204:207], v[2:5]
	v_mfma_f32_16x16x32_bf16 v[54:57], v[168:171], v[184:187], v[54:57]
	v_mfma_f32_16x16x32_bf16 v[50:53], v[176:179], v[184:187], v[50:53]
	v_mfma_f32_16x16x32_bf16 v[38:41], v[168:171], v[192:195], v[38:41]
	v_mfma_f32_16x16x32_bf16 v[34:37], v[176:179], v[192:195], v[34:37]
	v_mfma_f32_16x16x32_bf16 v[22:25], v[168:171], v[200:203], v[22:25]
	v_mfma_f32_16x16x32_bf16 v[18:21], v[176:179], v[200:203], v[18:21]
	v_mfma_f32_16x16x32_bf16 v[6:9], v[168:171], v[208:211], v[6:9]
	v_mfma_f32_16x16x32_bf16 v[2:5], v[176:179], v[208:211], v[2:5]
	s_barrier
	s_add_i32 s49, 0, 0x18000
	s_add_i32 s50, 0, 0x1c000
	v_add_u32_e32 v142, s49, v157
	v_add_u32_e32 v162, s50, v157
	ds_read_b128 v[130:133], v142
	ds_read_b128 v[134:137], v142 offset:1024
	ds_read_b128 v[138:141], v142 offset:2048
	ds_read_b128 v[142:145], v142 offset:3072
	ds_read_b128 v[164:167], v162
	ds_read_b128 v[168:171], v162 offset:1024
	ds_read_b128 v[172:175], v162 offset:2048
	ds_read_b128 v[176:179], v162 offset:3072
	s_add_u32 s22, s22, 0x40000
	s_addc_u32 s23, s23, 0
	s_mov_b32 m0, s31
	v_lshl_add_u64 v[220:221], s[22:23], 0, v[154:155]
	ds_read_b128 v[180:183], v163 offset:32768
	ds_read_b128 v[184:187], v163 offset:33792
	ds_read_b128 v[188:191], v163 offset:34816
	ds_read_b128 v[192:195], v163 offset:35840
	ds_read_b128 v[196:199], v163 offset:36864
	ds_read_b128 v[200:203], v163 offset:37888
	ds_read_b128 v[204:207], v163 offset:38912
	ds_read_b128 v[208:211], v163 offset:39936
	global_load_lds_dwordx4 v[220:221], off
	v_lshl_add_u64 v[220:221], s[22:23], 0, v[150:151]
	s_mov_b32 m0, s33
	s_nop 0
	global_load_lds_dwordx4 v[220:221], off
	s_waitcnt vmcnt(8)
	s_waitcnt lgkmcnt(0)
	s_barrier
	s_waitcnt lgkmcnt(0)
	v_mfma_f32_16x16x32_bf16 v[126:129], v[130:133], v[180:183], v[126:129]
	v_mfma_f32_16x16x32_bf16 v[122:125], v[138:141], v[180:183], v[122:125]
	v_mfma_f32_16x16x32_bf16 v[110:113], v[130:133], v[188:191], v[110:113]
	v_mfma_f32_16x16x32_bf16 v[106:109], v[138:141], v[188:191], v[106:109]
	v_mfma_f32_16x16x32_bf16 v[94:97], v[130:133], v[196:199], v[94:97]
	v_mfma_f32_16x16x32_bf16 v[90:93], v[138:141], v[196:199], v[90:93]
	v_mfma_f32_16x16x32_bf16 v[78:81], v[130:133], v[204:207], v[78:81]
	v_mfma_f32_16x16x32_bf16 v[74:77], v[138:141], v[204:207], v[74:77]
	v_mfma_f32_16x16x32_bf16 v[126:129], v[134:137], v[184:187], v[126:129]
	v_mfma_f32_16x16x32_bf16 v[122:125], v[142:145], v[184:187], v[122:125]
	v_mfma_f32_16x16x32_bf16 v[110:113], v[134:137], v[192:195], v[110:113]
	v_mfma_f32_16x16x32_bf16 v[106:109], v[142:145], v[192:195], v[106:109]
	v_mfma_f32_16x16x32_bf16 v[94:97], v[134:137], v[200:203], v[94:97]
	v_mfma_f32_16x16x32_bf16 v[90:93], v[142:145], v[200:203], v[90:93]
	v_mfma_f32_16x16x32_bf16 v[78:81], v[134:137], v[208:211], v[78:81]
	v_mfma_f32_16x16x32_bf16 v[74:77], v[142:145], v[208:211], v[74:77]
	v_mfma_f32_16x16x32_bf16 v[118:121], v[164:167], v[180:183], v[118:121]
	v_mfma_f32_16x16x32_bf16 v[114:117], v[172:175], v[180:183], v[114:117]
	v_mfma_f32_16x16x32_bf16 v[102:105], v[164:167], v[188:191], v[102:105]
	v_mfma_f32_16x16x32_bf16 v[98:101], v[172:175], v[188:191], v[98:101]
	v_mfma_f32_16x16x32_bf16 v[86:89], v[164:167], v[196:199], v[86:89]
	v_mfma_f32_16x16x32_bf16 v[82:85], v[172:175], v[196:199], v[82:85]
	v_mfma_f32_16x16x32_bf16 v[70:73], v[164:167], v[204:207], v[70:73]
	v_mfma_f32_16x16x32_bf16 v[66:69], v[172:175], v[204:207], v[66:69]
	v_mfma_f32_16x16x32_bf16 v[118:121], v[168:171], v[184:187], v[118:121]
	v_mfma_f32_16x16x32_bf16 v[114:117], v[176:179], v[184:187], v[114:117]
	v_mfma_f32_16x16x32_bf16 v[102:105], v[168:171], v[192:195], v[102:105]
	v_mfma_f32_16x16x32_bf16 v[98:101], v[176:179], v[192:195], v[98:101]
	v_mfma_f32_16x16x32_bf16 v[86:89], v[168:171], v[200:203], v[86:89]
	v_mfma_f32_16x16x32_bf16 v[82:85], v[176:179], v[200:203], v[82:85]
	v_mfma_f32_16x16x32_bf16 v[70:73], v[168:171], v[208:211], v[70:73]
	v_mfma_f32_16x16x32_bf16 v[66:69], v[176:179], v[208:211], v[66:69]
	s_barrier
	s_add_i32 s22, s49, s28
	v_lshl_add_u64 v[212:213], v[212:213], 0, s[2:3]
	s_mov_b32 m0, s22
	ds_read_b128 v[180:183], v163 offset:49152
	ds_read_b128 v[184:187], v163 offset:50176
	ds_read_b128 v[188:191], v163 offset:51200
	ds_read_b128 v[192:195], v163 offset:52224
	ds_read_b128 v[196:199], v163 offset:53248
	ds_read_b128 v[200:203], v163 offset:54272
	ds_read_b128 v[204:207], v163 offset:55296
	ds_read_b128 v[208:211], v163 offset:56320
	global_load_lds_dwordx4 v[212:213], off
	s_add_i32 m0, s22, 0x2000
	s_add_u32 s20, s20, 0x40080
	v_lshl_add_u64 v[212:213], v[214:215], 0, s[2:3]
	s_addc_u32 s21, s21, 0
	s_add_i32 s22, s50, s28
	global_load_lds_dwordx4 v[212:213], off
	v_lshl_add_u64 v[212:213], s[20:21], 0, v[152:153]
	s_mov_b32 m0, s22
	s_nop 0
	global_load_lds_dwordx4 v[212:213], off
	v_lshl_add_u64 v[212:213], s[20:21], 0, v[148:149]
	s_add_i32 m0, s22, 0x2000
	s_nop 0
	global_load_lds_dwordx4 v[212:213], off
	v_lshl_add_u64 v[212:213], v[216:217], 0, s[2:3]
	s_mov_b32 m0, s39
	s_nop 0
	global_load_lds_dwordx4 v[212:213], off
	v_lshl_add_u64 v[212:213], v[218:219], 0, s[2:3]
	s_mov_b32 m0, s40
	s_nop 0
	global_load_lds_dwordx4 v[212:213], off
	s_waitcnt vmcnt(8)
	s_waitcnt lgkmcnt(0)
	s_barrier
	s_waitcnt lgkmcnt(0)
	v_mfma_f32_16x16x32_bf16 v[62:65], v[130:133], v[180:183], v[62:65]
	v_mfma_f32_16x16x32_bf16 v[58:61], v[138:141], v[180:183], v[58:61]
	v_mfma_f32_16x16x32_bf16 v[46:49], v[130:133], v[188:191], v[46:49]
	v_mfma_f32_16x16x32_bf16 v[42:45], v[138:141], v[188:191], v[42:45]
	v_mfma_f32_16x16x32_bf16 v[30:33], v[130:133], v[196:199], v[30:33]
	v_mfma_f32_16x16x32_bf16 v[26:29], v[138:141], v[196:199], v[26:29]
	v_mfma_f32_16x16x32_bf16 v[14:17], v[130:133], v[204:207], v[14:17]
	v_mfma_f32_16x16x32_bf16 v[10:13], v[138:141], v[204:207], v[10:13]
	v_mfma_f32_16x16x32_bf16 v[62:65], v[134:137], v[184:187], v[62:65]
	v_mfma_f32_16x16x32_bf16 v[58:61], v[142:145], v[184:187], v[58:61]
	v_mfma_f32_16x16x32_bf16 v[46:49], v[134:137], v[192:195], v[46:49]
	v_mfma_f32_16x16x32_bf16 v[42:45], v[142:145], v[192:195], v[42:45]
	v_mfma_f32_16x16x32_bf16 v[30:33], v[134:137], v[200:203], v[30:33]
	v_mfma_f32_16x16x32_bf16 v[26:29], v[142:145], v[200:203], v[26:29]
	v_mfma_f32_16x16x32_bf16 v[14:17], v[134:137], v[208:211], v[14:17]
	v_mfma_f32_16x16x32_bf16 v[10:13], v[142:145], v[208:211], v[10:13]
	v_mfma_f32_16x16x32_bf16 v[54:57], v[164:167], v[180:183], v[54:57]
	v_mfma_f32_16x16x32_bf16 v[50:53], v[172:175], v[180:183], v[50:53]
	v_mfma_f32_16x16x32_bf16 v[38:41], v[164:167], v[188:191], v[38:41]
	v_mfma_f32_16x16x32_bf16 v[34:37], v[172:175], v[188:191], v[34:37]
	v_mfma_f32_16x16x32_bf16 v[22:25], v[164:167], v[196:199], v[22:25]
	v_mfma_f32_16x16x32_bf16 v[18:21], v[172:175], v[196:199], v[18:21]
	v_mfma_f32_16x16x32_bf16 v[6:9], v[164:167], v[204:207], v[6:9]
	v_mfma_f32_16x16x32_bf16 v[2:5], v[172:175], v[204:207], v[2:5]
	v_mfma_f32_16x16x32_bf16 v[54:57], v[168:171], v[184:187], v[54:57]
	v_mfma_f32_16x16x32_bf16 v[50:53], v[176:179], v[184:187], v[50:53]
	v_mfma_f32_16x16x32_bf16 v[38:41], v[168:171], v[192:195], v[38:41]
	v_mfma_f32_16x16x32_bf16 v[34:37], v[176:179], v[192:195], v[34:37]
	v_mfma_f32_16x16x32_bf16 v[22:25], v[168:171], v[200:203], v[22:25]
	v_mfma_f32_16x16x32_bf16 v[18:21], v[176:179], v[200:203], v[18:21]
	v_mfma_f32_16x16x32_bf16 v[6:9], v[168:171], v[208:211], v[6:9]
	v_mfma_f32_16x16x32_bf16 v[2:5], v[176:179], v[208:211], v[2:5]
	s_barrier
	s_add_i32 s48, s48, 2
	s_add_u32 s18, s18, 0x100
	s_addc_u32 s19, s19, 0
	s_add_u32 s46, s46, 0x100
	s_addc_u32 s47, s47, 0
	s_cmp_gt_u32 s48, 13
	s_cbranch_scc0 .LBB0_550
	s_setprio 0
	s_and_b64 vcc, exec, s[8:9]
	s_cbranch_vccz .LBB0_553
	s_barrier

.LBB0_801:
	s_ashr_i32 s17, s16, 31
	s_lshl_b64 s[18:19], s[16:17], 19
	s_add_u32 s18, s30, s18
	s_addc_u32 s19, s31, s19
	s_and_b64 s[20:21], s[6:7], exec
	s_cselect_b32 s17, s19, s23
	s_cselect_b32 s45, s18, s22
	s_ashr_i32 s15, s14, 31
	s_lshl_b64 s[20:21], s[14:15], 19
	s_add_u32 s20, s34, s20
	s_addc_u32 s21, s35, s21
	s_and_b64 s[26:27], s[6:7], exec
	s_cselect_b32 s15, s21, s25
	s_cselect_b32 s46, s20, s24
	s_add_u32 s22, s22, 0x40080
	s_addc_u32 s23, s23, 0
	s_add_u32 s47, s24, 0x100
	v_mov_b32_e32 v2, 0
	s_addc_u32 s48, s25, 0
	s_mov_b32 s49, -2
	v_mov_b32_e32 v3, v2
	v_mov_b32_e32 v4, v2
	v_mov_b32_e32 v5, v2
	v_mov_b32_e32 v6, v2
	v_mov_b32_e32 v7, v2
	v_mov_b32_e32 v8, v2
	v_mov_b32_e32 v9, v2
	v_mov_b32_e32 v18, v2
	v_mov_b32_e32 v19, v2
	v_mov_b32_e32 v20, v2
	v_mov_b32_e32 v21, v2
	v_mov_b32_e32 v22, v2
	v_mov_b32_e32 v23, v2
	v_mov_b32_e32 v24, v2
	v_mov_b32_e32 v25, v2
	v_mov_b32_e32 v34, v2
	v_mov_b32_e32 v35, v2
	v_mov_b32_e32 v36, v2
	v_mov_b32_e32 v37, v2
	v_mov_b32_e32 v42, v2
	v_mov_b32_e32 v43, v2
	v_mov_b32_e32 v44, v2
	v_mov_b32_e32 v45, v2
	v_mov_b32_e32 v66, v2
	v_mov_b32_e32 v67, v2
	v_mov_b32_e32 v68, v2
	v_mov_b32_e32 v69, v2
	v_mov_b32_e32 v70, v2
	v_mov_b32_e32 v71, v2
	v_mov_b32_e32 v72, v2
	v_mov_b32_e32 v73, v2
	v_mov_b32_e32 v10, v2
	v_mov_b32_e32 v11, v2
	v_mov_b32_e32 v12, v2
	v_mov_b32_e32 v13, v2
	v_mov_b32_e32 v14, v2
	v_mov_b32_e32 v15, v2
	v_mov_b32_e32 v16, v2
	v_mov_b32_e32 v17, v2
	v_mov_b32_e32 v26, v2
	v_mov_b32_e32 v27, v2
	v_mov_b32_e32 v28, v2
	v_mov_b32_e32 v29, v2
	v_mov_b32_e32 v30, v2
	v_mov_b32_e32 v31, v2
	v_mov_b32_e32 v32, v2
	v_mov_b32_e32 v33, v2
	v_mov_b32_e32 v58, v2
	v_mov_b32_e32 v59, v2
	v_mov_b32_e32 v60, v2
	v_mov_b32_e32 v61, v2
	v_mov_b32_e32 v62, v2
	v_mov_b32_e32 v63, v2
	v_mov_b32_e32 v64, v2
	v_mov_b32_e32 v65, v2
	v_mov_b32_e32 v74, v2
	v_mov_b32_e32 v75, v2
	v_mov_b32_e32 v76, v2
	v_mov_b32_e32 v77, v2
	v_mov_b32_e32 v78, v2
	v_mov_b32_e32 v79, v2
	v_mov_b32_e32 v80, v2
	v_mov_b32_e32 v81, v2
	v_mov_b32_e32 v82, v2
	v_mov_b32_e32 v83, v2
	v_mov_b32_e32 v84, v2
	v_mov_b32_e32 v85, v2
	v_mov_b32_e32 v86, v2
	v_mov_b32_e32 v87, v2
	v_mov_b32_e32 v88, v2
	v_mov_b32_e32 v89, v2
	v_mov_b32_e32 v98, v2
	v_mov_b32_e32 v99, v2
	v_mov_b32_e32 v100, v2
	v_mov_b32_e32 v101, v2
	v_mov_b32_e32 v102, v2
	v_mov_b32_e32 v103, v2
	v_mov_b32_e32 v104, v2
	v_mov_b32_e32 v105, v2
	v_mov_b32_e32 v114, v2
	v_mov_b32_e32 v115, v2
	v_mov_b32_e32 v116, v2
	v_mov_b32_e32 v117, v2
	v_mov_b32_e32 v118, v2
	v_mov_b32_e32 v119, v2
	v_mov_b32_e32 v120, v2
	v_mov_b32_e32 v121, v2
	v_mov_b32_e32 v130, v2
	v_mov_b32_e32 v131, v2
	v_mov_b32_e32 v132, v2
	v_mov_b32_e32 v133, v2
	v_mov_b32_e32 v134, v2
	v_mov_b32_e32 v135, v2
	v_mov_b32_e32 v136, v2
	v_mov_b32_e32 v137, v2
	v_mov_b32_e32 v90, v2
	v_mov_b32_e32 v91, v2
	v_mov_b32_e32 v92, v2
	v_mov_b32_e32 v93, v2
	v_mov_b32_e32 v94, v2
	v_mov_b32_e32 v95, v2
	v_mov_b32_e32 v96, v2
	v_mov_b32_e32 v97, v2
	v_mov_b32_e32 v106, v2
	v_mov_b32_e32 v107, v2
	v_mov_b32_e32 v108, v2
	v_mov_b32_e32 v109, v2
	v_mov_b32_e32 v110, v2
	v_mov_b32_e32 v111, v2
	v_mov_b32_e32 v112, v2
	v_mov_b32_e32 v113, v2
	v_mov_b32_e32 v122, v2
	v_mov_b32_e32 v123, v2
	v_mov_b32_e32 v124, v2
	v_mov_b32_e32 v125, v2
	v_mov_b32_e32 v126, v2
	v_mov_b32_e32 v127, v2
	v_mov_b32_e32 v128, v2
	v_mov_b32_e32 v129, v2
	v_mov_b32_e32 v142, v2
	v_mov_b32_e32 v143, v2
	v_mov_b32_e32 v144, v2
	v_mov_b32_e32 v145, v2
	v_mov_b32_e32 v138, v2
	v_mov_b32_e32 v139, v2
	v_mov_b32_e32 v140, v2
	v_mov_b32_e32 v141, v2
	v_readfirstlane_b32 s84, v224
	s_bitcmp1_b32 s84, 8
	s_cbranch_scc0 .Lsprio_3
	s_setprio 1
.Lsprio_3:
.LBB0_802:
	s_add_u32 s24, s22, 0xfffc0080
	s_addc_u32 s25, s23, -1
	s_add_i32 s50, 0, 0x10000
	s_cmp_eq_u32 s49, 12
	s_cselect_b32 s27, s17, s25
	s_cselect_b32 s26, s45, s24
	s_cselect_b32 s25, s15, s48
	s_cselect_b32 s24, s46, s47
	s_add_i32 s52, 0, 0x14000
	v_add_u32_e32 v54, s50, v168
	v_add_u32_e32 v171, s52, v168
	ds_read_b128 v[38:41], v54
	ds_read_b128 v[46:49], v54 offset:1024
	ds_read_b128 v[50:53], v54 offset:2048
	ds_read_b128 v[54:57], v54 offset:3072
	ds_read_b128 v[160:163], v171
	ds_read_b128 v[164:167], v171 offset:1024
	ds_read_b128 v[172:175], v171 offset:2048
	ds_read_b128 v[176:179], v171 offset:3072
	v_lshl_add_u64 v[212:213], s[22:23], 0, v[156:157]
	s_add_i32 m0, s37, 0xc000
	ds_read_b128 v[180:183], v170
	ds_read_b128 v[184:187], v170 offset:1024
	ds_read_b128 v[188:191], v170 offset:2048
	ds_read_b128 v[192:195], v170 offset:3072
	ds_read_b128 v[196:199], v170 offset:4096
	ds_read_b128 v[200:203], v170 offset:5120
	ds_read_b128 v[204:207], v170 offset:6144
	ds_read_b128 v[208:211], v170 offset:7168
	global_load_lds_dwordx4 v[212:213], off
	v_lshl_add_u64 v[212:213], s[22:23], 0, v[158:159]
	s_add_i32 m0, s37, 0xe000
	s_nop 0
	global_load_lds_dwordx4 v[212:213], off
	s_waitcnt vmcnt(8)
	s_waitcnt lgkmcnt(0)
	s_barrier
	s_waitcnt lgkmcnt(0)
	v_mfma_f32_16x16x32_bf16 v[138:141], v[38:41], v[180:183], v[138:141]
	v_mfma_f32_16x16x32_bf16 v[142:145], v[50:53], v[180:183], v[142:145]
	v_mfma_f32_16x16x32_bf16 v[126:129], v[38:41], v[188:191], v[126:129]
	v_mfma_f32_16x16x32_bf16 v[122:125], v[50:53], v[188:191], v[122:125]
	v_mfma_f32_16x16x32_bf16 v[110:113], v[38:41], v[196:199], v[110:113]
	v_mfma_f32_16x16x32_bf16 v[106:109], v[50:53], v[196:199], v[106:109]
	v_mfma_f32_16x16x32_bf16 v[94:97], v[38:41], v[204:207], v[94:97]
	v_mfma_f32_16x16x32_bf16 v[90:93], v[50:53], v[204:207], v[90:93]
	v_mfma_f32_16x16x32_bf16 v[138:141], v[46:49], v[184:187], v[138:141]
	v_mfma_f32_16x16x32_bf16 v[142:145], v[54:57], v[184:187], v[142:145]
	v_mfma_f32_16x16x32_bf16 v[126:129], v[46:49], v[192:195], v[126:129]
	v_mfma_f32_16x16x32_bf16 v[122:125], v[54:57], v[192:195], v[122:125]
	v_mfma_f32_16x16x32_bf16 v[110:113], v[46:49], v[200:203], v[110:113]
	v_mfma_f32_16x16x32_bf16 v[106:109], v[54:57], v[200:203], v[106:109]
	v_mfma_f32_16x16x32_bf16 v[94:97], v[46:49], v[208:211], v[94:97]
	v_mfma_f32_16x16x32_bf16 v[90:93], v[54:57], v[208:211], v[90:93]
	v_mfma_f32_16x16x32_bf16 v[134:137], v[160:163], v[180:183], v[134:137]
	v_mfma_f32_16x16x32_bf16 v[130:133], v[172:175], v[180:183], v[130:133]
	v_mfma_f32_16x16x32_bf16 v[118:121], v[160:163], v[188:191], v[118:121]
	v_mfma_f32_16x16x32_bf16 v[114:117], v[172:175], v[188:191], v[114:117]
	v_mfma_f32_16x16x32_bf16 v[102:105], v[160:163], v[196:199], v[102:105]
	v_mfma_f32_16x16x32_bf16 v[98:101], v[172:175], v[196:199], v[98:101]
	v_mfma_f32_16x16x32_bf16 v[86:89], v[160:163], v[204:207], v[86:89]
	v_mfma_f32_16x16x32_bf16 v[82:85], v[172:175], v[204:207], v[82:85]
	v_mfma_f32_16x16x32_bf16 v[134:137], v[164:167], v[184:187], v[134:137]
	v_mfma_f32_16x16x32_bf16 v[130:133], v[176:179], v[184:187], v[130:133]
	v_mfma_f32_16x16x32_bf16 v[118:121], v[164:167], v[192:195], v[118:121]
	v_mfma_f32_16x16x32_bf16 v[114:117], v[176:179], v[192:195], v[114:117]
	v_mfma_f32_16x16x32_bf16 v[102:105], v[164:167], v[200:203], v[102:105]
	v_mfma_f32_16x16x32_bf16 v[98:101], v[176:179], v[200:203], v[98:101]
	v_mfma_f32_16x16x32_bf16 v[86:89], v[164:167], v[208:211], v[86:89]
	v_mfma_f32_16x16x32_bf16 v[82:85], v[176:179], v[208:211], v[82:85]
	s_barrier
	s_add_i32 s50, s50, s36
	v_lshl_add_u64 v[212:213], s[24:25], 0, v[152:153]
	s_mov_b32 m0, s50
	ds_read_b128 v[180:183], v170 offset:16384
	ds_read_b128 v[184:187], v170 offset:17408
	ds_read_b128 v[188:191], v170 offset:18432
	ds_read_b128 v[192:195], v170 offset:19456
	ds_read_b128 v[196:199], v170 offset:20480
	ds_read_b128 v[200:203], v170 offset:21504
	ds_read_b128 v[204:207], v170 offset:22528
	ds_read_b128 v[208:211], v170 offset:23552
	global_load_lds_dwordx4 v[212:213], off
	s_add_i32 m0, s50, 0x2000
	s_add_u32 s50, s24, 0x40000
	v_lshl_add_u64 v[214:215], s[24:25], 0, v[148:149]
	s_addc_u32 s51, s25, 0
	s_add_i32 s52, s52, s36
	global_load_lds_dwordx4 v[214:215], off
	v_lshl_add_u64 v[216:217], s[50:51], 0, v[152:153]
	s_mov_b32 m0, s52
	v_lshl_add_u64 v[218:219], s[26:27], 0, v[150:151]
	global_load_lds_dwordx4 v[216:217], off
	v_lshl_add_u64 v[216:217], s[50:51], 0, v[148:149]
	s_add_i32 m0, s52, 0x2000
	s_nop 0
	global_load_lds_dwordx4 v[216:217], off
	v_lshl_add_u64 v[216:217], s[26:27], 0, v[154:155]
	s_mov_b32 m0, s37
	s_nop 0
	global_load_lds_dwordx4 v[216:217], off
	s_mov_b32 m0, s38
	s_nop 0
	global_load_lds_dwordx4 v[218:219], off
	s_waitcnt vmcnt(8)
	s_waitcnt lgkmcnt(0)
	s_barrier
	s_waitcnt lgkmcnt(0)
	v_mfma_f32_16x16x32_bf16 v[78:81], v[38:41], v[180:183], v[78:81]
	v_mfma_f32_16x16x32_bf16 v[74:77], v[50:53], v[180:183], v[74:77]
	v_mfma_f32_16x16x32_bf16 v[62:65], v[38:41], v[188:191], v[62:65]
	v_mfma_f32_16x16x32_bf16 v[58:61], v[50:53], v[188:191], v[58:61]
	v_mfma_f32_16x16x32_bf16 v[30:33], v[38:41], v[196:199], v[30:33]
	v_mfma_f32_16x16x32_bf16 v[26:29], v[50:53], v[196:199], v[26:29]
	v_mfma_f32_16x16x32_bf16 v[14:17], v[38:41], v[204:207], v[14:17]
	v_mfma_f32_16x16x32_bf16 v[10:13], v[50:53], v[204:207], v[10:13]
	v_mfma_f32_16x16x32_bf16 v[78:81], v[46:49], v[184:187], v[78:81]
	v_mfma_f32_16x16x32_bf16 v[74:77], v[54:57], v[184:187], v[74:77]
	v_mfma_f32_16x16x32_bf16 v[62:65], v[46:49], v[192:195], v[62:65]
	v_mfma_f32_16x16x32_bf16 v[58:61], v[54:57], v[192:195], v[58:61]
	v_mfma_f32_16x16x32_bf16 v[30:33], v[46:49], v[200:203], v[30:33]
	v_mfma_f32_16x16x32_bf16 v[26:29], v[54:57], v[200:203], v[26:29]
	v_mfma_f32_16x16x32_bf16 v[14:17], v[46:49], v[208:211], v[14:17]
	v_mfma_f32_16x16x32_bf16 v[10:13], v[54:57], v[208:211], v[10:13]
	v_mfma_f32_16x16x32_bf16 v[42:45], v[160:163], v[188:191], v[42:45]
	v_mfma_f32_16x16x32_bf16 v[34:37], v[172:175], v[188:191], v[34:37]
	v_mfma_f32_16x16x32_bf16 v[22:25], v[160:163], v[196:199], v[22:25]
	v_mfma_f32_16x16x32_bf16 v[18:21], v[172:175], v[196:199], v[18:21]
	v_mfma_f32_16x16x32_bf16 v[6:9], v[160:163], v[204:207], v[6:9]
	v_mfma_f32_16x16x32_bf16 v[2:5], v[172:175], v[204:207], v[2:5]
	v_mfma_f32_16x16x32_bf16 v[38:41], v[160:163], v[180:183], v[70:73]
	v_mfma_f32_16x16x32_bf16 v[46:49], v[172:175], v[180:183], v[66:69]
	v_mfma_f32_16x16x32_bf16 v[42:45], v[164:167], v[192:195], v[42:45]
	v_mfma_f32_16x16x32_bf16 v[34:37], v[176:179], v[192:195], v[34:37]
	v_mfma_f32_16x16x32_bf16 v[22:25], v[164:167], v[200:203], v[22:25]
	v_mfma_f32_16x16x32_bf16 v[18:21], v[176:179], v[200:203], v[18:21]
	v_mfma_f32_16x16x32_bf16 v[6:9], v[164:167], v[208:211], v[6:9]
	v_mfma_f32_16x16x32_bf16 v[2:5], v[176:179], v[208:211], v[2:5]
	v_mfma_f32_16x16x32_bf16 v[38:41], v[164:167], v[184:187], v[38:41]
	v_mfma_f32_16x16x32_bf16 v[46:49], v[176:179], v[184:187], v[46:49]
	s_barrier
	s_add_i32 s50, 0, 0x18000
	s_add_i32 s51, 0, 0x1c000
	v_add_u32_e32 v70, s50, v168
	v_add_u32_e32 v171, s51, v168
	ds_read_b128 v[50:53], v70
	ds_read_b128 v[54:57], v70 offset:1024
	ds_read_b128 v[66:69], v70 offset:2048
	ds_read_b128 v[70:73], v70 offset:3072
	ds_read_b128 v[160:163], v171
	ds_read_b128 v[164:167], v171 offset:1024
	ds_read_b128 v[172:175], v171 offset:2048
	ds_read_b128 v[176:179], v171 offset:3072
	s_add_u32 s26, s26, 0x40000
	s_addc_u32 s27, s27, 0
	s_mov_b32 m0, s39
	v_lshl_add_u64 v[220:221], s[26:27], 0, v[154:155]
	ds_read_b128 v[180:183], v170 offset:32768
	ds_read_b128 v[184:187], v170 offset:33792
	ds_read_b128 v[188:191], v170 offset:34816
	ds_read_b128 v[192:195], v170 offset:35840
	ds_read_b128 v[196:199], v170 offset:36864
	ds_read_b128 v[200:203], v170 offset:37888
	ds_read_b128 v[204:207], v170 offset:38912
	ds_read_b128 v[208:211], v170 offset:39936
	global_load_lds_dwordx4 v[220:221], off
	v_lshl_add_u64 v[220:221], s[26:27], 0, v[150:151]
	s_mov_b32 m0, s40
	s_nop 0
	global_load_lds_dwordx4 v[220:221], off
	s_waitcnt vmcnt(8)
	s_waitcnt lgkmcnt(0)
	s_barrier
	s_waitcnt lgkmcnt(0)
	v_mfma_f32_16x16x32_bf16 v[138:141], v[50:53], v[180:183], v[138:141]
	v_mfma_f32_16x16x32_bf16 v[142:145], v[66:69], v[180:183], v[142:145]
	v_mfma_f32_16x16x32_bf16 v[126:129], v[50:53], v[188:191], v[126:129]
	v_mfma_f32_16x16x32_bf16 v[122:125], v[66:69], v[188:191], v[122:125]
	v_mfma_f32_16x16x32_bf16 v[110:113], v[50:53], v[196:199], v[110:113]
	v_mfma_f32_16x16x32_bf16 v[106:109], v[66:69], v[196:199], v[106:109]
	v_mfma_f32_16x16x32_bf16 v[94:97], v[50:53], v[204:207], v[94:97]
	v_mfma_f32_16x16x32_bf16 v[90:93], v[66:69], v[204:207], v[90:93]
	v_mfma_f32_16x16x32_bf16 v[138:141], v[54:57], v[184:187], v[138:141]
	v_mfma_f32_16x16x32_bf16 v[142:145], v[70:73], v[184:187], v[142:145]
	v_mfma_f32_16x16x32_bf16 v[126:129], v[54:57], v[192:195], v[126:129]
	v_mfma_f32_16x16x32_bf16 v[122:125], v[70:73], v[192:195], v[122:125]
	v_mfma_f32_16x16x32_bf16 v[110:113], v[54:57], v[200:203], v[110:113]
	v_mfma_f32_16x16x32_bf16 v[106:109], v[70:73], v[200:203], v[106:109]
	v_mfma_f32_16x16x32_bf16 v[94:97], v[54:57], v[208:211], v[94:97]
	v_mfma_f32_16x16x32_bf16 v[90:93], v[70:73], v[208:211], v[90:93]
	v_mfma_f32_16x16x32_bf16 v[134:137], v[160:163], v[180:183], v[134:137]
	v_mfma_f32_16x16x32_bf16 v[130:133], v[172:175], v[180:183], v[130:133]
	v_mfma_f32_16x16x32_bf16 v[118:121], v[160:163], v[188:191], v[118:121]
	v_mfma_f32_16x16x32_bf16 v[114:117], v[172:175], v[188:191], v[114:117]
	v_mfma_f32_16x16x32_bf16 v[102:105], v[160:163], v[196:199], v[102:105]
	v_mfma_f32_16x16x32_bf16 v[98:101], v[172:175], v[196:199], v[98:101]
	v_mfma_f32_16x16x32_bf16 v[86:89], v[160:163], v[204:207], v[86:89]
	v_mfma_f32_16x16x32_bf16 v[82:85], v[172:175], v[204:207], v[82:85]
	v_mfma_f32_16x16x32_bf16 v[134:137], v[164:167], v[184:187], v[134:137]
	v_mfma_f32_16x16x32_bf16 v[130:133], v[176:179], v[184:187], v[130:133]
	v_mfma_f32_16x16x32_bf16 v[118:121], v[164:167], v[192:195], v[118:121]
	v_mfma_f32_16x16x32_bf16 v[114:117], v[176:179], v[192:195], v[114:117]
	v_mfma_f32_16x16x32_bf16 v[102:105], v[164:167], v[200:203], v[102:105]
	v_mfma_f32_16x16x32_bf16 v[98:101], v[176:179], v[200:203], v[98:101]
	v_mfma_f32_16x16x32_bf16 v[86:89], v[164:167], v[208:211], v[86:89]
	v_mfma_f32_16x16x32_bf16 v[82:85], v[176:179], v[208:211], v[82:85]
	s_barrier
	s_add_i32 s26, s50, s36
	v_lshl_add_u64 v[212:213], v[212:213], 0, s[2:3]
	s_mov_b32 m0, s26
	ds_read_b128 v[180:183], v170 offset:49152
	ds_read_b128 v[184:187], v170 offset:50176
	ds_read_b128 v[188:191], v170 offset:51200
	ds_read_b128 v[192:195], v170 offset:52224
	ds_read_b128 v[196:199], v170 offset:53248
	ds_read_b128 v[200:203], v170 offset:54272
	ds_read_b128 v[204:207], v170 offset:55296
	ds_read_b128 v[208:211], v170 offset:56320
	global_load_lds_dwordx4 v[212:213], off
	s_add_i32 m0, s26, 0x2000
	s_add_u32 s24, s24, 0x40080
	v_lshl_add_u64 v[212:213], v[214:215], 0, s[2:3]
	s_addc_u32 s25, s25, 0
	s_add_i32 s26, s51, s36
	global_load_lds_dwordx4 v[212:213], off
	v_lshl_add_u64 v[212:213], s[24:25], 0, v[152:153]
	s_mov_b32 m0, s26
	s_nop 0
	global_load_lds_dwordx4 v[212:213], off
	v_lshl_add_u64 v[212:213], s[24:25], 0, v[148:149]
	s_add_i32 m0, s26, 0x2000
	s_nop 0
	global_load_lds_dwordx4 v[212:213], off
	v_lshl_add_u64 v[212:213], v[216:217], 0, s[2:3]
	s_mov_b32 m0, s41
	s_nop 0
	global_load_lds_dwordx4 v[212:213], off
	v_lshl_add_u64 v[212:213], v[218:219], 0, s[2:3]
	s_mov_b32 m0, s42
	s_nop 0
	global_load_lds_dwordx4 v[212:213], off
	s_waitcnt vmcnt(8)
	s_waitcnt lgkmcnt(0)
	s_barrier
	s_waitcnt lgkmcnt(0)
	v_mfma_f32_16x16x32_bf16 v[78:81], v[50:53], v[180:183], v[78:81]
	v_mfma_f32_16x16x32_bf16 v[74:77], v[66:69], v[180:183], v[74:77]
	v_mfma_f32_16x16x32_bf16 v[62:65], v[50:53], v[188:191], v[62:65]
	v_mfma_f32_16x16x32_bf16 v[58:61], v[66:69], v[188:191], v[58:61]
	v_mfma_f32_16x16x32_bf16 v[30:33], v[50:53], v[196:199], v[30:33]
	v_mfma_f32_16x16x32_bf16 v[26:29], v[66:69], v[196:199], v[26:29]
	v_mfma_f32_16x16x32_bf16 v[14:17], v[50:53], v[204:207], v[14:17]
	v_mfma_f32_16x16x32_bf16 v[10:13], v[66:69], v[204:207], v[10:13]
	v_mfma_f32_16x16x32_bf16 v[78:81], v[54:57], v[184:187], v[78:81]
	v_mfma_f32_16x16x32_bf16 v[74:77], v[70:73], v[184:187], v[74:77]
	v_mfma_f32_16x16x32_bf16 v[62:65], v[54:57], v[192:195], v[62:65]
	v_mfma_f32_16x16x32_bf16 v[58:61], v[70:73], v[192:195], v[58:61]
	v_mfma_f32_16x16x32_bf16 v[30:33], v[54:57], v[200:203], v[30:33]
	v_mfma_f32_16x16x32_bf16 v[26:29], v[70:73], v[200:203], v[26:29]
	v_mfma_f32_16x16x32_bf16 v[14:17], v[54:57], v[208:211], v[14:17]
	v_mfma_f32_16x16x32_bf16 v[10:13], v[70:73], v[208:211], v[10:13]
	v_mfma_f32_16x16x32_bf16 v[38:41], v[160:163], v[180:183], v[38:41]
	v_mfma_f32_16x16x32_bf16 v[70:73], v[164:167], v[184:187], v[38:41]
	v_mfma_f32_16x16x32_bf16 v[38:41], v[172:175], v[180:183], v[46:49]
	v_mfma_f32_16x16x32_bf16 v[66:69], v[176:179], v[184:187], v[38:41]
	v_mfma_f32_16x16x32_bf16 v[38:41], v[160:163], v[188:191], v[42:45]
	v_mfma_f32_16x16x32_bf16 v[34:37], v[172:175], v[188:191], v[34:37]
	v_mfma_f32_16x16x32_bf16 v[22:25], v[160:163], v[196:199], v[22:25]
	v_mfma_f32_16x16x32_bf16 v[18:21], v[172:175], v[196:199], v[18:21]
	v_mfma_f32_16x16x32_bf16 v[6:9], v[160:163], v[204:207], v[6:9]
	v_mfma_f32_16x16x32_bf16 v[2:5], v[172:175], v[204:207], v[2:5]
	v_mfma_f32_16x16x32_bf16 v[42:45], v[164:167], v[192:195], v[38:41]
	v_mfma_f32_16x16x32_bf16 v[34:37], v[176:179], v[192:195], v[34:37]
	v_mfma_f32_16x16x32_bf16 v[22:25], v[164:167], v[200:203], v[22:25]
	v_mfma_f32_16x16x32_bf16 v[18:21], v[176:179], v[200:203], v[18:21]
	v_mfma_f32_16x16x32_bf16 v[6:9], v[164:167], v[208:211], v[6:9]
	v_mfma_f32_16x16x32_bf16 v[2:5], v[176:179], v[208:211], v[2:5]
	s_barrier
	s_add_i32 s49, s49, 2
	s_add_u32 s22, s22, 0x100
	s_addc_u32 s23, s23, 0
	s_add_u32 s47, s47, 0x100
	s_addc_u32 s48, s48, 0
	s_cmp_gt_u32 s49, 13
	s_cbranch_scc0 .LBB0_802
	s_setprio 0
	s_and_b64 vcc, exec, s[12:13]
	s_cbranch_vccz .LBB0_805
	s_barrier

.LBB0_877:
	s_ashr_i32 s23, s22, 31
	s_lshl_b64 s[24:25], s[22:23], 19
	s_add_u32 s24, s38, s24
	s_addc_u32 s25, s39, s25
	s_and_b64 s[26:27], s[8:9], exec
	s_cselect_b32 s5, s25, s1
	s_cselect_b32 s23, s24, s0
	s_ashr_i32 s21, s20, 31
	s_lshl_b64 s[26:27], s[20:21], 19
	s_add_u32 s26, s40, s26
	s_addc_u32 s27, s41, s27
	s_and_b64 s[34:35], s[8:9], exec
	s_cselect_b32 s21, s27, s31
	s_cselect_b32 s29, s26, s30
	s_add_u32 s0, s0, 0x40080
	s_addc_u32 s1, s1, 0
	s_add_u32 s33, s30, 0x100
	v_mov_b32_e32 v2, 0
	s_addc_u32 s36, s31, 0
	s_mov_b32 s37, -2
	v_mov_b32_e32 v3, v2
	v_mov_b32_e32 v4, v2
	v_mov_b32_e32 v5, v2
	v_mov_b32_e32 v6, v2
	v_mov_b32_e32 v7, v2
	v_mov_b32_e32 v8, v2
	v_mov_b32_e32 v9, v2
	v_mov_b32_e32 v18, v2
	v_mov_b32_e32 v19, v2
	v_mov_b32_e32 v20, v2
	v_mov_b32_e32 v21, v2
	v_mov_b32_e32 v22, v2
	v_mov_b32_e32 v23, v2
	v_mov_b32_e32 v24, v2
	v_mov_b32_e32 v25, v2
	v_mov_b32_e32 v34, v2
	v_mov_b32_e32 v35, v2
	v_mov_b32_e32 v36, v2
	v_mov_b32_e32 v37, v2
	v_mov_b32_e32 v38, v2
	v_mov_b32_e32 v39, v2
	v_mov_b32_e32 v40, v2
	v_mov_b32_e32 v41, v2
	v_mov_b32_e32 v66, v2
	v_mov_b32_e32 v67, v2
	v_mov_b32_e32 v68, v2
	v_mov_b32_e32 v69, v2
	v_mov_b32_e32 v70, v2
	v_mov_b32_e32 v71, v2
	v_mov_b32_e32 v72, v2
	v_mov_b32_e32 v73, v2
	v_mov_b32_e32 v10, v2
	v_mov_b32_e32 v11, v2
	v_mov_b32_e32 v12, v2
	v_mov_b32_e32 v13, v2
	v_mov_b32_e32 v14, v2
	v_mov_b32_e32 v15, v2
	v_mov_b32_e32 v16, v2
	v_mov_b32_e32 v17, v2
	v_mov_b32_e32 v26, v2
	v_mov_b32_e32 v27, v2
	v_mov_b32_e32 v28, v2
	v_mov_b32_e32 v29, v2
	v_mov_b32_e32 v30, v2
	v_mov_b32_e32 v31, v2
	v_mov_b32_e32 v32, v2
	v_mov_b32_e32 v33, v2
	v_mov_b32_e32 v42, v2
	v_mov_b32_e32 v43, v2
	v_mov_b32_e32 v44, v2
	v_mov_b32_e32 v45, v2
	v_mov_b32_e32 v46, v2
	v_mov_b32_e32 v47, v2
	v_mov_b32_e32 v48, v2
	v_mov_b32_e32 v49, v2
	v_mov_b32_e32 v74, v2
	v_mov_b32_e32 v75, v2
	v_mov_b32_e32 v76, v2
	v_mov_b32_e32 v77, v2
	v_mov_b32_e32 v78, v2
	v_mov_b32_e32 v79, v2
	v_mov_b32_e32 v80, v2
	v_mov_b32_e32 v81, v2
	v_mov_b32_e32 v82, v2
	v_mov_b32_e32 v83, v2
	v_mov_b32_e32 v84, v2
	v_mov_b32_e32 v85, v2
	v_mov_b32_e32 v86, v2
	v_mov_b32_e32 v87, v2
	v_mov_b32_e32 v88, v2
	v_mov_b32_e32 v89, v2
	v_mov_b32_e32 v98, v2
	v_mov_b32_e32 v99, v2
	v_mov_b32_e32 v100, v2
	v_mov_b32_e32 v101, v2
	v_mov_b32_e32 v102, v2
	v_mov_b32_e32 v103, v2
	v_mov_b32_e32 v104, v2
	v_mov_b32_e32 v105, v2
	v_mov_b32_e32 v114, v2
	v_mov_b32_e32 v115, v2
	v_mov_b32_e32 v116, v2
	v_mov_b32_e32 v117, v2
	v_mov_b32_e32 v118, v2
	v_mov_b32_e32 v119, v2
	v_mov_b32_e32 v120, v2
	v_mov_b32_e32 v121, v2
	v_mov_b32_e32 v130, v2
	v_mov_b32_e32 v131, v2
	v_mov_b32_e32 v132, v2
	v_mov_b32_e32 v133, v2
	v_mov_b32_e32 v134, v2
	v_mov_b32_e32 v135, v2
	v_mov_b32_e32 v136, v2
	v_mov_b32_e32 v137, v2
	v_mov_b32_e32 v90, v2
	v_mov_b32_e32 v91, v2
	v_mov_b32_e32 v92, v2
	v_mov_b32_e32 v93, v2
	v_mov_b32_e32 v94, v2
	v_mov_b32_e32 v95, v2
	v_mov_b32_e32 v96, v2
	v_mov_b32_e32 v97, v2
	v_mov_b32_e32 v106, v2
	v_mov_b32_e32 v107, v2
	v_mov_b32_e32 v108, v2
	v_mov_b32_e32 v109, v2
	v_mov_b32_e32 v110, v2
	v_mov_b32_e32 v111, v2
	v_mov_b32_e32 v112, v2
	v_mov_b32_e32 v113, v2
	v_mov_b32_e32 v122, v2
	v_mov_b32_e32 v123, v2
	v_mov_b32_e32 v124, v2
	v_mov_b32_e32 v125, v2
	v_mov_b32_e32 v126, v2
	v_mov_b32_e32 v127, v2
	v_mov_b32_e32 v128, v2
	v_mov_b32_e32 v129, v2
	v_mov_b32_e32 v138, v2
	v_mov_b32_e32 v139, v2
	v_mov_b32_e32 v140, v2
	v_mov_b32_e32 v141, v2
	v_mov_b32_e32 v142, v2
	v_mov_b32_e32 v143, v2
	v_mov_b32_e32 v144, v2
	v_mov_b32_e32 v145, v2
	v_readfirstlane_b32 s84, v224
	s_bitcmp1_b32 s84, 8
	s_cbranch_scc0 .Lsprio_4
	s_setprio 1
.Lsprio_4:
.LBB0_878:
	s_add_u32 s30, s0, 0xfffc0080
	s_addc_u32 s31, s1, -1
	s_add_i32 s54, 0, 0x10000
	s_cmp_eq_u32 s37, 12
	s_cselect_b32 s35, s5, s31
	s_cselect_b32 s34, s23, s30
	s_cselect_b32 s31, s21, s36
	s_cselect_b32 s30, s29, s33
	s_add_i32 s56, 0, 0x14000
	v_add_u32_e32 v62, s54, v153
	v_add_u32_e32 v176, s56, v153
	ds_read_b128 v[50:53], v62
	ds_read_b128 v[54:57], v62 offset:1024
	ds_read_b128 v[58:61], v62 offset:2048
	ds_read_b128 v[62:65], v62 offset:3072
	ds_read_b128 v[164:167], v176
	ds_read_b128 v[168:171], v176 offset:1024
	ds_read_b128 v[172:175], v176 offset:2048
	ds_read_b128 v[176:179], v176 offset:3072
	v_lshl_add_u64 v[218:219], s[0:1], 0, v[160:161]
	s_add_i32 m0, s43, 0xc000
	ds_read_b128 v[180:183], v187
	ds_read_b128 v[190:193], v187 offset:1024
	ds_read_b128 v[194:197], v187 offset:2048
	ds_read_b128 v[198:201], v187 offset:3072
	ds_read_b128 v[202:205], v187 offset:4096
	ds_read_b128 v[206:209], v187 offset:5120
	ds_read_b128 v[210:213], v187 offset:6144
	ds_read_b128 v[214:217], v187 offset:7168
	global_load_lds_dwordx4 v[218:219], off
	v_lshl_add_u64 v[218:219], s[0:1], 0, v[162:163]
	s_add_i32 m0, s43, 0xe000
	s_nop 0
	global_load_lds_dwordx4 v[218:219], off
	s_waitcnt vmcnt(8)
	s_waitcnt lgkmcnt(0)
	s_barrier
	s_waitcnt lgkmcnt(0)
	v_mfma_f32_16x16x32_bf16 v[142:145], v[50:53], v[180:183], v[142:145]
	v_mfma_f32_16x16x32_bf16 v[138:141], v[58:61], v[180:183], v[138:141]
	v_mfma_f32_16x16x32_bf16 v[126:129], v[50:53], v[194:197], v[126:129]
	v_mfma_f32_16x16x32_bf16 v[122:125], v[58:61], v[194:197], v[122:125]
	v_mfma_f32_16x16x32_bf16 v[110:113], v[50:53], v[202:205], v[110:113]
	v_mfma_f32_16x16x32_bf16 v[106:109], v[58:61], v[202:205], v[106:109]
	v_mfma_f32_16x16x32_bf16 v[94:97], v[50:53], v[210:213], v[94:97]
	v_mfma_f32_16x16x32_bf16 v[90:93], v[58:61], v[210:213], v[90:93]
	v_mfma_f32_16x16x32_bf16 v[142:145], v[54:57], v[190:193], v[142:145]
	v_mfma_f32_16x16x32_bf16 v[138:141], v[62:65], v[190:193], v[138:141]
	v_mfma_f32_16x16x32_bf16 v[126:129], v[54:57], v[198:201], v[126:129]
	v_mfma_f32_16x16x32_bf16 v[122:125], v[62:65], v[198:201], v[122:125]
	v_mfma_f32_16x16x32_bf16 v[110:113], v[54:57], v[206:209], v[110:113]
	v_mfma_f32_16x16x32_bf16 v[106:109], v[62:65], v[206:209], v[106:109]
	v_mfma_f32_16x16x32_bf16 v[94:97], v[54:57], v[214:217], v[94:97]
	v_mfma_f32_16x16x32_bf16 v[90:93], v[62:65], v[214:217], v[90:93]
	v_mfma_f32_16x16x32_bf16 v[134:137], v[164:167], v[180:183], v[134:137]
	v_mfma_f32_16x16x32_bf16 v[130:133], v[172:175], v[180:183], v[130:133]
	v_mfma_f32_16x16x32_bf16 v[118:121], v[164:167], v[194:197], v[118:121]
	v_mfma_f32_16x16x32_bf16 v[114:117], v[172:175], v[194:197], v[114:117]
	v_mfma_f32_16x16x32_bf16 v[102:105], v[164:167], v[202:205], v[102:105]
	v_mfma_f32_16x16x32_bf16 v[98:101], v[172:175], v[202:205], v[98:101]
	v_mfma_f32_16x16x32_bf16 v[86:89], v[164:167], v[210:213], v[86:89]
	v_mfma_f32_16x16x32_bf16 v[82:85], v[172:175], v[210:213], v[82:85]
	v_mfma_f32_16x16x32_bf16 v[134:137], v[168:171], v[190:193], v[134:137]
	v_mfma_f32_16x16x32_bf16 v[130:133], v[176:179], v[190:193], v[130:133]
	v_mfma_f32_16x16x32_bf16 v[118:121], v[168:171], v[198:201], v[118:121]
	v_mfma_f32_16x16x32_bf16 v[114:117], v[176:179], v[198:201], v[114:117]
	v_mfma_f32_16x16x32_bf16 v[102:105], v[168:171], v[206:209], v[102:105]
	v_mfma_f32_16x16x32_bf16 v[98:101], v[176:179], v[206:209], v[98:101]
	v_mfma_f32_16x16x32_bf16 v[86:89], v[168:171], v[214:217], v[86:89]
	v_mfma_f32_16x16x32_bf16 v[82:85], v[176:179], v[214:217], v[82:85]
	s_barrier
	s_add_i32 s54, s54, s42
	v_lshl_add_u64 v[218:219], s[30:31], 0, v[148:149]
	s_mov_b32 m0, s54
	ds_read_b128 v[180:183], v187 offset:16384
	ds_read_b128 v[190:193], v187 offset:17408
	ds_read_b128 v[194:197], v187 offset:18432
	ds_read_b128 v[198:201], v187 offset:19456
	ds_read_b128 v[202:205], v187 offset:20480
	ds_read_b128 v[206:209], v187 offset:21504
	ds_read_b128 v[210:213], v187 offset:22528
	ds_read_b128 v[214:217], v187 offset:23552
	global_load_lds_dwordx4 v[218:219], off
	s_add_i32 m0, s54, 0x2000
	s_add_u32 s54, s30, 0x40000
	v_lshl_add_u64 v[220:221], s[30:31], 0, v[150:151]
	s_addc_u32 s55, s31, 0
	s_add_i32 s56, s56, s42
	global_load_lds_dwordx4 v[220:221], off
	v_lshl_add_u64 v[222:223], s[54:55], 0, v[148:149]
	s_mov_b32 m0, s56
	v_lshl_add_u64 v[226:227], s[34:35], 0, v[150:151]
	global_load_lds_dwordx4 v[222:223], off
	v_lshl_add_u64 v[222:223], s[54:55], 0, v[150:151]
	s_add_i32 m0, s56, 0x2000
	s_nop 0
	global_load_lds_dwordx4 v[222:223], off
	v_lshl_add_u64 v[222:223], s[34:35], 0, v[148:149]
	s_mov_b32 m0, s43
	s_nop 0
	global_load_lds_dwordx4 v[222:223], off
	s_mov_b32 m0, s44
	s_nop 0
	global_load_lds_dwordx4 v[226:227], off
	s_waitcnt vmcnt(8)
	s_waitcnt lgkmcnt(0)
	s_barrier
	s_waitcnt lgkmcnt(0)
	v_mfma_f32_16x16x32_bf16 v[78:81], v[50:53], v[180:183], v[78:81]
	v_mfma_f32_16x16x32_bf16 v[74:77], v[58:61], v[180:183], v[74:77]
	v_mfma_f32_16x16x32_bf16 v[46:49], v[50:53], v[194:197], v[46:49]
	v_mfma_f32_16x16x32_bf16 v[42:45], v[58:61], v[194:197], v[42:45]
	v_mfma_f32_16x16x32_bf16 v[30:33], v[50:53], v[202:205], v[30:33]
	v_mfma_f32_16x16x32_bf16 v[26:29], v[58:61], v[202:205], v[26:29]
	v_mfma_f32_16x16x32_bf16 v[14:17], v[50:53], v[210:213], v[14:17]
	v_mfma_f32_16x16x32_bf16 v[10:13], v[58:61], v[210:213], v[10:13]
	v_mfma_f32_16x16x32_bf16 v[78:81], v[54:57], v[190:193], v[78:81]
	v_mfma_f32_16x16x32_bf16 v[74:77], v[62:65], v[190:193], v[74:77]
	v_mfma_f32_16x16x32_bf16 v[46:49], v[54:57], v[198:201], v[46:49]
	v_mfma_f32_16x16x32_bf16 v[42:45], v[62:65], v[198:201], v[42:45]
	v_mfma_f32_16x16x32_bf16 v[30:33], v[54:57], v[206:209], v[30:33]
	v_mfma_f32_16x16x32_bf16 v[26:29], v[62:65], v[206:209], v[26:29]
	v_mfma_f32_16x16x32_bf16 v[14:17], v[54:57], v[214:217], v[14:17]
	v_mfma_f32_16x16x32_bf16 v[10:13], v[62:65], v[214:217], v[10:13]
	v_mfma_f32_16x16x32_bf16 v[38:41], v[164:167], v[194:197], v[38:41]
	v_mfma_f32_16x16x32_bf16 v[34:37], v[172:175], v[194:197], v[34:37]
	v_mfma_f32_16x16x32_bf16 v[22:25], v[164:167], v[202:205], v[22:25]
	v_mfma_f32_16x16x32_bf16 v[18:21], v[172:175], v[202:205], v[18:21]
	v_mfma_f32_16x16x32_bf16 v[6:9], v[164:167], v[210:213], v[6:9]
	v_mfma_f32_16x16x32_bf16 v[2:5], v[172:175], v[210:213], v[2:5]
	v_mfma_f32_16x16x32_bf16 v[50:53], v[164:167], v[180:183], v[70:73]
	v_mfma_f32_16x16x32_bf16 v[54:57], v[172:175], v[180:183], v[66:69]
	v_mfma_f32_16x16x32_bf16 v[38:41], v[168:171], v[198:201], v[38:41]
	v_mfma_f32_16x16x32_bf16 v[34:37], v[176:179], v[198:201], v[34:37]
	v_mfma_f32_16x16x32_bf16 v[22:25], v[168:171], v[206:209], v[22:25]
	v_mfma_f32_16x16x32_bf16 v[18:21], v[176:179], v[206:209], v[18:21]
	v_mfma_f32_16x16x32_bf16 v[6:9], v[168:171], v[214:217], v[6:9]
	v_mfma_f32_16x16x32_bf16 v[2:5], v[176:179], v[214:217], v[2:5]
	v_mfma_f32_16x16x32_bf16 v[50:53], v[168:171], v[190:193], v[50:53]
	v_mfma_f32_16x16x32_bf16 v[54:57], v[176:179], v[190:193], v[54:57]
	s_barrier
	s_add_i32 s54, 0, 0x18000
	s_add_i32 s55, 0, 0x1c000
	v_add_u32_e32 v70, s54, v153
	v_add_u32_e32 v176, s55, v153
	ds_read_b128 v[58:61], v70
	ds_read_b128 v[62:65], v70 offset:1024
	ds_read_b128 v[66:69], v70 offset:2048
	ds_read_b128 v[70:73], v70 offset:3072
	ds_read_b128 v[164:167], v176
	ds_read_b128 v[168:171], v176 offset:1024
	ds_read_b128 v[172:175], v176 offset:2048
	ds_read_b128 v[176:179], v176 offset:3072
	s_add_u32 s34, s34, 0x40000
	s_addc_u32 s35, s35, 0
	s_mov_b32 m0, s45
	v_lshl_add_u64 v[228:229], s[34:35], 0, v[148:149]
	ds_read_b128 v[180:183], v187 offset:32768
	ds_read_b128 v[190:193], v187 offset:33792
	ds_read_b128 v[194:197], v187 offset:34816
	ds_read_b128 v[198:201], v187 offset:35840
	ds_read_b128 v[202:205], v187 offset:36864
	ds_read_b128 v[206:209], v187 offset:37888
	ds_read_b128 v[210:213], v187 offset:38912
	ds_read_b128 v[214:217], v187 offset:39936
	global_load_lds_dwordx4 v[228:229], off
	v_lshl_add_u64 v[228:229], s[34:35], 0, v[150:151]
	s_mov_b32 m0, s46
	s_nop 0
	global_load_lds_dwordx4 v[228:229], off
	s_waitcnt vmcnt(8)
	s_waitcnt lgkmcnt(0)
	s_barrier
	s_waitcnt lgkmcnt(0)
	v_mfma_f32_16x16x32_bf16 v[142:145], v[58:61], v[180:183], v[142:145]
	v_mfma_f32_16x16x32_bf16 v[138:141], v[66:69], v[180:183], v[138:141]
	v_mfma_f32_16x16x32_bf16 v[126:129], v[58:61], v[194:197], v[126:129]
	v_mfma_f32_16x16x32_bf16 v[122:125], v[66:69], v[194:197], v[122:125]
	v_mfma_f32_16x16x32_bf16 v[110:113], v[58:61], v[202:205], v[110:113]
	v_mfma_f32_16x16x32_bf16 v[106:109], v[66:69], v[202:205], v[106:109]
	v_mfma_f32_16x16x32_bf16 v[94:97], v[58:61], v[210:213], v[94:97]
	v_mfma_f32_16x16x32_bf16 v[90:93], v[66:69], v[210:213], v[90:93]
	v_mfma_f32_16x16x32_bf16 v[142:145], v[62:65], v[190:193], v[142:145]
	v_mfma_f32_16x16x32_bf16 v[138:141], v[70:73], v[190:193], v[138:141]
	v_mfma_f32_16x16x32_bf16 v[126:129], v[62:65], v[198:201], v[126:129]
	v_mfma_f32_16x16x32_bf16 v[122:125], v[70:73], v[198:201], v[122:125]
	v_mfma_f32_16x16x32_bf16 v[110:113], v[62:65], v[206:209], v[110:113]
	v_mfma_f32_16x16x32_bf16 v[106:109], v[70:73], v[206:209], v[106:109]
	v_mfma_f32_16x16x32_bf16 v[94:97], v[62:65], v[214:217], v[94:97]
	v_mfma_f32_16x16x32_bf16 v[90:93], v[70:73], v[214:217], v[90:93]
	v_mfma_f32_16x16x32_bf16 v[134:137], v[164:167], v[180:183], v[134:137]
	v_mfma_f32_16x16x32_bf16 v[130:133], v[172:175], v[180:183], v[130:133]
	v_mfma_f32_16x16x32_bf16 v[118:121], v[164:167], v[194:197], v[118:121]
	v_mfma_f32_16x16x32_bf16 v[114:117], v[172:175], v[194:197], v[114:117]
	v_mfma_f32_16x16x32_bf16 v[102:105], v[164:167], v[202:205], v[102:105]
	v_mfma_f32_16x16x32_bf16 v[98:101], v[172:175], v[202:205], v[98:101]
	v_mfma_f32_16x16x32_bf16 v[86:89], v[164:167], v[210:213], v[86:89]
	v_mfma_f32_16x16x32_bf16 v[82:85], v[172:175], v[210:213], v[82:85]
	v_mfma_f32_16x16x32_bf16 v[134:137], v[168:171], v[190:193], v[134:137]
	v_mfma_f32_16x16x32_bf16 v[130:133], v[176:179], v[190:193], v[130:133]
	v_mfma_f32_16x16x32_bf16 v[118:121], v[168:171], v[198:201], v[118:121]
	v_mfma_f32_16x16x32_bf16 v[114:117], v[176:179], v[198:201], v[114:117]
	v_mfma_f32_16x16x32_bf16 v[102:105], v[168:171], v[206:209], v[102:105]
	v_mfma_f32_16x16x32_bf16 v[98:101], v[176:179], v[206:209], v[98:101]
	v_mfma_f32_16x16x32_bf16 v[86:89], v[168:171], v[214:217], v[86:89]
	v_mfma_f32_16x16x32_bf16 v[82:85], v[176:179], v[214:217], v[82:85]
	s_barrier
	s_add_i32 s34, s54, s42
	v_lshl_add_u64 v[218:219], v[218:219], 0, s[2:3]
	s_mov_b32 m0, s34
	ds_read_b128 v[180:183], v187 offset:49152
	ds_read_b128 v[190:193], v187 offset:50176
	ds_read_b128 v[194:197], v187 offset:51200
	ds_read_b128 v[198:201], v187 offset:52224
	ds_read_b128 v[202:205], v187 offset:53248
	ds_read_b128 v[206:209], v187 offset:54272
	ds_read_b128 v[210:213], v187 offset:55296
	ds_read_b128 v[214:217], v187 offset:56320
	global_load_lds_dwordx4 v[218:219], off
	s_add_i32 m0, s34, 0x2000
	s_add_u32 s30, s30, 0x40080
	v_lshl_add_u64 v[218:219], v[220:221], 0, s[2:3]
	s_addc_u32 s31, s31, 0
	s_add_i32 s34, s55, s42
	global_load_lds_dwordx4 v[218:219], off
	v_lshl_add_u64 v[218:219], s[30:31], 0, v[148:149]
	s_mov_b32 m0, s34
	s_nop 0
	global_load_lds_dwordx4 v[218:219], off
	v_lshl_add_u64 v[218:219], s[30:31], 0, v[150:151]
	s_add_i32 m0, s34, 0x2000
	s_nop 0
	global_load_lds_dwordx4 v[218:219], off
	v_lshl_add_u64 v[218:219], v[222:223], 0, s[2:3]
	s_mov_b32 m0, s50
	s_nop 0
	global_load_lds_dwordx4 v[218:219], off
	v_lshl_add_u64 v[218:219], v[226:227], 0, s[2:3]
	s_mov_b32 m0, s51
	s_nop 0
	global_load_lds_dwordx4 v[218:219], off
	s_waitcnt vmcnt(8)
	s_waitcnt lgkmcnt(0)
	s_barrier
	s_waitcnt lgkmcnt(0)
	v_mfma_f32_16x16x32_bf16 v[78:81], v[58:61], v[180:183], v[78:81]
	v_mfma_f32_16x16x32_bf16 v[74:77], v[66:69], v[180:183], v[74:77]
	v_mfma_f32_16x16x32_bf16 v[46:49], v[58:61], v[194:197], v[46:49]
	v_mfma_f32_16x16x32_bf16 v[42:45], v[66:69], v[194:197], v[42:45]
	v_mfma_f32_16x16x32_bf16 v[30:33], v[58:61], v[202:205], v[30:33]
	v_mfma_f32_16x16x32_bf16 v[26:29], v[66:69], v[202:205], v[26:29]
	v_mfma_f32_16x16x32_bf16 v[14:17], v[58:61], v[210:213], v[14:17]
	v_mfma_f32_16x16x32_bf16 v[10:13], v[66:69], v[210:213], v[10:13]
	v_mfma_f32_16x16x32_bf16 v[78:81], v[62:65], v[190:193], v[78:81]
	v_mfma_f32_16x16x32_bf16 v[74:77], v[70:73], v[190:193], v[74:77]
	v_mfma_f32_16x16x32_bf16 v[46:49], v[62:65], v[198:201], v[46:49]
	v_mfma_f32_16x16x32_bf16 v[42:45], v[70:73], v[198:201], v[42:45]
	v_mfma_f32_16x16x32_bf16 v[30:33], v[62:65], v[206:209], v[30:33]
	v_mfma_f32_16x16x32_bf16 v[26:29], v[70:73], v[206:209], v[26:29]
	v_mfma_f32_16x16x32_bf16 v[14:17], v[62:65], v[214:217], v[14:17]
	v_mfma_f32_16x16x32_bf16 v[10:13], v[70:73], v[214:217], v[10:13]
	v_mfma_f32_16x16x32_bf16 v[50:53], v[164:167], v[180:183], v[50:53]
	v_mfma_f32_16x16x32_bf16 v[70:73], v[168:171], v[190:193], v[50:53]
	v_mfma_f32_16x16x32_bf16 v[50:53], v[172:175], v[180:183], v[54:57]
	v_mfma_f32_16x16x32_bf16 v[38:41], v[164:167], v[194:197], v[38:41]
	v_mfma_f32_16x16x32_bf16 v[34:37], v[172:175], v[194:197], v[34:37]
	v_mfma_f32_16x16x32_bf16 v[22:25], v[164:167], v[202:205], v[22:25]
	v_mfma_f32_16x16x32_bf16 v[18:21], v[172:175], v[202:205], v[18:21]
	v_mfma_f32_16x16x32_bf16 v[6:9], v[164:167], v[210:213], v[6:9]
	v_mfma_f32_16x16x32_bf16 v[2:5], v[172:175], v[210:213], v[2:5]
	v_mfma_f32_16x16x32_bf16 v[66:69], v[176:179], v[190:193], v[50:53]
	v_mfma_f32_16x16x32_bf16 v[38:41], v[168:171], v[198:201], v[38:41]
	v_mfma_f32_16x16x32_bf16 v[34:37], v[176:179], v[198:201], v[34:37]
	v_mfma_f32_16x16x32_bf16 v[22:25], v[168:171], v[206:209], v[22:25]
	v_mfma_f32_16x16x32_bf16 v[18:21], v[176:179], v[206:209], v[18:21]
	v_mfma_f32_16x16x32_bf16 v[6:9], v[168:171], v[214:217], v[6:9]
	v_mfma_f32_16x16x32_bf16 v[2:5], v[176:179], v[214:217], v[2:5]
	s_barrier
	s_add_i32 s37, s37, 2
	s_add_u32 s0, s0, 0x100
	s_addc_u32 s1, s1, 0
	s_add_u32 s33, s33, 0x100
	s_addc_u32 s36, s36, 0
	s_cmp_gt_u32 s37, 13
	s_cbranch_scc0 .LBB0_878
	s_setprio 0
	s_and_b64 vcc, exec, s[18:19]
	s_cbranch_vccz .LBB0_881
	s_barrier

.LBB0_1263:
	s_ashr_i32 s23, s22, 31
	s_lshl_b64 s[26:27], s[22:23], 19
	s_add_u32 s5, s47, s26
	s_addc_u32 s7, s54, s27
	s_ashr_i32 s21, s20, 31
	s_lshl_b64 s[28:29], s[20:21], 7
	s_add_u32 s26, s5, s28
	s_addc_u32 s27, s7, s29
	s_and_b64 s[38:39], s[8:9], exec
	s_cselect_b32 s5, s27, s35
	s_cselect_b32 s7, s26, s34
	s_ashr_i32 s25, s24, 31
	s_lshl_b64 s[38:39], s[24:25], 19
	s_add_u32 s21, s55, s38
	s_addc_u32 s23, s56, s39
	s_add_u32 s28, s21, s28
	s_addc_u32 s29, s23, s29
	s_and_b64 s[38:39], s[8:9], exec
	s_cselect_b32 s21, s29, s37
	s_cselect_b32 s23, s28, s36
	s_add_u32 s34, s34, 0x40080
	s_addc_u32 s35, s35, 0
	s_add_u32 s25, s36, 0x100
	v_mov_b32_e32 v2, 0
	s_addc_u32 s31, s37, 0
	s_mov_b32 s40, 2
	v_mov_b32_e32 v3, v2
	v_mov_b32_e32 v4, v2
	v_mov_b32_e32 v5, v2
	v_mov_b32_e32 v6, v2
	v_mov_b32_e32 v7, v2
	v_mov_b32_e32 v8, v2
	v_mov_b32_e32 v9, v2
	v_mov_b32_e32 v10, v2
	v_mov_b32_e32 v11, v2
	v_mov_b32_e32 v12, v2
	v_mov_b32_e32 v13, v2
	v_mov_b32_e32 v14, v2
	v_mov_b32_e32 v15, v2
	v_mov_b32_e32 v16, v2
	v_mov_b32_e32 v17, v2
	v_mov_b32_e32 v18, v2
	v_mov_b32_e32 v19, v2
	v_mov_b32_e32 v20, v2
	v_mov_b32_e32 v21, v2
	v_mov_b32_e32 v22, v2
	v_mov_b32_e32 v23, v2
	v_mov_b32_e32 v24, v2
	v_mov_b32_e32 v25, v2
	v_mov_b32_e32 v26, v2
	v_mov_b32_e32 v27, v2
	v_mov_b32_e32 v28, v2
	v_mov_b32_e32 v29, v2
	v_mov_b32_e32 v30, v2
	v_mov_b32_e32 v31, v2
	v_mov_b32_e32 v32, v2
	v_mov_b32_e32 v33, v2
	v_mov_b32_e32 v66, v2
	v_mov_b32_e32 v67, v2
	v_mov_b32_e32 v68, v2
	v_mov_b32_e32 v69, v2
	v_mov_b32_e32 v70, v2
	v_mov_b32_e32 v71, v2
	v_mov_b32_e32 v72, v2
	v_mov_b32_e32 v73, v2
	v_mov_b32_e32 v78, v2
	v_mov_b32_e32 v79, v2
	v_mov_b32_e32 v80, v2
	v_mov_b32_e32 v81, v2
	v_mov_b32_e32 v86, v2
	v_mov_b32_e32 v87, v2
	v_mov_b32_e32 v88, v2
	v_mov_b32_e32 v89, v2
	v_mov_b32_e32 v106, v2
	v_mov_b32_e32 v107, v2
	v_mov_b32_e32 v108, v2
	v_mov_b32_e32 v109, v2
	v_mov_b32_e32 v110, v2
	v_mov_b32_e32 v111, v2
	v_mov_b32_e32 v112, v2
	v_mov_b32_e32 v113, v2
	v_mov_b32_e32 v126, v2
	v_mov_b32_e32 v127, v2
	v_mov_b32_e32 v128, v2
	v_mov_b32_e32 v129, v2
	v_mov_b32_e32 v122, v2
	v_mov_b32_e32 v123, v2
	v_mov_b32_e32 v124, v2
	v_mov_b32_e32 v125, v2
	v_mov_b32_e32 v34, v2
	v_mov_b32_e32 v35, v2
	v_mov_b32_e32 v36, v2
	v_mov_b32_e32 v37, v2
	v_mov_b32_e32 v38, v2
	v_mov_b32_e32 v39, v2
	v_mov_b32_e32 v40, v2
	v_mov_b32_e32 v41, v2
	v_mov_b32_e32 v42, v2
	v_mov_b32_e32 v43, v2
	v_mov_b32_e32 v44, v2
	v_mov_b32_e32 v45, v2
	v_mov_b32_e32 v46, v2
	v_mov_b32_e32 v47, v2
	v_mov_b32_e32 v48, v2
	v_mov_b32_e32 v49, v2
	v_mov_b32_e32 v50, v2
	v_mov_b32_e32 v51, v2
	v_mov_b32_e32 v52, v2
	v_mov_b32_e32 v53, v2
	v_mov_b32_e32 v54, v2
	v_mov_b32_e32 v55, v2
	v_mov_b32_e32 v56, v2
	v_mov_b32_e32 v57, v2
	v_mov_b32_e32 v58, v2
	v_mov_b32_e32 v59, v2
	v_mov_b32_e32 v60, v2
	v_mov_b32_e32 v61, v2
	v_mov_b32_e32 v62, v2
	v_mov_b32_e32 v63, v2
	v_mov_b32_e32 v64, v2
	v_mov_b32_e32 v65, v2
	v_mov_b32_e32 v118, v2
	v_mov_b32_e32 v119, v2
	v_mov_b32_e32 v120, v2
	v_mov_b32_e32 v121, v2
	v_mov_b32_e32 v114, v2
	v_mov_b32_e32 v115, v2
	v_mov_b32_e32 v116, v2
	v_mov_b32_e32 v117, v2
	v_mov_b32_e32 v102, v2
	v_mov_b32_e32 v103, v2
	v_mov_b32_e32 v104, v2
	v_mov_b32_e32 v105, v2
	v_mov_b32_e32 v98, v2
	v_mov_b32_e32 v99, v2
	v_mov_b32_e32 v100, v2
	v_mov_b32_e32 v101, v2
	v_mov_b32_e32 v94, v2
	v_mov_b32_e32 v95, v2
	v_mov_b32_e32 v96, v2
	v_mov_b32_e32 v97, v2
	v_mov_b32_e32 v90, v2
	v_mov_b32_e32 v91, v2
	v_mov_b32_e32 v92, v2
	v_mov_b32_e32 v93, v2
	v_mov_b32_e32 v82, v2
	v_mov_b32_e32 v83, v2
	v_mov_b32_e32 v84, v2
	v_mov_b32_e32 v85, v2
	v_mov_b32_e32 v74, v2
	v_mov_b32_e32 v75, v2
	v_mov_b32_e32 v76, v2
	v_mov_b32_e32 v77, v2
	v_readfirstlane_b32 s84, v224
	s_bitcmp1_b32 s84, 8
	s_cbranch_scc0 .Lsprio_5
	s_setprio 1
.Lsprio_5:
.LBB0_1264:
	s_add_u32 s36, s34, 0xfffc0080
	s_addc_u32 s37, s35, -1
	s_add_i32 s41, 0, 0x10000
	s_cmp_eq_u32 s74, s40
	s_cselect_b32 s39, s5, s37
	s_cselect_b32 s38, s7, s36
	s_cselect_b32 s37, s21, s31
	s_cselect_b32 s36, s23, s25
	s_add_i32 s44, 0, 0x14000
	v_add_u32_e32 v142, s41, v236
	v_add_u32_e32 v174, s44, v236
	ds_read_b128 v[130:133], v142
	ds_read_b128 v[134:137], v142 offset:1024
	ds_read_b128 v[138:141], v142 offset:2048
	ds_read_b128 v[142:145], v142 offset:3072
	ds_read_b128 v[162:165], v174
	ds_read_b128 v[166:169], v174 offset:1024
	ds_read_b128 v[170:173], v174 offset:2048
	ds_read_b128 v[174:177], v174 offset:3072
	v_lshl_add_u64 v[210:211], s[34:35], 0, v[158:159]
	s_add_i32 m0, s58, 0xc000
	ds_read_b128 v[178:181], v245
	ds_read_b128 v[182:185], v245 offset:1024
	ds_read_b128 v[186:189], v245 offset:2048
	ds_read_b128 v[190:193], v245 offset:3072
	ds_read_b128 v[194:197], v245 offset:4096
	ds_read_b128 v[198:201], v245 offset:5120
	ds_read_b128 v[202:205], v245 offset:6144
	ds_read_b128 v[206:209], v245 offset:7168
	global_load_lds_dwordx4 v[210:211], off
	v_lshl_add_u64 v[210:211], s[34:35], 0, v[160:161]
	s_add_i32 m0, s58, 0xe000
	s_nop 0
	global_load_lds_dwordx4 v[210:211], off
	s_waitcnt vmcnt(8)
	s_waitcnt lgkmcnt(0)
	s_barrier
	s_waitcnt lgkmcnt(0)
	v_mfma_f32_16x16x32_bf16 v[74:77], v[130:133], v[178:181], v[74:77]
	v_mfma_f32_16x16x32_bf16 v[82:85], v[138:141], v[178:181], v[82:85]
	v_mfma_f32_16x16x32_bf16 v[90:93], v[130:133], v[186:189], v[90:93]
	v_mfma_f32_16x16x32_bf16 v[94:97], v[138:141], v[186:189], v[94:97]
	v_mfma_f32_16x16x32_bf16 v[98:101], v[130:133], v[194:197], v[98:101]
	v_mfma_f32_16x16x32_bf16 v[102:105], v[138:141], v[194:197], v[102:105]
	v_mfma_f32_16x16x32_bf16 v[114:117], v[130:133], v[202:205], v[114:117]
	v_mfma_f32_16x16x32_bf16 v[118:121], v[138:141], v[202:205], v[118:121]
	v_mfma_f32_16x16x32_bf16 v[74:77], v[134:137], v[182:185], v[74:77]
	v_mfma_f32_16x16x32_bf16 v[82:85], v[142:145], v[182:185], v[82:85]
	v_mfma_f32_16x16x32_bf16 v[90:93], v[134:137], v[190:193], v[90:93]
	v_mfma_f32_16x16x32_bf16 v[94:97], v[142:145], v[190:193], v[94:97]
	v_mfma_f32_16x16x32_bf16 v[98:101], v[134:137], v[198:201], v[98:101]
	v_mfma_f32_16x16x32_bf16 v[102:105], v[142:145], v[198:201], v[102:105]
	v_mfma_f32_16x16x32_bf16 v[114:117], v[134:137], v[206:209], v[114:117]
	v_mfma_f32_16x16x32_bf16 v[118:121], v[142:145], v[206:209], v[118:121]
	v_mfma_f32_16x16x32_bf16 v[62:65], v[162:165], v[178:181], v[62:65]
	v_mfma_f32_16x16x32_bf16 v[58:61], v[170:173], v[178:181], v[58:61]
	v_mfma_f32_16x16x32_bf16 v[54:57], v[162:165], v[186:189], v[54:57]
	v_mfma_f32_16x16x32_bf16 v[50:53], v[170:173], v[186:189], v[50:53]
	v_mfma_f32_16x16x32_bf16 v[46:49], v[162:165], v[194:197], v[46:49]
	v_mfma_f32_16x16x32_bf16 v[42:45], v[170:173], v[194:197], v[42:45]
	v_mfma_f32_16x16x32_bf16 v[38:41], v[162:165], v[202:205], v[38:41]
	v_mfma_f32_16x16x32_bf16 v[34:37], v[170:173], v[202:205], v[34:37]
	v_mfma_f32_16x16x32_bf16 v[62:65], v[166:169], v[182:185], v[62:65]
	v_mfma_f32_16x16x32_bf16 v[58:61], v[174:177], v[182:185], v[58:61]
	v_mfma_f32_16x16x32_bf16 v[54:57], v[166:169], v[190:193], v[54:57]
	v_mfma_f32_16x16x32_bf16 v[50:53], v[174:177], v[190:193], v[50:53]
	v_mfma_f32_16x16x32_bf16 v[46:49], v[166:169], v[198:201], v[46:49]
	v_mfma_f32_16x16x32_bf16 v[42:45], v[174:177], v[198:201], v[42:45]
	v_mfma_f32_16x16x32_bf16 v[38:41], v[166:169], v[206:209], v[38:41]
	v_mfma_f32_16x16x32_bf16 v[34:37], v[174:177], v[206:209], v[34:37]
	s_barrier
	s_add_i32 s41, s41, s57
	v_lshl_add_u64 v[210:211], s[36:37], 0, v[150:151]
	s_mov_b32 m0, s41
	ds_read_b128 v[178:181], v245 offset:16384
	ds_read_b128 v[182:185], v245 offset:17408
	ds_read_b128 v[186:189], v245 offset:18432
	ds_read_b128 v[190:193], v245 offset:19456
	ds_read_b128 v[194:197], v245 offset:20480
	ds_read_b128 v[198:201], v245 offset:21504
	ds_read_b128 v[202:205], v245 offset:22528
	ds_read_b128 v[206:209], v245 offset:23552
	global_load_lds_dwordx4 v[210:211], off
	s_add_i32 m0, s41, 0x2000
	s_add_u32 s42, s36, 0x40000
	v_lshl_add_u64 v[212:213], s[36:37], 0, v[154:155]
	s_addc_u32 s43, s37, 0
	s_add_i32 s41, s44, s57
	global_load_lds_dwordx4 v[212:213], off
	v_lshl_add_u64 v[214:215], s[42:43], 0, v[150:151]
	s_mov_b32 m0, s41
	v_lshl_add_u64 v[216:217], s[38:39], 0, v[152:153]
	global_load_lds_dwordx4 v[214:215], off
	v_lshl_add_u64 v[214:215], s[42:43], 0, v[154:155]
	s_add_i32 m0, s41, 0x2000
	s_nop 0
	global_load_lds_dwordx4 v[214:215], off
	v_lshl_add_u64 v[214:215], s[38:39], 0, v[148:149]
	s_mov_b32 m0, s58
	s_nop 0
	global_load_lds_dwordx4 v[214:215], off
	s_mov_b32 m0, s59
	s_nop 0
	global_load_lds_dwordx4 v[216:217], off
	s_waitcnt vmcnt(8)
	s_waitcnt lgkmcnt(0)
	s_barrier
	s_waitcnt lgkmcnt(0)
	v_mfma_f32_16x16x32_bf16 v[122:125], v[130:133], v[178:181], v[122:125]
	v_mfma_f32_16x16x32_bf16 v[126:129], v[138:141], v[178:181], v[126:129]
	v_mfma_f32_16x16x32_bf16 v[110:113], v[130:133], v[186:189], v[110:113]
	v_mfma_f32_16x16x32_bf16 v[106:109], v[138:141], v[186:189], v[106:109]
	v_mfma_f32_16x16x32_bf16 v[86:89], v[130:133], v[194:197], v[86:89]
	v_mfma_f32_16x16x32_bf16 v[78:81], v[138:141], v[194:197], v[78:81]
	v_mfma_f32_16x16x32_bf16 v[70:73], v[130:133], v[202:205], v[70:73]
	v_mfma_f32_16x16x32_bf16 v[66:69], v[138:141], v[202:205], v[66:69]
	v_mfma_f32_16x16x32_bf16 v[122:125], v[134:137], v[182:185], v[122:125]
	v_mfma_f32_16x16x32_bf16 v[126:129], v[142:145], v[182:185], v[126:129]
	v_mfma_f32_16x16x32_bf16 v[110:113], v[134:137], v[190:193], v[110:113]
	v_mfma_f32_16x16x32_bf16 v[106:109], v[142:145], v[190:193], v[106:109]
	v_mfma_f32_16x16x32_bf16 v[86:89], v[134:137], v[198:201], v[86:89]
	v_mfma_f32_16x16x32_bf16 v[78:81], v[142:145], v[198:201], v[78:81]
	v_mfma_f32_16x16x32_bf16 v[70:73], v[134:137], v[206:209], v[70:73]
	v_mfma_f32_16x16x32_bf16 v[66:69], v[142:145], v[206:209], v[66:69]
	v_mfma_f32_16x16x32_bf16 v[30:33], v[162:165], v[178:181], v[30:33]
	v_mfma_f32_16x16x32_bf16 v[26:29], v[170:173], v[178:181], v[26:29]
	v_mfma_f32_16x16x32_bf16 v[22:25], v[162:165], v[186:189], v[22:25]
	v_mfma_f32_16x16x32_bf16 v[18:21], v[170:173], v[186:189], v[18:21]
	v_mfma_f32_16x16x32_bf16 v[14:17], v[162:165], v[194:197], v[14:17]
	v_mfma_f32_16x16x32_bf16 v[10:13], v[170:173], v[194:197], v[10:13]
	v_mfma_f32_16x16x32_bf16 v[6:9], v[162:165], v[202:205], v[6:9]
	v_mfma_f32_16x16x32_bf16 v[2:5], v[170:173], v[202:205], v[2:5]
	v_mfma_f32_16x16x32_bf16 v[30:33], v[166:169], v[182:185], v[30:33]
	v_mfma_f32_16x16x32_bf16 v[26:29], v[174:177], v[182:185], v[26:29]
	v_mfma_f32_16x16x32_bf16 v[22:25], v[166:169], v[190:193], v[22:25]
	v_mfma_f32_16x16x32_bf16 v[18:21], v[174:177], v[190:193], v[18:21]
	v_mfma_f32_16x16x32_bf16 v[14:17], v[166:169], v[198:201], v[14:17]
	v_mfma_f32_16x16x32_bf16 v[10:13], v[174:177], v[198:201], v[10:13]
	v_mfma_f32_16x16x32_bf16 v[6:9], v[166:169], v[206:209], v[6:9]
	v_mfma_f32_16x16x32_bf16 v[2:5], v[174:177], v[206:209], v[2:5]
	s_barrier
	s_add_i32 s41, 0, 0x18000
	s_add_i32 s42, 0, 0x1c000
	v_add_u32_e32 v142, s41, v236
	v_add_u32_e32 v174, s42, v236
	ds_read_b128 v[130:133], v142
	ds_read_b128 v[134:137], v142 offset:1024
	ds_read_b128 v[138:141], v142 offset:2048
	ds_read_b128 v[142:145], v142 offset:3072
	ds_read_b128 v[162:165], v174
	ds_read_b128 v[166:169], v174 offset:1024
	ds_read_b128 v[170:173], v174 offset:2048
	ds_read_b128 v[174:177], v174 offset:3072
	s_add_u32 s38, s38, 0x40000
	s_addc_u32 s39, s39, 0
	s_mov_b32 m0, s60
	v_lshl_add_u64 v[218:219], s[38:39], 0, v[148:149]
	ds_read_b128 v[178:181], v245 offset:32768
	ds_read_b128 v[182:185], v245 offset:33792
	ds_read_b128 v[186:189], v245 offset:34816
	ds_read_b128 v[190:193], v245 offset:35840
	ds_read_b128 v[194:197], v245 offset:36864
	ds_read_b128 v[198:201], v245 offset:37888
	ds_read_b128 v[202:205], v245 offset:38912
	ds_read_b128 v[206:209], v245 offset:39936
	global_load_lds_dwordx4 v[218:219], off
	v_lshl_add_u64 v[218:219], s[38:39], 0, v[152:153]
	s_mov_b32 m0, s61
	s_nop 0
	global_load_lds_dwordx4 v[218:219], off
	s_waitcnt vmcnt(8)
	s_waitcnt lgkmcnt(0)
	s_barrier
	s_waitcnt lgkmcnt(0)
	v_mfma_f32_16x16x32_bf16 v[74:77], v[130:133], v[178:181], v[74:77]
	v_mfma_f32_16x16x32_bf16 v[82:85], v[138:141], v[178:181], v[82:85]
	v_mfma_f32_16x16x32_bf16 v[90:93], v[130:133], v[186:189], v[90:93]
	v_mfma_f32_16x16x32_bf16 v[94:97], v[138:141], v[186:189], v[94:97]
	v_mfma_f32_16x16x32_bf16 v[98:101], v[130:133], v[194:197], v[98:101]
	v_mfma_f32_16x16x32_bf16 v[102:105], v[138:141], v[194:197], v[102:105]
	v_mfma_f32_16x16x32_bf16 v[114:117], v[130:133], v[202:205], v[114:117]
	v_mfma_f32_16x16x32_bf16 v[118:121], v[138:141], v[202:205], v[118:121]
	v_mfma_f32_16x16x32_bf16 v[74:77], v[134:137], v[182:185], v[74:77]
	v_mfma_f32_16x16x32_bf16 v[82:85], v[142:145], v[182:185], v[82:85]
	v_mfma_f32_16x16x32_bf16 v[90:93], v[134:137], v[190:193], v[90:93]
	v_mfma_f32_16x16x32_bf16 v[94:97], v[142:145], v[190:193], v[94:97]
	v_mfma_f32_16x16x32_bf16 v[98:101], v[134:137], v[198:201], v[98:101]
	v_mfma_f32_16x16x32_bf16 v[102:105], v[142:145], v[198:201], v[102:105]
	v_mfma_f32_16x16x32_bf16 v[114:117], v[134:137], v[206:209], v[114:117]
	v_mfma_f32_16x16x32_bf16 v[118:121], v[142:145], v[206:209], v[118:121]
	v_mfma_f32_16x16x32_bf16 v[62:65], v[162:165], v[178:181], v[62:65]
	v_mfma_f32_16x16x32_bf16 v[58:61], v[170:173], v[178:181], v[58:61]
	v_mfma_f32_16x16x32_bf16 v[54:57], v[162:165], v[186:189], v[54:57]
	v_mfma_f32_16x16x32_bf16 v[50:53], v[170:173], v[186:189], v[50:53]
	v_mfma_f32_16x16x32_bf16 v[46:49], v[162:165], v[194:197], v[46:49]
	v_mfma_f32_16x16x32_bf16 v[42:45], v[170:173], v[194:197], v[42:45]
	v_mfma_f32_16x16x32_bf16 v[38:41], v[162:165], v[202:205], v[38:41]
	v_mfma_f32_16x16x32_bf16 v[34:37], v[170:173], v[202:205], v[34:37]
	v_mfma_f32_16x16x32_bf16 v[62:65], v[166:169], v[182:185], v[62:65]
	v_mfma_f32_16x16x32_bf16 v[58:61], v[174:177], v[182:185], v[58:61]
	v_mfma_f32_16x16x32_bf16 v[54:57], v[166:169], v[190:193], v[54:57]
	v_mfma_f32_16x16x32_bf16 v[50:53], v[174:177], v[190:193], v[50:53]
	v_mfma_f32_16x16x32_bf16 v[46:49], v[166:169], v[198:201], v[46:49]
	v_mfma_f32_16x16x32_bf16 v[42:45], v[174:177], v[198:201], v[42:45]
	v_mfma_f32_16x16x32_bf16 v[38:41], v[166:169], v[206:209], v[38:41]
	v_mfma_f32_16x16x32_bf16 v[34:37], v[174:177], v[206:209], v[34:37]
	s_barrier
	s_add_i32 s38, s41, s57
	v_lshl_add_u64 v[210:211], v[210:211], 0, s[2:3]
	s_mov_b32 m0, s38
	ds_read_b128 v[178:181], v245 offset:49152
	ds_read_b128 v[182:185], v245 offset:50176
	ds_read_b128 v[186:189], v245 offset:51200
	ds_read_b128 v[190:193], v245 offset:52224
	ds_read_b128 v[194:197], v245 offset:53248
	ds_read_b128 v[198:201], v245 offset:54272
	ds_read_b128 v[202:205], v245 offset:55296
	ds_read_b128 v[206:209], v245 offset:56320
	global_load_lds_dwordx4 v[210:211], off
	s_add_i32 m0, s38, 0x2000
	s_add_u32 s36, s36, 0x40080
	v_lshl_add_u64 v[210:211], v[212:213], 0, s[2:3]
	s_addc_u32 s37, s37, 0
	s_add_i32 s38, s42, s57
	global_load_lds_dwordx4 v[210:211], off
	v_lshl_add_u64 v[210:211], s[36:37], 0, v[150:151]
	s_mov_b32 m0, s38
	s_nop 0
	global_load_lds_dwordx4 v[210:211], off
	v_lshl_add_u64 v[210:211], s[36:37], 0, v[154:155]
	s_add_i32 m0, s38, 0x2000
	s_nop 0
	global_load_lds_dwordx4 v[210:211], off
	v_lshl_add_u64 v[210:211], v[214:215], 0, s[2:3]
	s_mov_b32 m0, s70
	s_nop 0
	global_load_lds_dwordx4 v[210:211], off
	v_lshl_add_u64 v[210:211], v[216:217], 0, s[2:3]
	s_mov_b32 m0, s71
	s_nop 0
	global_load_lds_dwordx4 v[210:211], off
	s_waitcnt vmcnt(8)
	s_waitcnt lgkmcnt(0)
	s_barrier
	s_waitcnt lgkmcnt(0)
	v_mfma_f32_16x16x32_bf16 v[122:125], v[130:133], v[178:181], v[122:125]
	v_mfma_f32_16x16x32_bf16 v[126:129], v[138:141], v[178:181], v[126:129]
	v_mfma_f32_16x16x32_bf16 v[110:113], v[130:133], v[186:189], v[110:113]
	v_mfma_f32_16x16x32_bf16 v[106:109], v[138:141], v[186:189], v[106:109]
	v_mfma_f32_16x16x32_bf16 v[86:89], v[130:133], v[194:197], v[86:89]
	v_mfma_f32_16x16x32_bf16 v[78:81], v[138:141], v[194:197], v[78:81]
	v_mfma_f32_16x16x32_bf16 v[70:73], v[130:133], v[202:205], v[70:73]
	v_mfma_f32_16x16x32_bf16 v[66:69], v[138:141], v[202:205], v[66:69]
	v_mfma_f32_16x16x32_bf16 v[122:125], v[134:137], v[182:185], v[122:125]
	v_mfma_f32_16x16x32_bf16 v[126:129], v[142:145], v[182:185], v[126:129]
	v_mfma_f32_16x16x32_bf16 v[110:113], v[134:137], v[190:193], v[110:113]
	v_mfma_f32_16x16x32_bf16 v[106:109], v[142:145], v[190:193], v[106:109]
	v_mfma_f32_16x16x32_bf16 v[86:89], v[134:137], v[198:201], v[86:89]
	v_mfma_f32_16x16x32_bf16 v[78:81], v[142:145], v[198:201], v[78:81]
	v_mfma_f32_16x16x32_bf16 v[70:73], v[134:137], v[206:209], v[70:73]
	v_mfma_f32_16x16x32_bf16 v[66:69], v[142:145], v[206:209], v[66:69]
	v_mfma_f32_16x16x32_bf16 v[30:33], v[162:165], v[178:181], v[30:33]
	v_mfma_f32_16x16x32_bf16 v[26:29], v[170:173], v[178:181], v[26:29]
	v_mfma_f32_16x16x32_bf16 v[22:25], v[162:165], v[186:189], v[22:25]
	v_mfma_f32_16x16x32_bf16 v[18:21], v[170:173], v[186:189], v[18:21]
	v_mfma_f32_16x16x32_bf16 v[14:17], v[162:165], v[194:197], v[14:17]
	v_mfma_f32_16x16x32_bf16 v[10:13], v[170:173], v[194:197], v[10:13]
	v_mfma_f32_16x16x32_bf16 v[6:9], v[162:165], v[202:205], v[6:9]
	v_mfma_f32_16x16x32_bf16 v[2:5], v[170:173], v[202:205], v[2:5]
	v_mfma_f32_16x16x32_bf16 v[30:33], v[166:169], v[182:185], v[30:33]
	v_mfma_f32_16x16x32_bf16 v[26:29], v[174:177], v[182:185], v[26:29]
	v_mfma_f32_16x16x32_bf16 v[22:25], v[166:169], v[190:193], v[22:25]
	v_mfma_f32_16x16x32_bf16 v[18:21], v[174:177], v[190:193], v[18:21]
	v_mfma_f32_16x16x32_bf16 v[14:17], v[166:169], v[198:201], v[14:17]
	v_mfma_f32_16x16x32_bf16 v[10:13], v[174:177], v[198:201], v[10:13]
	v_mfma_f32_16x16x32_bf16 v[6:9], v[166:169], v[206:209], v[6:9]
	v_mfma_f32_16x16x32_bf16 v[2:5], v[174:177], v[206:209], v[2:5]
	s_barrier
	s_add_i32 s36, s40, 2
	s_add_u32 s34, s34, 0x100
	s_addc_u32 s35, s35, 0
	s_add_u32 s25, s25, 0x100
	s_addc_u32 s31, s31, 0
	s_cmp_ge_i32 s40, s74
	s_mov_b32 s40, s36
	s_cbranch_scc0 .LBB0_1264
	s_setprio 0
	s_and_b64 vcc, exec, s[16:17]
	s_cbranch_vccz .LBB0_1267
	s_barrier

.LBB0_1484:
	s_ashr_i32 s17, s16, 31
	s_lshl_b64 s[18:19], s[16:17], 19
	s_add_u32 s18, s34, s18
	s_addc_u32 s19, s35, s19
	s_and_b64 s[20:21], s[6:7], exec
	s_cselect_b32 s17, s19, s27
	s_cselect_b32 s23, s18, s26
	s_ashr_i32 s15, s14, 31
	s_lshl_b64 s[20:21], s[14:15], 19
	s_add_u32 s20, s36, s20
	s_addc_u32 s21, s37, s21
	s_and_b64 s[30:31], s[6:7], exec
	s_cselect_b32 s15, s21, s29
	s_cselect_b32 s33, s20, s28
	s_add_u32 s26, s26, 0x40080
	s_addc_u32 s27, s27, 0
	s_add_u32 s50, s28, 0x100
	v_mov_b32_e32 v2, 0
	s_addc_u32 s51, s29, 0
	s_mov_b32 s52, -2
	v_mov_b32_e32 v3, v2
	v_mov_b32_e32 v4, v2
	v_mov_b32_e32 v5, v2
	v_mov_b32_e32 v6, v2
	v_mov_b32_e32 v7, v2
	v_mov_b32_e32 v8, v2
	v_mov_b32_e32 v9, v2
	v_mov_b32_e32 v18, v2
	v_mov_b32_e32 v19, v2
	v_mov_b32_e32 v20, v2
	v_mov_b32_e32 v21, v2
	v_mov_b32_e32 v22, v2
	v_mov_b32_e32 v23, v2
	v_mov_b32_e32 v24, v2
	v_mov_b32_e32 v25, v2
	v_mov_b32_e32 v50, v2
	v_mov_b32_e32 v51, v2
	v_mov_b32_e32 v52, v2
	v_mov_b32_e32 v53, v2
	v_mov_b32_e32 v54, v2
	v_mov_b32_e32 v55, v2
	v_mov_b32_e32 v56, v2
	v_mov_b32_e32 v57, v2
	v_mov_b32_e32 v66, v2
	v_mov_b32_e32 v67, v2
	v_mov_b32_e32 v68, v2
	v_mov_b32_e32 v69, v2
	v_mov_b32_e32 v70, v2
	v_mov_b32_e32 v71, v2
	v_mov_b32_e32 v72, v2
	v_mov_b32_e32 v73, v2
	v_mov_b32_e32 v10, v2
	v_mov_b32_e32 v11, v2
	v_mov_b32_e32 v12, v2
	v_mov_b32_e32 v13, v2
	v_mov_b32_e32 v14, v2
	v_mov_b32_e32 v15, v2
	v_mov_b32_e32 v16, v2
	v_mov_b32_e32 v17, v2
	v_mov_b32_e32 v26, v2
	v_mov_b32_e32 v27, v2
	v_mov_b32_e32 v28, v2
	v_mov_b32_e32 v29, v2
	v_mov_b32_e32 v30, v2
	v_mov_b32_e32 v31, v2
	v_mov_b32_e32 v32, v2
	v_mov_b32_e32 v33, v2
	v_mov_b32_e32 v58, v2
	v_mov_b32_e32 v59, v2
	v_mov_b32_e32 v60, v2
	v_mov_b32_e32 v61, v2
	v_mov_b32_e32 v62, v2
	v_mov_b32_e32 v63, v2
	v_mov_b32_e32 v64, v2
	v_mov_b32_e32 v65, v2
	v_mov_b32_e32 v74, v2
	v_mov_b32_e32 v75, v2
	v_mov_b32_e32 v76, v2
	v_mov_b32_e32 v77, v2
	v_mov_b32_e32 v78, v2
	v_mov_b32_e32 v79, v2
	v_mov_b32_e32 v80, v2
	v_mov_b32_e32 v81, v2
	v_mov_b32_e32 v82, v2
	v_mov_b32_e32 v83, v2
	v_mov_b32_e32 v84, v2
	v_mov_b32_e32 v85, v2
	v_mov_b32_e32 v86, v2
	v_mov_b32_e32 v87, v2
	v_mov_b32_e32 v88, v2
	v_mov_b32_e32 v89, v2
	v_mov_b32_e32 v98, v2
	v_mov_b32_e32 v99, v2
	v_mov_b32_e32 v100, v2
	v_mov_b32_e32 v101, v2
	v_mov_b32_e32 v102, v2
	v_mov_b32_e32 v103, v2
	v_mov_b32_e32 v104, v2
	v_mov_b32_e32 v105, v2
	v_mov_b32_e32 v114, v2
	v_mov_b32_e32 v115, v2
	v_mov_b32_e32 v116, v2
	v_mov_b32_e32 v117, v2
	v_mov_b32_e32 v118, v2
	v_mov_b32_e32 v119, v2
	v_mov_b32_e32 v120, v2
	v_mov_b32_e32 v121, v2
	v_mov_b32_e32 v130, v2
	v_mov_b32_e32 v131, v2
	v_mov_b32_e32 v132, v2
	v_mov_b32_e32 v133, v2
	v_mov_b32_e32 v134, v2
	v_mov_b32_e32 v135, v2
	v_mov_b32_e32 v136, v2
	v_mov_b32_e32 v137, v2
	v_mov_b32_e32 v90, v2
	v_mov_b32_e32 v91, v2
	v_mov_b32_e32 v92, v2
	v_mov_b32_e32 v93, v2
	v_mov_b32_e32 v94, v2
	v_mov_b32_e32 v95, v2
	v_mov_b32_e32 v96, v2
	v_mov_b32_e32 v97, v2
	v_mov_b32_e32 v106, v2
	v_mov_b32_e32 v107, v2
	v_mov_b32_e32 v108, v2
	v_mov_b32_e32 v109, v2
	v_mov_b32_e32 v110, v2
	v_mov_b32_e32 v111, v2
	v_mov_b32_e32 v112, v2
	v_mov_b32_e32 v113, v2
	v_mov_b32_e32 v122, v2
	v_mov_b32_e32 v123, v2
	v_mov_b32_e32 v124, v2
	v_mov_b32_e32 v125, v2
	v_mov_b32_e32 v126, v2
	v_mov_b32_e32 v127, v2
	v_mov_b32_e32 v128, v2
	v_mov_b32_e32 v129, v2
	v_mov_b32_e32 v138, v2
	v_mov_b32_e32 v139, v2
	v_mov_b32_e32 v140, v2
	v_mov_b32_e32 v141, v2
	v_mov_b32_e32 v142, v2
	v_mov_b32_e32 v143, v2
	v_mov_b32_e32 v144, v2
	v_mov_b32_e32 v145, v2
	v_readfirstlane_b32 s84, v224
	s_bitcmp1_b32 s84, 8
	s_cbranch_scc0 .Lsprio_6
	s_setprio 1
.Lsprio_6:
.LBB0_1485:
	s_add_u32 s28, s26, 0xfffc0080
	s_addc_u32 s29, s27, -1
	s_add_i32 s53, 0, 0x10000
	s_cmp_eq_u32 s52, 12
	s_cselect_b32 s31, s17, s29
	s_cselect_b32 s30, s23, s28
	s_cselect_b32 s29, s15, s51
	s_cselect_b32 s28, s33, s50
	s_add_i32 s56, 0, 0x14000
	v_add_u32_e32 v46, s53, v164
	v_add_u32_e32 v171, s56, v164
	ds_read_b128 v[34:37], v46
	ds_read_b128 v[38:41], v46 offset:1024
	ds_read_b128 v[42:45], v46 offset:2048
	ds_read_b128 v[46:49], v46 offset:3072
	ds_read_b128 v[160:163], v171
	ds_read_b128 v[172:175], v171 offset:1024
	ds_read_b128 v[176:179], v171 offset:2048
	ds_read_b128 v[180:183], v171 offset:3072
	v_lshl_add_u64 v[216:217], s[26:27], 0, v[156:157]
	s_add_i32 m0, s25, 0xc000
	ds_read_b128 v[184:187], v169
	ds_read_b128 v[188:191], v169 offset:1024
	ds_read_b128 v[192:195], v169 offset:2048
	ds_read_b128 v[196:199], v169 offset:3072
	ds_read_b128 v[200:203], v169 offset:4096
	ds_read_b128 v[204:207], v169 offset:5120
	ds_read_b128 v[208:211], v169 offset:6144
	ds_read_b128 v[212:215], v169 offset:7168
	global_load_lds_dwordx4 v[216:217], off
	v_lshl_add_u64 v[216:217], s[26:27], 0, v[158:159]
	s_add_i32 m0, s25, 0xe000
	s_nop 0
	global_load_lds_dwordx4 v[216:217], off
	s_waitcnt vmcnt(8)
	s_waitcnt lgkmcnt(0)
	s_barrier
	s_waitcnt lgkmcnt(0)
	v_mfma_f32_16x16x32_bf16 v[142:145], v[34:37], v[184:187], v[142:145]
	v_mfma_f32_16x16x32_bf16 v[138:141], v[42:45], v[184:187], v[138:141]
	v_mfma_f32_16x16x32_bf16 v[126:129], v[34:37], v[192:195], v[126:129]
	v_mfma_f32_16x16x32_bf16 v[122:125], v[42:45], v[192:195], v[122:125]
	v_mfma_f32_16x16x32_bf16 v[110:113], v[34:37], v[200:203], v[110:113]
	v_mfma_f32_16x16x32_bf16 v[106:109], v[42:45], v[200:203], v[106:109]
	v_mfma_f32_16x16x32_bf16 v[94:97], v[34:37], v[208:211], v[94:97]
	v_mfma_f32_16x16x32_bf16 v[90:93], v[42:45], v[208:211], v[90:93]
	v_mfma_f32_16x16x32_bf16 v[142:145], v[38:41], v[188:191], v[142:145]
	v_mfma_f32_16x16x32_bf16 v[138:141], v[46:49], v[188:191], v[138:141]
	v_mfma_f32_16x16x32_bf16 v[126:129], v[38:41], v[196:199], v[126:129]
	v_mfma_f32_16x16x32_bf16 v[122:125], v[46:49], v[196:199], v[122:125]
	v_mfma_f32_16x16x32_bf16 v[110:113], v[38:41], v[204:207], v[110:113]
	v_mfma_f32_16x16x32_bf16 v[106:109], v[46:49], v[204:207], v[106:109]
	v_mfma_f32_16x16x32_bf16 v[94:97], v[38:41], v[212:215], v[94:97]
	v_mfma_f32_16x16x32_bf16 v[90:93], v[46:49], v[212:215], v[90:93]
	v_mfma_f32_16x16x32_bf16 v[134:137], v[160:163], v[184:187], v[134:137]
	v_mfma_f32_16x16x32_bf16 v[130:133], v[176:179], v[184:187], v[130:133]
	v_mfma_f32_16x16x32_bf16 v[118:121], v[160:163], v[192:195], v[118:121]
	v_mfma_f32_16x16x32_bf16 v[114:117], v[176:179], v[192:195], v[114:117]
	v_mfma_f32_16x16x32_bf16 v[102:105], v[160:163], v[200:203], v[102:105]
	v_mfma_f32_16x16x32_bf16 v[98:101], v[176:179], v[200:203], v[98:101]
	v_mfma_f32_16x16x32_bf16 v[86:89], v[160:163], v[208:211], v[86:89]
	v_mfma_f32_16x16x32_bf16 v[82:85], v[176:179], v[208:211], v[82:85]
	v_mfma_f32_16x16x32_bf16 v[134:137], v[172:175], v[188:191], v[134:137]
	v_mfma_f32_16x16x32_bf16 v[130:133], v[180:183], v[188:191], v[130:133]
	v_mfma_f32_16x16x32_bf16 v[118:121], v[172:175], v[196:199], v[118:121]
	v_mfma_f32_16x16x32_bf16 v[114:117], v[180:183], v[196:199], v[114:117]
	v_mfma_f32_16x16x32_bf16 v[102:105], v[172:175], v[204:207], v[102:105]
	v_mfma_f32_16x16x32_bf16 v[98:101], v[180:183], v[204:207], v[98:101]
	v_mfma_f32_16x16x32_bf16 v[86:89], v[172:175], v[212:215], v[86:89]
	v_mfma_f32_16x16x32_bf16 v[82:85], v[180:183], v[212:215], v[82:85]
	s_barrier
	s_add_i32 s53, s53, s38
	v_lshl_add_u64 v[216:217], s[28:29], 0, v[152:153]
	s_mov_b32 m0, s53
	ds_read_b128 v[184:187], v169 offset:16384
	ds_read_b128 v[188:191], v169 offset:17408
	ds_read_b128 v[192:195], v169 offset:18432
	ds_read_b128 v[196:199], v169 offset:19456
	ds_read_b128 v[200:203], v169 offset:20480
	ds_read_b128 v[204:207], v169 offset:21504
	ds_read_b128 v[208:211], v169 offset:22528
	ds_read_b128 v[212:215], v169 offset:23552
	global_load_lds_dwordx4 v[216:217], off
	s_add_i32 m0, s53, 0x2000
	s_add_u32 s54, s28, 0x40000
	v_lshl_add_u64 v[218:219], s[28:29], 0, v[148:149]
	s_addc_u32 s55, s29, 0
	s_add_i32 s53, s56, s38
	global_load_lds_dwordx4 v[218:219], off
	v_lshl_add_u64 v[220:221], s[54:55], 0, v[152:153]
	s_mov_b32 m0, s53
	v_lshl_add_u64 v[222:223], s[30:31], 0, v[150:151]
	global_load_lds_dwordx4 v[220:221], off
	v_lshl_add_u64 v[220:221], s[54:55], 0, v[148:149]
	s_add_i32 m0, s53, 0x2000
	s_nop 0
	global_load_lds_dwordx4 v[220:221], off
	v_lshl_add_u64 v[220:221], s[30:31], 0, v[154:155]
	s_mov_b32 m0, s25
	s_nop 0
	global_load_lds_dwordx4 v[220:221], off
	s_mov_b32 m0, s40
	s_nop 0
	global_load_lds_dwordx4 v[222:223], off
	s_waitcnt vmcnt(8)
	s_waitcnt lgkmcnt(0)
	s_barrier
	s_waitcnt lgkmcnt(0)
	v_mfma_f32_16x16x32_bf16 v[78:81], v[34:37], v[184:187], v[78:81]
	v_mfma_f32_16x16x32_bf16 v[74:77], v[42:45], v[184:187], v[74:77]
	v_mfma_f32_16x16x32_bf16 v[62:65], v[34:37], v[192:195], v[62:65]
	v_mfma_f32_16x16x32_bf16 v[58:61], v[42:45], v[192:195], v[58:61]
	v_mfma_f32_16x16x32_bf16 v[30:33], v[34:37], v[200:203], v[30:33]
	v_mfma_f32_16x16x32_bf16 v[26:29], v[42:45], v[200:203], v[26:29]
	v_mfma_f32_16x16x32_bf16 v[14:17], v[34:37], v[208:211], v[14:17]
	v_mfma_f32_16x16x32_bf16 v[10:13], v[42:45], v[208:211], v[10:13]
	v_mfma_f32_16x16x32_bf16 v[78:81], v[38:41], v[188:191], v[78:81]
	v_mfma_f32_16x16x32_bf16 v[74:77], v[46:49], v[188:191], v[74:77]
	v_mfma_f32_16x16x32_bf16 v[62:65], v[38:41], v[196:199], v[62:65]
	v_mfma_f32_16x16x32_bf16 v[58:61], v[46:49], v[196:199], v[58:61]
	v_mfma_f32_16x16x32_bf16 v[30:33], v[38:41], v[204:207], v[30:33]
	v_mfma_f32_16x16x32_bf16 v[26:29], v[46:49], v[204:207], v[26:29]
	v_mfma_f32_16x16x32_bf16 v[14:17], v[38:41], v[212:215], v[14:17]
	v_mfma_f32_16x16x32_bf16 v[10:13], v[46:49], v[212:215], v[10:13]
	v_mfma_f32_16x16x32_bf16 v[22:25], v[160:163], v[200:203], v[22:25]
	v_mfma_f32_16x16x32_bf16 v[18:21], v[176:179], v[200:203], v[18:21]
	v_mfma_f32_16x16x32_bf16 v[6:9], v[160:163], v[208:211], v[6:9]
	v_mfma_f32_16x16x32_bf16 v[2:5], v[176:179], v[208:211], v[2:5]
	v_mfma_f32_16x16x32_bf16 v[34:37], v[160:163], v[184:187], v[70:73]
	v_mfma_f32_16x16x32_bf16 v[38:41], v[176:179], v[184:187], v[66:69]
	v_mfma_f32_16x16x32_bf16 v[42:45], v[160:163], v[192:195], v[54:57]
	v_mfma_f32_16x16x32_bf16 v[46:49], v[176:179], v[192:195], v[50:53]
	v_mfma_f32_16x16x32_bf16 v[22:25], v[172:175], v[204:207], v[22:25]
	v_mfma_f32_16x16x32_bf16 v[18:21], v[180:183], v[204:207], v[18:21]
	v_mfma_f32_16x16x32_bf16 v[6:9], v[172:175], v[212:215], v[6:9]
	v_mfma_f32_16x16x32_bf16 v[2:5], v[180:183], v[212:215], v[2:5]
	v_mfma_f32_16x16x32_bf16 v[34:37], v[172:175], v[188:191], v[34:37]
	v_mfma_f32_16x16x32_bf16 v[38:41], v[180:183], v[188:191], v[38:41]
	v_mfma_f32_16x16x32_bf16 v[42:45], v[172:175], v[196:199], v[42:45]
	v_mfma_f32_16x16x32_bf16 v[46:49], v[180:183], v[196:199], v[46:49]
	s_barrier
	s_add_i32 s53, 0, 0x18000
	s_add_i32 s54, 0, 0x1c000
	v_add_u32_e32 v70, s53, v164
	v_add_u32_e32 v171, s54, v164
	ds_read_b128 v[50:53], v70
	ds_read_b128 v[54:57], v70 offset:1024
	ds_read_b128 v[66:69], v70 offset:2048
	ds_read_b128 v[70:73], v70 offset:3072
	ds_read_b128 v[160:163], v171
	ds_read_b128 v[172:175], v171 offset:1024
	ds_read_b128 v[176:179], v171 offset:2048
	ds_read_b128 v[180:183], v171 offset:3072
	s_add_u32 s30, s30, 0x40000
	s_addc_u32 s31, s31, 0
	s_mov_b32 m0, s41
	v_lshl_add_u64 v[226:227], s[30:31], 0, v[154:155]
	ds_read_b128 v[184:187], v169 offset:32768
	ds_read_b128 v[188:191], v169 offset:33792
	ds_read_b128 v[192:195], v169 offset:34816
	ds_read_b128 v[196:199], v169 offset:35840
	ds_read_b128 v[200:203], v169 offset:36864
	ds_read_b128 v[204:207], v169 offset:37888
	ds_read_b128 v[208:211], v169 offset:38912
	ds_read_b128 v[212:215], v169 offset:39936
	global_load_lds_dwordx4 v[226:227], off
	v_lshl_add_u64 v[226:227], s[30:31], 0, v[150:151]
	s_mov_b32 m0, s42
	s_nop 0
	global_load_lds_dwordx4 v[226:227], off
	s_waitcnt vmcnt(8)
	s_waitcnt lgkmcnt(0)
	s_barrier
	s_waitcnt lgkmcnt(0)
	v_mfma_f32_16x16x32_bf16 v[142:145], v[50:53], v[184:187], v[142:145]
	v_mfma_f32_16x16x32_bf16 v[138:141], v[66:69], v[184:187], v[138:141]
	v_mfma_f32_16x16x32_bf16 v[126:129], v[50:53], v[192:195], v[126:129]
	v_mfma_f32_16x16x32_bf16 v[122:125], v[66:69], v[192:195], v[122:125]
	v_mfma_f32_16x16x32_bf16 v[110:113], v[50:53], v[200:203], v[110:113]
	v_mfma_f32_16x16x32_bf16 v[106:109], v[66:69], v[200:203], v[106:109]
	v_mfma_f32_16x16x32_bf16 v[94:97], v[50:53], v[208:211], v[94:97]
	v_mfma_f32_16x16x32_bf16 v[90:93], v[66:69], v[208:211], v[90:93]
	v_mfma_f32_16x16x32_bf16 v[142:145], v[54:57], v[188:191], v[142:145]
	v_mfma_f32_16x16x32_bf16 v[138:141], v[70:73], v[188:191], v[138:141]
	v_mfma_f32_16x16x32_bf16 v[126:129], v[54:57], v[196:199], v[126:129]
	v_mfma_f32_16x16x32_bf16 v[122:125], v[70:73], v[196:199], v[122:125]
	v_mfma_f32_16x16x32_bf16 v[110:113], v[54:57], v[204:207], v[110:113]
	v_mfma_f32_16x16x32_bf16 v[106:109], v[70:73], v[204:207], v[106:109]
	v_mfma_f32_16x16x32_bf16 v[94:97], v[54:57], v[212:215], v[94:97]
	v_mfma_f32_16x16x32_bf16 v[90:93], v[70:73], v[212:215], v[90:93]
	v_mfma_f32_16x16x32_bf16 v[134:137], v[160:163], v[184:187], v[134:137]
	v_mfma_f32_16x16x32_bf16 v[130:133], v[176:179], v[184:187], v[130:133]
	v_mfma_f32_16x16x32_bf16 v[118:121], v[160:163], v[192:195], v[118:121]
	v_mfma_f32_16x16x32_bf16 v[114:117], v[176:179], v[192:195], v[114:117]
	v_mfma_f32_16x16x32_bf16 v[102:105], v[160:163], v[200:203], v[102:105]
	v_mfma_f32_16x16x32_bf16 v[98:101], v[176:179], v[200:203], v[98:101]
	v_mfma_f32_16x16x32_bf16 v[86:89], v[160:163], v[208:211], v[86:89]
	v_mfma_f32_16x16x32_bf16 v[82:85], v[176:179], v[208:211], v[82:85]
	v_mfma_f32_16x16x32_bf16 v[134:137], v[172:175], v[188:191], v[134:137]
	v_mfma_f32_16x16x32_bf16 v[130:133], v[180:183], v[188:191], v[130:133]
	v_mfma_f32_16x16x32_bf16 v[118:121], v[172:175], v[196:199], v[118:121]
	v_mfma_f32_16x16x32_bf16 v[114:117], v[180:183], v[196:199], v[114:117]
	v_mfma_f32_16x16x32_bf16 v[102:105], v[172:175], v[204:207], v[102:105]
	v_mfma_f32_16x16x32_bf16 v[98:101], v[180:183], v[204:207], v[98:101]
	v_mfma_f32_16x16x32_bf16 v[86:89], v[172:175], v[212:215], v[86:89]
	v_mfma_f32_16x16x32_bf16 v[82:85], v[180:183], v[212:215], v[82:85]
	s_barrier
	s_add_i32 s30, s53, s38
	v_lshl_add_u64 v[216:217], v[216:217], 0, s[2:3]
	s_mov_b32 m0, s30
	ds_read_b128 v[184:187], v169 offset:49152
	ds_read_b128 v[188:191], v169 offset:50176
	ds_read_b128 v[192:195], v169 offset:51200
	ds_read_b128 v[196:199], v169 offset:52224
	ds_read_b128 v[200:203], v169 offset:53248
	ds_read_b128 v[204:207], v169 offset:54272
	ds_read_b128 v[208:211], v169 offset:55296
	ds_read_b128 v[212:215], v169 offset:56320
	global_load_lds_dwordx4 v[216:217], off
	s_add_i32 m0, s30, 0x2000
	s_add_u32 s28, s28, 0x40080
	v_lshl_add_u64 v[216:217], v[218:219], 0, s[2:3]
	s_addc_u32 s29, s29, 0
	s_add_i32 s30, s54, s38
	global_load_lds_dwordx4 v[216:217], off
	v_lshl_add_u64 v[216:217], s[28:29], 0, v[152:153]
	s_mov_b32 m0, s30
	s_nop 0
	global_load_lds_dwordx4 v[216:217], off
	v_lshl_add_u64 v[216:217], s[28:29], 0, v[148:149]
	s_add_i32 m0, s30, 0x2000
	s_nop 0
	global_load_lds_dwordx4 v[216:217], off
	v_lshl_add_u64 v[216:217], v[220:221], 0, s[2:3]
	s_mov_b32 m0, s45
	s_nop 0
	global_load_lds_dwordx4 v[216:217], off
	v_lshl_add_u64 v[216:217], v[222:223], 0, s[2:3]
	s_mov_b32 m0, s46
	s_nop 0
	global_load_lds_dwordx4 v[216:217], off
	s_waitcnt vmcnt(8)
	s_waitcnt lgkmcnt(0)
	s_barrier
	s_waitcnt lgkmcnt(0)
	v_mfma_f32_16x16x32_bf16 v[78:81], v[50:53], v[184:187], v[78:81]
	v_mfma_f32_16x16x32_bf16 v[74:77], v[66:69], v[184:187], v[74:77]
	v_mfma_f32_16x16x32_bf16 v[62:65], v[50:53], v[192:195], v[62:65]
	v_mfma_f32_16x16x32_bf16 v[58:61], v[66:69], v[192:195], v[58:61]
	v_mfma_f32_16x16x32_bf16 v[30:33], v[50:53], v[200:203], v[30:33]
	v_mfma_f32_16x16x32_bf16 v[26:29], v[66:69], v[200:203], v[26:29]
	v_mfma_f32_16x16x32_bf16 v[14:17], v[50:53], v[208:211], v[14:17]
	v_mfma_f32_16x16x32_bf16 v[10:13], v[66:69], v[208:211], v[10:13]
	v_mfma_f32_16x16x32_bf16 v[78:81], v[54:57], v[188:191], v[78:81]
	v_mfma_f32_16x16x32_bf16 v[74:77], v[70:73], v[188:191], v[74:77]
	v_mfma_f32_16x16x32_bf16 v[62:65], v[54:57], v[196:199], v[62:65]
	v_mfma_f32_16x16x32_bf16 v[58:61], v[70:73], v[196:199], v[58:61]
	v_mfma_f32_16x16x32_bf16 v[30:33], v[54:57], v[204:207], v[30:33]
	v_mfma_f32_16x16x32_bf16 v[26:29], v[70:73], v[204:207], v[26:29]
	v_mfma_f32_16x16x32_bf16 v[14:17], v[54:57], v[212:215], v[14:17]
	v_mfma_f32_16x16x32_bf16 v[10:13], v[70:73], v[212:215], v[10:13]
	v_mfma_f32_16x16x32_bf16 v[34:37], v[160:163], v[184:187], v[34:37]
	v_mfma_f32_16x16x32_bf16 v[70:73], v[172:175], v[188:191], v[34:37]
	v_mfma_f32_16x16x32_bf16 v[34:37], v[176:179], v[184:187], v[38:41]
	v_mfma_f32_16x16x32_bf16 v[66:69], v[180:183], v[188:191], v[34:37]
	v_mfma_f32_16x16x32_bf16 v[34:37], v[160:163], v[192:195], v[42:45]
	v_mfma_f32_16x16x32_bf16 v[54:57], v[172:175], v[196:199], v[34:37]
	v_mfma_f32_16x16x32_bf16 v[34:37], v[176:179], v[192:195], v[46:49]
	v_mfma_f32_16x16x32_bf16 v[22:25], v[160:163], v[200:203], v[22:25]
	v_mfma_f32_16x16x32_bf16 v[18:21], v[176:179], v[200:203], v[18:21]
	v_mfma_f32_16x16x32_bf16 v[6:9], v[160:163], v[208:211], v[6:9]
	v_mfma_f32_16x16x32_bf16 v[2:5], v[176:179], v[208:211], v[2:5]
	v_mfma_f32_16x16x32_bf16 v[50:53], v[180:183], v[196:199], v[34:37]
	v_mfma_f32_16x16x32_bf16 v[22:25], v[172:175], v[204:207], v[22:25]
	v_mfma_f32_16x16x32_bf16 v[18:21], v[180:183], v[204:207], v[18:21]
	v_mfma_f32_16x16x32_bf16 v[6:9], v[172:175], v[212:215], v[6:9]
	v_mfma_f32_16x16x32_bf16 v[2:5], v[180:183], v[212:215], v[2:5]
	s_barrier
	s_add_i32 s52, s52, 2
	s_add_u32 s26, s26, 0x100
	s_addc_u32 s27, s27, 0
	s_add_u32 s50, s50, 0x100
	s_addc_u32 s51, s51, 0
	s_cmp_gt_u32 s52, 13
	s_cbranch_scc0 .LBB0_1485
	s_setprio 0
	s_and_b64 vcc, exec, s[12:13]
	s_cbranch_vccz .LBB0_1488
	s_barrier

.LBB0_1569:
	s_add_u32 s7, s30, 0x100
	v_mov_b32_e32 v2, 0
	s_addc_u32 s23, s31, 0
	s_mov_b32 s36, 2
	v_mov_b32_e32 v3, v2
	v_mov_b32_e32 v4, v2
	v_mov_b32_e32 v5, v2
	v_mov_b32_e32 v6, v2
	v_mov_b32_e32 v7, v2
	v_mov_b32_e32 v8, v2
	v_mov_b32_e32 v9, v2
	v_mov_b32_e32 v10, v2
	v_mov_b32_e32 v11, v2
	v_mov_b32_e32 v12, v2
	v_mov_b32_e32 v13, v2
	v_mov_b32_e32 v14, v2
	v_mov_b32_e32 v15, v2
	v_mov_b32_e32 v16, v2
	v_mov_b32_e32 v17, v2
	v_mov_b32_e32 v18, v2
	v_mov_b32_e32 v19, v2
	v_mov_b32_e32 v20, v2
	v_mov_b32_e32 v21, v2
	v_mov_b32_e32 v22, v2
	v_mov_b32_e32 v23, v2
	v_mov_b32_e32 v24, v2
	v_mov_b32_e32 v25, v2
	v_mov_b32_e32 v26, v2
	v_mov_b32_e32 v27, v2
	v_mov_b32_e32 v28, v2
	v_mov_b32_e32 v29, v2
	v_mov_b32_e32 v30, v2
	v_mov_b32_e32 v31, v2
	v_mov_b32_e32 v32, v2
	v_mov_b32_e32 v33, v2
	v_mov_b32_e32 v66, v2
	v_mov_b32_e32 v67, v2
	v_mov_b32_e32 v68, v2
	v_mov_b32_e32 v69, v2
	v_mov_b32_e32 v70, v2
	v_mov_b32_e32 v71, v2
	v_mov_b32_e32 v72, v2
	v_mov_b32_e32 v73, v2
	v_mov_b32_e32 v82, v2
	v_mov_b32_e32 v83, v2
	v_mov_b32_e32 v84, v2
	v_mov_b32_e32 v85, v2
	v_mov_b32_e32 v86, v2
	v_mov_b32_e32 v87, v2
	v_mov_b32_e32 v88, v2
	v_mov_b32_e32 v89, v2
	v_mov_b32_e32 v106, v2
	v_mov_b32_e32 v107, v2
	v_mov_b32_e32 v108, v2
	v_mov_b32_e32 v109, v2
	v_mov_b32_e32 v110, v2
	v_mov_b32_e32 v111, v2
	v_mov_b32_e32 v112, v2
	v_mov_b32_e32 v113, v2
	v_mov_b32_e32 v126, v2
	v_mov_b32_e32 v127, v2
	v_mov_b32_e32 v128, v2
	v_mov_b32_e32 v129, v2
	v_mov_b32_e32 v122, v2
	v_mov_b32_e32 v123, v2
	v_mov_b32_e32 v124, v2
	v_mov_b32_e32 v125, v2
	v_mov_b32_e32 v34, v2
	v_mov_b32_e32 v35, v2
	v_mov_b32_e32 v36, v2
	v_mov_b32_e32 v37, v2
	v_mov_b32_e32 v38, v2
	v_mov_b32_e32 v39, v2
	v_mov_b32_e32 v40, v2
	v_mov_b32_e32 v41, v2
	v_mov_b32_e32 v42, v2
	v_mov_b32_e32 v43, v2
	v_mov_b32_e32 v44, v2
	v_mov_b32_e32 v45, v2
	v_mov_b32_e32 v46, v2
	v_mov_b32_e32 v47, v2
	v_mov_b32_e32 v48, v2
	v_mov_b32_e32 v49, v2
	v_mov_b32_e32 v50, v2
	v_mov_b32_e32 v51, v2
	v_mov_b32_e32 v52, v2
	v_mov_b32_e32 v53, v2
	v_mov_b32_e32 v54, v2
	v_mov_b32_e32 v55, v2
	v_mov_b32_e32 v56, v2
	v_mov_b32_e32 v57, v2
	v_mov_b32_e32 v58, v2
	v_mov_b32_e32 v59, v2
	v_mov_b32_e32 v60, v2
	v_mov_b32_e32 v61, v2
	v_mov_b32_e32 v62, v2
	v_mov_b32_e32 v63, v2
	v_mov_b32_e32 v64, v2
	v_mov_b32_e32 v65, v2
	v_mov_b32_e32 v118, v2
	v_mov_b32_e32 v119, v2
	v_mov_b32_e32 v120, v2
	v_mov_b32_e32 v121, v2
	v_mov_b32_e32 v114, v2
	v_mov_b32_e32 v115, v2
	v_mov_b32_e32 v116, v2
	v_mov_b32_e32 v117, v2
	v_mov_b32_e32 v102, v2
	v_mov_b32_e32 v103, v2
	v_mov_b32_e32 v104, v2
	v_mov_b32_e32 v105, v2
	v_mov_b32_e32 v98, v2
	v_mov_b32_e32 v99, v2
	v_mov_b32_e32 v100, v2
	v_mov_b32_e32 v101, v2
	v_mov_b32_e32 v94, v2
	v_mov_b32_e32 v95, v2
	v_mov_b32_e32 v96, v2
	v_mov_b32_e32 v97, v2
	v_mov_b32_e32 v90, v2
	v_mov_b32_e32 v91, v2
	v_mov_b32_e32 v92, v2
	v_mov_b32_e32 v93, v2
	v_mov_b32_e32 v78, v2
	v_mov_b32_e32 v79, v2
	v_mov_b32_e32 v80, v2
	v_mov_b32_e32 v81, v2
	v_mov_b32_e32 v74, v2
	v_mov_b32_e32 v75, v2
	v_mov_b32_e32 v76, v2
	v_mov_b32_e32 v77, v2
	v_readfirstlane_b32 s84, v224
	s_bitcmp1_b32 s84, 8
	s_cbranch_scc0 .Lsprio_7
	s_setprio 1
.Lsprio_7:
.LBB0_1570:
	s_add_u32 s4, s28, 0x100
	s_addc_u32 s5, s29, 0
	s_add_i32 s37, 0, 0x10000
	s_cmp_eq_u32 s69, s36
	s_cselect_b32 s35, s25, s5
	s_cselect_b32 s34, s24, s4
	s_cselect_b32 s31, s27, s23
	s_cselect_b32 s30, s26, s7
	s_add_i32 s38, 0, 0x14000
	v_add_u32_e32 v158, s37, v236
	v_add_u32_e32 v174, s38, v236
	ds_read_b128 v[130:133], v158
	ds_read_b128 v[134:137], v158 offset:1024
	ds_read_b128 v[154:157], v158 offset:2048
	ds_read_b128 v[158:161], v158 offset:3072
	ds_read_b128 v[162:165], v174
	ds_read_b128 v[166:169], v174 offset:1024
	ds_read_b128 v[170:173], v174 offset:2048
	ds_read_b128 v[174:177], v174 offset:3072
	v_lshl_add_u64 v[210:211], s[28:29], 0, v[150:151]
	s_add_i32 m0, s49, 0xc000
	ds_read_b128 v[178:181], v245
	ds_read_b128 v[182:185], v245 offset:1024
	ds_read_b128 v[186:189], v245 offset:2048
	ds_read_b128 v[190:193], v245 offset:3072
	ds_read_b128 v[194:197], v245 offset:4096
	ds_read_b128 v[198:201], v245 offset:5120
	ds_read_b128 v[202:205], v245 offset:6144
	ds_read_b128 v[206:209], v245 offset:7168
	global_load_lds_dwordx4 v[210:211], off
	v_lshl_add_u64 v[210:211], s[28:29], 0, v[152:153]
	s_add_i32 m0, s49, 0xe000
	s_nop 0
	global_load_lds_dwordx4 v[210:211], off
	s_waitcnt vmcnt(8)
	s_waitcnt lgkmcnt(0)
	s_barrier
	s_waitcnt lgkmcnt(0)
	v_mfma_f32_16x16x32_bf16 v[74:77], v[130:133], v[178:181], v[74:77]
	v_mfma_f32_16x16x32_bf16 v[78:81], v[154:157], v[178:181], v[78:81]
	v_mfma_f32_16x16x32_bf16 v[90:93], v[130:133], v[186:189], v[90:93]
	v_mfma_f32_16x16x32_bf16 v[94:97], v[154:157], v[186:189], v[94:97]
	v_mfma_f32_16x16x32_bf16 v[98:101], v[130:133], v[194:197], v[98:101]
	v_mfma_f32_16x16x32_bf16 v[102:105], v[154:157], v[194:197], v[102:105]
	v_mfma_f32_16x16x32_bf16 v[114:117], v[130:133], v[202:205], v[114:117]
	v_mfma_f32_16x16x32_bf16 v[118:121], v[154:157], v[202:205], v[118:121]
	v_mfma_f32_16x16x32_bf16 v[74:77], v[134:137], v[182:185], v[74:77]
	v_mfma_f32_16x16x32_bf16 v[78:81], v[158:161], v[182:185], v[78:81]
	v_mfma_f32_16x16x32_bf16 v[90:93], v[134:137], v[190:193], v[90:93]
	v_mfma_f32_16x16x32_bf16 v[94:97], v[158:161], v[190:193], v[94:97]
	v_mfma_f32_16x16x32_bf16 v[98:101], v[134:137], v[198:201], v[98:101]
	v_mfma_f32_16x16x32_bf16 v[102:105], v[158:161], v[198:201], v[102:105]
	v_mfma_f32_16x16x32_bf16 v[114:117], v[134:137], v[206:209], v[114:117]
	v_mfma_f32_16x16x32_bf16 v[118:121], v[158:161], v[206:209], v[118:121]
	v_mfma_f32_16x16x32_bf16 v[62:65], v[162:165], v[178:181], v[62:65]
	v_mfma_f32_16x16x32_bf16 v[58:61], v[170:173], v[178:181], v[58:61]
	v_mfma_f32_16x16x32_bf16 v[54:57], v[162:165], v[186:189], v[54:57]
	v_mfma_f32_16x16x32_bf16 v[50:53], v[170:173], v[186:189], v[50:53]
	v_mfma_f32_16x16x32_bf16 v[46:49], v[162:165], v[194:197], v[46:49]
	v_mfma_f32_16x16x32_bf16 v[42:45], v[170:173], v[194:197], v[42:45]
	v_mfma_f32_16x16x32_bf16 v[38:41], v[162:165], v[202:205], v[38:41]
	v_mfma_f32_16x16x32_bf16 v[34:37], v[170:173], v[202:205], v[34:37]
	v_mfma_f32_16x16x32_bf16 v[62:65], v[166:169], v[182:185], v[62:65]
	v_mfma_f32_16x16x32_bf16 v[58:61], v[174:177], v[182:185], v[58:61]
	v_mfma_f32_16x16x32_bf16 v[54:57], v[166:169], v[190:193], v[54:57]
	v_mfma_f32_16x16x32_bf16 v[50:53], v[174:177], v[190:193], v[50:53]
	v_mfma_f32_16x16x32_bf16 v[46:49], v[166:169], v[198:201], v[46:49]
	v_mfma_f32_16x16x32_bf16 v[42:45], v[174:177], v[198:201], v[42:45]
	v_mfma_f32_16x16x32_bf16 v[38:41], v[166:169], v[206:209], v[38:41]
	v_mfma_f32_16x16x32_bf16 v[34:37], v[174:177], v[206:209], v[34:37]
	s_barrier
	s_add_i32 s28, s37, s43
	v_lshl_add_u64 v[210:211], s[30:31], 0, v[140:141]
	s_mov_b32 m0, s28
	ds_read_b128 v[178:181], v245 offset:16384
	ds_read_b128 v[182:185], v245 offset:17408
	ds_read_b128 v[186:189], v245 offset:18432
	ds_read_b128 v[190:193], v245 offset:19456
	ds_read_b128 v[194:197], v245 offset:20480
	ds_read_b128 v[198:201], v245 offset:21504
	ds_read_b128 v[202:205], v245 offset:22528
	ds_read_b128 v[206:209], v245 offset:23552
	global_load_lds_dwordx4 v[210:211], off
	s_add_i32 m0, s28, 0x2000
	s_add_u32 s28, s30, 0xb0000
	v_lshl_add_u64 v[212:213], s[30:31], 0, v[144:145]
	s_addc_u32 s29, s31, 0
	s_add_i32 s37, s38, s43
	global_load_lds_dwordx4 v[212:213], off
	v_lshl_add_u64 v[214:215], s[28:29], 0, v[140:141]
	s_mov_b32 m0, s37
	v_lshl_add_u64 v[216:217], s[34:35], 0, v[142:143]
	global_load_lds_dwordx4 v[214:215], off
	v_lshl_add_u64 v[214:215], s[28:29], 0, v[144:145]
	s_add_i32 m0, s37, 0x2000
	s_nop 0
	global_load_lds_dwordx4 v[214:215], off
	v_lshl_add_u64 v[214:215], s[34:35], 0, v[138:139]
	s_mov_b32 m0, s49
	s_nop 0
	global_load_lds_dwordx4 v[214:215], off
	s_mov_b32 m0, s50
	s_nop 0
	global_load_lds_dwordx4 v[216:217], off
	s_waitcnt vmcnt(8)
	s_waitcnt lgkmcnt(0)
	s_barrier
	s_waitcnt lgkmcnt(0)
	v_mfma_f32_16x16x32_bf16 v[122:125], v[130:133], v[178:181], v[122:125]
	v_mfma_f32_16x16x32_bf16 v[126:129], v[154:157], v[178:181], v[126:129]
	v_mfma_f32_16x16x32_bf16 v[110:113], v[130:133], v[186:189], v[110:113]
	v_mfma_f32_16x16x32_bf16 v[106:109], v[154:157], v[186:189], v[106:109]
	v_mfma_f32_16x16x32_bf16 v[86:89], v[130:133], v[194:197], v[86:89]
	v_mfma_f32_16x16x32_bf16 v[82:85], v[154:157], v[194:197], v[82:85]
	v_mfma_f32_16x16x32_bf16 v[70:73], v[130:133], v[202:205], v[70:73]
	v_mfma_f32_16x16x32_bf16 v[66:69], v[154:157], v[202:205], v[66:69]
	v_mfma_f32_16x16x32_bf16 v[122:125], v[134:137], v[182:185], v[122:125]
	v_mfma_f32_16x16x32_bf16 v[126:129], v[158:161], v[182:185], v[126:129]
	v_mfma_f32_16x16x32_bf16 v[110:113], v[134:137], v[190:193], v[110:113]
	v_mfma_f32_16x16x32_bf16 v[106:109], v[158:161], v[190:193], v[106:109]
	v_mfma_f32_16x16x32_bf16 v[86:89], v[134:137], v[198:201], v[86:89]
	v_mfma_f32_16x16x32_bf16 v[82:85], v[158:161], v[198:201], v[82:85]
	v_mfma_f32_16x16x32_bf16 v[70:73], v[134:137], v[206:209], v[70:73]
	v_mfma_f32_16x16x32_bf16 v[66:69], v[158:161], v[206:209], v[66:69]
	v_mfma_f32_16x16x32_bf16 v[30:33], v[162:165], v[178:181], v[30:33]
	v_mfma_f32_16x16x32_bf16 v[26:29], v[170:173], v[178:181], v[26:29]
	v_mfma_f32_16x16x32_bf16 v[22:25], v[162:165], v[186:189], v[22:25]
	v_mfma_f32_16x16x32_bf16 v[18:21], v[170:173], v[186:189], v[18:21]
	v_mfma_f32_16x16x32_bf16 v[14:17], v[162:165], v[194:197], v[14:17]
	v_mfma_f32_16x16x32_bf16 v[10:13], v[170:173], v[194:197], v[10:13]
	v_mfma_f32_16x16x32_bf16 v[6:9], v[162:165], v[202:205], v[6:9]
	v_mfma_f32_16x16x32_bf16 v[2:5], v[170:173], v[202:205], v[2:5]
	v_mfma_f32_16x16x32_bf16 v[30:33], v[166:169], v[182:185], v[30:33]
	v_mfma_f32_16x16x32_bf16 v[26:29], v[174:177], v[182:185], v[26:29]
	v_mfma_f32_16x16x32_bf16 v[22:25], v[166:169], v[190:193], v[22:25]
	v_mfma_f32_16x16x32_bf16 v[18:21], v[174:177], v[190:193], v[18:21]
	v_mfma_f32_16x16x32_bf16 v[14:17], v[166:169], v[198:201], v[14:17]
	v_mfma_f32_16x16x32_bf16 v[10:13], v[174:177], v[198:201], v[10:13]
	v_mfma_f32_16x16x32_bf16 v[6:9], v[166:169], v[206:209], v[6:9]
	v_mfma_f32_16x16x32_bf16 v[2:5], v[174:177], v[206:209], v[2:5]
	s_barrier
	s_add_i32 s37, 0, 0x18000
	s_add_i32 s38, 0, 0x1c000
	v_add_u32_e32 v158, s37, v236
	v_add_u32_e32 v174, s38, v236
	ds_read_b128 v[130:133], v158
	ds_read_b128 v[134:137], v158 offset:1024
	ds_read_b128 v[154:157], v158 offset:2048
	ds_read_b128 v[158:161], v158 offset:3072
	ds_read_b128 v[162:165], v174
	ds_read_b128 v[166:169], v174 offset:1024
	ds_read_b128 v[170:173], v174 offset:2048
	ds_read_b128 v[174:177], v174 offset:3072
	s_add_u32 s28, s34, 0xb0000
	s_addc_u32 s29, s35, 0
	s_mov_b32 m0, s51
	v_lshl_add_u64 v[218:219], s[28:29], 0, v[138:139]
	ds_read_b128 v[178:181], v245 offset:32768
	ds_read_b128 v[182:185], v245 offset:33792
	ds_read_b128 v[186:189], v245 offset:34816
	ds_read_b128 v[190:193], v245 offset:35840
	ds_read_b128 v[194:197], v245 offset:36864
	ds_read_b128 v[198:201], v245 offset:37888
	ds_read_b128 v[202:205], v245 offset:38912
	ds_read_b128 v[206:209], v245 offset:39936
	global_load_lds_dwordx4 v[218:219], off
	v_lshl_add_u64 v[218:219], s[28:29], 0, v[142:143]
	s_mov_b32 m0, s52
	s_nop 0
	global_load_lds_dwordx4 v[218:219], off
	s_waitcnt vmcnt(8)
	s_waitcnt lgkmcnt(0)
	s_barrier
	s_waitcnt lgkmcnt(0)
	v_mfma_f32_16x16x32_bf16 v[74:77], v[130:133], v[178:181], v[74:77]
	v_mfma_f32_16x16x32_bf16 v[78:81], v[154:157], v[178:181], v[78:81]
	v_mfma_f32_16x16x32_bf16 v[90:93], v[130:133], v[186:189], v[90:93]
	v_mfma_f32_16x16x32_bf16 v[94:97], v[154:157], v[186:189], v[94:97]
	v_mfma_f32_16x16x32_bf16 v[98:101], v[130:133], v[194:197], v[98:101]
	v_mfma_f32_16x16x32_bf16 v[102:105], v[154:157], v[194:197], v[102:105]
	v_mfma_f32_16x16x32_bf16 v[114:117], v[130:133], v[202:205], v[114:117]
	v_mfma_f32_16x16x32_bf16 v[118:121], v[154:157], v[202:205], v[118:121]
	v_mfma_f32_16x16x32_bf16 v[74:77], v[134:137], v[182:185], v[74:77]
	v_mfma_f32_16x16x32_bf16 v[78:81], v[158:161], v[182:185], v[78:81]
	v_mfma_f32_16x16x32_bf16 v[90:93], v[134:137], v[190:193], v[90:93]
	v_mfma_f32_16x16x32_bf16 v[94:97], v[158:161], v[190:193], v[94:97]
	v_mfma_f32_16x16x32_bf16 v[98:101], v[134:137], v[198:201], v[98:101]
	v_mfma_f32_16x16x32_bf16 v[102:105], v[158:161], v[198:201], v[102:105]
	v_mfma_f32_16x16x32_bf16 v[114:117], v[134:137], v[206:209], v[114:117]
	v_mfma_f32_16x16x32_bf16 v[118:121], v[158:161], v[206:209], v[118:121]
	v_mfma_f32_16x16x32_bf16 v[62:65], v[162:165], v[178:181], v[62:65]
	v_mfma_f32_16x16x32_bf16 v[58:61], v[170:173], v[178:181], v[58:61]
	v_mfma_f32_16x16x32_bf16 v[54:57], v[162:165], v[186:189], v[54:57]
	v_mfma_f32_16x16x32_bf16 v[50:53], v[170:173], v[186:189], v[50:53]
	v_mfma_f32_16x16x32_bf16 v[46:49], v[162:165], v[194:197], v[46:49]
	v_mfma_f32_16x16x32_bf16 v[42:45], v[170:173], v[194:197], v[42:45]
	v_mfma_f32_16x16x32_bf16 v[38:41], v[162:165], v[202:205], v[38:41]
	v_mfma_f32_16x16x32_bf16 v[34:37], v[170:173], v[202:205], v[34:37]
	v_mfma_f32_16x16x32_bf16 v[62:65], v[166:169], v[182:185], v[62:65]
	v_mfma_f32_16x16x32_bf16 v[58:61], v[174:177], v[182:185], v[58:61]
	v_mfma_f32_16x16x32_bf16 v[54:57], v[166:169], v[190:193], v[54:57]
	v_mfma_f32_16x16x32_bf16 v[50:53], v[174:177], v[190:193], v[50:53]
	v_mfma_f32_16x16x32_bf16 v[46:49], v[166:169], v[198:201], v[46:49]
	v_mfma_f32_16x16x32_bf16 v[42:45], v[174:177], v[198:201], v[42:45]
	v_mfma_f32_16x16x32_bf16 v[38:41], v[166:169], v[206:209], v[38:41]
	v_mfma_f32_16x16x32_bf16 v[34:37], v[174:177], v[206:209], v[34:37]
	s_barrier
	s_add_i32 s28, s37, s43
	v_lshl_add_u64 v[210:211], v[210:211], 0, s[2:3]
	s_mov_b32 m0, s28
	ds_read_b128 v[178:181], v245 offset:49152
	ds_read_b128 v[182:185], v245 offset:50176
	ds_read_b128 v[186:189], v245 offset:51200
	ds_read_b128 v[190:193], v245 offset:52224
	ds_read_b128 v[194:197], v245 offset:53248
	ds_read_b128 v[198:201], v245 offset:54272
	ds_read_b128 v[202:205], v245 offset:55296
	ds_read_b128 v[206:209], v245 offset:56320
	global_load_lds_dwordx4 v[210:211], off
	s_add_i32 m0, s28, 0x2000
	s_add_u32 s28, s30, 0xb0080
	v_lshl_add_u64 v[210:211], v[212:213], 0, s[2:3]
	s_addc_u32 s29, s31, 0
	s_add_i32 s30, s38, s43
	global_load_lds_dwordx4 v[210:211], off
	v_lshl_add_u64 v[210:211], s[28:29], 0, v[140:141]
	s_mov_b32 m0, s30
	s_nop 0
	global_load_lds_dwordx4 v[210:211], off
	v_lshl_add_u64 v[210:211], s[28:29], 0, v[144:145]
	s_add_i32 m0, s30, 0x2000
	s_nop 0
	global_load_lds_dwordx4 v[210:211], off
	v_lshl_add_u64 v[210:211], v[214:215], 0, s[2:3]
	s_mov_b32 m0, s61
	s_nop 0
	global_load_lds_dwordx4 v[210:211], off
	v_lshl_add_u64 v[210:211], v[216:217], 0, s[2:3]
	s_mov_b32 m0, s62
	s_nop 0
	global_load_lds_dwordx4 v[210:211], off
	s_waitcnt vmcnt(8)
	s_waitcnt lgkmcnt(0)
	s_barrier
	s_waitcnt lgkmcnt(0)
	v_mfma_f32_16x16x32_bf16 v[122:125], v[130:133], v[178:181], v[122:125]
	v_mfma_f32_16x16x32_bf16 v[126:129], v[154:157], v[178:181], v[126:129]
	v_mfma_f32_16x16x32_bf16 v[110:113], v[130:133], v[186:189], v[110:113]
	v_mfma_f32_16x16x32_bf16 v[106:109], v[154:157], v[186:189], v[106:109]
	v_mfma_f32_16x16x32_bf16 v[86:89], v[130:133], v[194:197], v[86:89]
	v_mfma_f32_16x16x32_bf16 v[82:85], v[154:157], v[194:197], v[82:85]
	v_mfma_f32_16x16x32_bf16 v[70:73], v[130:133], v[202:205], v[70:73]
	v_mfma_f32_16x16x32_bf16 v[66:69], v[154:157], v[202:205], v[66:69]
	v_mfma_f32_16x16x32_bf16 v[122:125], v[134:137], v[182:185], v[122:125]
	v_mfma_f32_16x16x32_bf16 v[126:129], v[158:161], v[182:185], v[126:129]
	v_mfma_f32_16x16x32_bf16 v[110:113], v[134:137], v[190:193], v[110:113]
	v_mfma_f32_16x16x32_bf16 v[106:109], v[158:161], v[190:193], v[106:109]
	v_mfma_f32_16x16x32_bf16 v[86:89], v[134:137], v[198:201], v[86:89]
	v_mfma_f32_16x16x32_bf16 v[82:85], v[158:161], v[198:201], v[82:85]
	v_mfma_f32_16x16x32_bf16 v[70:73], v[134:137], v[206:209], v[70:73]
	v_mfma_f32_16x16x32_bf16 v[66:69], v[158:161], v[206:209], v[66:69]
	v_mfma_f32_16x16x32_bf16 v[30:33], v[162:165], v[178:181], v[30:33]
	v_mfma_f32_16x16x32_bf16 v[26:29], v[170:173], v[178:181], v[26:29]
	v_mfma_f32_16x16x32_bf16 v[22:25], v[162:165], v[186:189], v[22:25]
	v_mfma_f32_16x16x32_bf16 v[18:21], v[170:173], v[186:189], v[18:21]
	v_mfma_f32_16x16x32_bf16 v[14:17], v[162:165], v[194:197], v[14:17]
	v_mfma_f32_16x16x32_bf16 v[10:13], v[170:173], v[194:197], v[10:13]
	v_mfma_f32_16x16x32_bf16 v[6:9], v[162:165], v[202:205], v[6:9]
	v_mfma_f32_16x16x32_bf16 v[2:5], v[170:173], v[202:205], v[2:5]
	v_mfma_f32_16x16x32_bf16 v[30:33], v[166:169], v[182:185], v[30:33]
	v_mfma_f32_16x16x32_bf16 v[26:29], v[174:177], v[182:185], v[26:29]
	v_mfma_f32_16x16x32_bf16 v[22:25], v[166:169], v[190:193], v[22:25]
	v_mfma_f32_16x16x32_bf16 v[18:21], v[174:177], v[190:193], v[18:21]
	v_mfma_f32_16x16x32_bf16 v[14:17], v[166:169], v[198:201], v[14:17]
	v_mfma_f32_16x16x32_bf16 v[10:13], v[174:177], v[198:201], v[10:13]
	v_mfma_f32_16x16x32_bf16 v[6:9], v[166:169], v[206:209], v[6:9]
	v_mfma_f32_16x16x32_bf16 v[2:5], v[174:177], v[206:209], v[2:5]
	s_barrier
	s_add_i32 s30, s36, 2
	s_add_u32 s7, s7, 0x100
	s_addc_u32 s23, s23, 0
	s_cmp_ge_i32 s36, s69
	s_mov_b64 s[28:29], s[4:5]
	s_mov_b32 s36, s30
	s_cbranch_scc0 .LBB0_1570
	s_setprio 0
	s_and_b64 vcc, exec, s[18:19]
	s_cbranch_vccz .LBB0_1573
	s_barrier
